# K-loops: barrier behind the first four register-resident MFMAs
# baseline (speedup 1.0000x reference)
.LBB0_147:
	s_and_b32 s13, s12, 0x18000
	v_add_u32_e32 v222, s13, v180
	s_add_i32 s13, s12, 0xfffe8000
	s_and_b32 s13, s13, 0x18000
	v_or_b32_e32 v223, s13, v179
	v_add_u32_e32 v233, s13, v176
	s_waitcnt lgkmcnt(0)
	v_mfma_f32_32x32x16_bf16 v[112:127], v[150:153], v[142:145], v[112:127]
	v_mfma_f32_32x32x16_bf16 v[96:111], v[150:153], v[130:133], v[96:111]
	v_mfma_f32_32x32x16_bf16 v[80:95], v[146:149], v[142:145], v[80:95]
	v_mfma_f32_32x32x16_bf16 v[64:79], v[146:149], v[130:133], v[64:79]
	s_waitcnt vmcnt(8)
	s_barrier
	v_add_u32_e32 v206, v223, v177
	v_add_u32_e32 v234, v233, v177
	ds_read_b128 v[202:205], v206 offset:16384
	ds_read_b128 v[206:209], v206 offset:18432
	ds_read_b128 v[210:213], v234
	v_mfma_f32_32x32x16_bf16 v[48:63], v[138:141], v[142:145], v[48:63]
	v_mfma_f32_32x32x16_bf16 v[32:47], v[138:141], v[130:133], v[32:47]
	ds_read_b128 v[214:217], v234 offset:2048
	v_readfirstlane_b32 s13, v222
	s_mov_b32 m0, s13
	s_nop 0
	global_load_lds_dwordx4 v[170:171], off
	v_mfma_f32_32x32x16_bf16 v[16:31], v[134:137], v[142:145], v[16:31]
	v_mfma_f32_32x32x16_bf16 v[0:15], v[134:137], v[130:133], v[0:15]
	ds_read_b128 v[224:227], v234 offset:4096
	s_add_i32 s14, s13, 0x2000
	v_lshl_add_u64 v[150:151], v[170:171], 0, s[34:35]
	s_mov_b32 m0, s14
	s_nop 0
	global_load_lds_dwordx4 v[150:151], off
	ds_read_b128 v[234:237], v234 offset:6144
	s_waitcnt lgkmcnt(3)
	v_mfma_f32_32x32x16_bf16 v[112:127], v[210:213], v[202:205], v[112:127]
	v_add_u32_e32 v130, v223, v178
	v_add_u32_e32 v134, v233, v178
	ds_read_b128 v[142:145], v130 offset:16384
	v_mfma_f32_32x32x16_bf16 v[96:111], v[210:213], v[206:209], v[96:111]
	ds_read_b128 v[130:133], v130 offset:18432
	s_add_i32 s14, s13, 0x6000
	s_addk_i32 s13, 0x4000
	s_mov_b32 m0, s13
	s_nop 0
	global_load_lds_dwordx4 v[172:173], off
	s_waitcnt lgkmcnt(4)
	v_mfma_f32_32x32x16_bf16 v[80:95], v[214:217], v[202:205], v[80:95]
	ds_read_b128 v[150:153], v134
	v_mfma_f32_32x32x16_bf16 v[64:79], v[214:217], v[206:209], v[64:79]
	ds_read_b128 v[146:149], v134 offset:2048
	s_waitcnt lgkmcnt(5)
	v_mfma_f32_32x32x16_bf16 v[48:63], v[224:227], v[202:205], v[48:63]
	ds_read_b128 v[138:141], v134 offset:4096
	v_mfma_f32_32x32x16_bf16 v[32:47], v[224:227], v[206:209], v[32:47]
	ds_read_b128 v[134:137], v134 offset:6144
	v_lshl_add_u64 v[222:223], v[172:173], 0, s[34:35]
	s_mov_b32 m0, s14
	s_nop 0
	global_load_lds_dwordx4 v[222:223], off
	s_waitcnt lgkmcnt(6)
	v_mfma_f32_32x32x16_bf16 v[16:31], v[234:237], v[202:205], v[16:31]
	s_add_i32 s12, s12, 0x8000
	v_lshl_add_u64 v[170:171], v[170:171], 0, 64
	v_lshl_add_u64 v[172:173], v[172:173], 0, 64
	s_cmp_eq_u32 s12, 0x100000
	v_mfma_f32_32x32x16_bf16 v[0:15], v[234:237], v[206:209], v[0:15]
	s_cbranch_scc0 .LBB0_147
	s_waitcnt vmcnt(8) lgkmcnt(0)
	s_barrier
	v_add_u32_e32 v202, v179, v177
	v_add_u32_e32 v222, v176, v177
	ds_read_b128 v[170:173], v202 offset:49152
	ds_read_b128 v[202:205], v202 offset:51200
	ds_read_b128 v[206:209], v222 offset:32768
	ds_read_b128 v[210:213], v222 offset:34816
	ds_read_b128 v[214:217], v222 offset:36864
	ds_read_b128 v[224:227], v222 offset:38912
	s_waitcnt lgkmcnt(9)
	v_mfma_f32_32x32x16_bf16 v[112:127], v[150:153], v[142:145], v[112:127]
	v_mfma_f32_32x32x16_bf16 v[96:111], v[150:153], v[130:133], v[96:111]
	s_waitcnt lgkmcnt(8)
	v_mfma_f32_32x32x16_bf16 v[80:95], v[146:149], v[142:145], v[80:95]
	v_mfma_f32_32x32x16_bf16 v[64:79], v[146:149], v[130:133], v[64:79]
	s_waitcnt lgkmcnt(7)
	v_mfma_f32_32x32x16_bf16 v[48:63], v[138:141], v[142:145], v[48:63]
	v_mfma_f32_32x32x16_bf16 v[32:47], v[138:141], v[130:133], v[32:47]
	s_waitcnt lgkmcnt(6)
	v_mfma_f32_32x32x16_bf16 v[16:31], v[134:137], v[142:145], v[16:31]
	v_mfma_f32_32x32x16_bf16 v[0:15], v[134:137], v[130:133], v[0:15]
	v_add_u32_e32 v134, v179, v178
	v_add_u32_e32 v150, v176, v178
	ds_read_b128 v[130:133], v134 offset:49152
	ds_read_b128 v[134:137], v134 offset:51200
	ds_read_b128 v[138:141], v150 offset:32768
	ds_read_b128 v[142:145], v150 offset:34816
	ds_read_b128 v[146:149], v150 offset:36864
	ds_read_b128 v[150:153], v150 offset:38912
	s_waitcnt lgkmcnt(9)
	v_mfma_f32_32x32x16_bf16 v[112:127], v[206:209], v[170:173], v[112:127]
	v_mfma_f32_32x32x16_bf16 v[96:111], v[206:209], v[202:205], v[96:111]
	s_waitcnt lgkmcnt(8)
	v_mfma_f32_32x32x16_bf16 v[80:95], v[210:213], v[170:173], v[80:95]
	v_mfma_f32_32x32x16_bf16 v[64:79], v[210:213], v[202:205], v[64:79]
	s_waitcnt lgkmcnt(7)
	v_mfma_f32_32x32x16_bf16 v[48:63], v[214:217], v[170:173], v[48:63]
	v_mfma_f32_32x32x16_bf16 v[32:47], v[214:217], v[202:205], v[32:47]
	s_waitcnt lgkmcnt(6)
	v_mfma_f32_32x32x16_bf16 v[0:15], v[224:227], v[202:205], v[0:15]
	s_waitcnt vmcnt(4) lgkmcnt(0)
	s_barrier
	v_add_u32_e32 v202, v199, v177
	v_add_u32_e32 v222, v200, v177
	v_mfma_f32_32x32x16_bf16 v[16:31], v[224:227], v[170:173], v[16:31]
	ds_read_b128 v[170:173], v202 offset:16384
	ds_read_b128 v[202:205], v202 offset:18432
	ds_read_b128 v[206:209], v222
	ds_read_b128 v[210:213], v222 offset:2048
	ds_read_b128 v[214:217], v222 offset:4096
	ds_read_b128 v[224:227], v222 offset:6144
	s_waitcnt lgkmcnt(9)
	v_mfma_f32_32x32x16_bf16 v[112:127], v[138:141], v[130:133], v[112:127]
	v_mfma_f32_32x32x16_bf16 v[96:111], v[138:141], v[134:137], v[96:111]
	s_waitcnt lgkmcnt(8)
	v_mfma_f32_32x32x16_bf16 v[80:95], v[142:145], v[130:133], v[80:95]
	v_mfma_f32_32x32x16_bf16 v[64:79], v[142:145], v[134:137], v[64:79]
	s_waitcnt lgkmcnt(7)
	v_mfma_f32_32x32x16_bf16 v[48:63], v[146:149], v[130:133], v[48:63]
	v_mfma_f32_32x32x16_bf16 v[32:47], v[146:149], v[134:137], v[32:47]
	s_waitcnt lgkmcnt(6)
	v_mfma_f32_32x32x16_bf16 v[16:31], v[150:153], v[130:133], v[16:31]
	v_mfma_f32_32x32x16_bf16 v[0:15], v[150:153], v[134:137], v[0:15]
	v_add_u32_e32 v134, v199, v178
	v_add_u32_e32 v150, v200, v178
	ds_read_b128 v[130:133], v134 offset:16384
	ds_read_b128 v[134:137], v134 offset:18432
	ds_read_b128 v[138:141], v150
	ds_read_b128 v[142:145], v150 offset:2048
	ds_read_b128 v[146:149], v150 offset:4096
	ds_read_b128 v[150:153], v150 offset:6144
	s_waitcnt lgkmcnt(9)
	v_mfma_f32_32x32x16_bf16 v[112:127], v[206:209], v[170:173], v[112:127]
	v_mfma_f32_32x32x16_bf16 v[96:111], v[206:209], v[202:205], v[96:111]
	s_waitcnt lgkmcnt(8)
	v_mfma_f32_32x32x16_bf16 v[80:95], v[210:213], v[170:173], v[80:95]
	v_mfma_f32_32x32x16_bf16 v[64:79], v[210:213], v[202:205], v[64:79]
	s_waitcnt lgkmcnt(7)
	v_mfma_f32_32x32x16_bf16 v[48:63], v[214:217], v[170:173], v[48:63]
	v_mfma_f32_32x32x16_bf16 v[32:47], v[214:217], v[202:205], v[32:47]
	s_waitcnt lgkmcnt(6)
	v_mfma_f32_32x32x16_bf16 v[0:15], v[224:227], v[202:205], v[0:15]
	s_waitcnt vmcnt(0) lgkmcnt(0)
	s_barrier
	v_add_u32_e32 v202, v197, v177
	v_add_u32_e32 v222, v198, v177
	v_mfma_f32_32x32x16_bf16 v[16:31], v[224:227], v[170:173], v[16:31]
	ds_read_b128 v[170:173], v202 offset:16384
	ds_read_b128 v[202:205], v202 offset:18432
	ds_read_b128 v[206:209], v222
	ds_read_b128 v[210:213], v222 offset:2048
	ds_read_b128 v[214:217], v222 offset:4096
	ds_read_b128 v[224:227], v222 offset:6144
	s_waitcnt lgkmcnt(9)
	v_mfma_f32_32x32x16_bf16 v[112:127], v[138:141], v[130:133], v[112:127]
	v_mfma_f32_32x32x16_bf16 v[96:111], v[138:141], v[134:137], v[96:111]
	s_waitcnt lgkmcnt(8)
	v_mfma_f32_32x32x16_bf16 v[80:95], v[142:145], v[130:133], v[80:95]
	v_mfma_f32_32x32x16_bf16 v[64:79], v[142:145], v[134:137], v[64:79]
	s_waitcnt lgkmcnt(7)
	v_mfma_f32_32x32x16_bf16 v[48:63], v[146:149], v[130:133], v[48:63]
	v_mfma_f32_32x32x16_bf16 v[32:47], v[146:149], v[134:137], v[32:47]
	s_waitcnt lgkmcnt(6)
	v_mfma_f32_32x32x16_bf16 v[16:31], v[150:153], v[130:133], v[16:31]
	v_mfma_f32_32x32x16_bf16 v[0:15], v[150:153], v[134:137], v[0:15]
	v_add_u32_e32 v134, v197, v178
	v_add_u32_e32 v150, v198, v178
	ds_read_b128 v[130:133], v134 offset:16384
	ds_read_b128 v[134:137], v134 offset:18432
	ds_read_b128 v[138:141], v150
	ds_read_b128 v[142:145], v150 offset:2048
	ds_read_b128 v[146:149], v150 offset:4096
	ds_read_b128 v[150:153], v150 offset:6144
	s_waitcnt lgkmcnt(9)
	v_mfma_f32_32x32x16_bf16 v[112:127], v[206:209], v[170:173], v[112:127]
	v_mfma_f32_32x32x16_bf16 v[96:111], v[206:209], v[202:205], v[96:111]
	s_waitcnt lgkmcnt(8)
	v_mfma_f32_32x32x16_bf16 v[80:95], v[210:213], v[170:173], v[80:95]
	v_mfma_f32_32x32x16_bf16 v[64:79], v[210:213], v[202:205], v[64:79]
	s_waitcnt lgkmcnt(7)
	v_mfma_f32_32x32x16_bf16 v[48:63], v[214:217], v[170:173], v[48:63]
	v_mfma_f32_32x32x16_bf16 v[32:47], v[214:217], v[202:205], v[32:47]
	s_waitcnt lgkmcnt(6)
	v_mfma_f32_32x32x16_bf16 v[16:31], v[224:227], v[170:173], v[16:31]
	v_mfma_f32_32x32x16_bf16 v[0:15], v[224:227], v[202:205], v[0:15]
	s_waitcnt lgkmcnt(3)
	v_mfma_f32_32x32x16_bf16 v[96:111], v[138:141], v[134:137], v[96:111]
	v_mfma_f32_32x32x16_bf16 v[112:127], v[138:141], v[130:133], v[112:127]
	s_nop 10
	v_cvt_pk_bf16_f32 v96, v96, s0
	v_cvt_pk_bf16_f32 v98, v98, s0
	s_waitcnt lgkmcnt(2)
	v_mfma_f32_32x32x16_bf16 v[80:95], v[142:145], v[130:133], v[80:95]
	v_cvt_pk_bf16_f32 v112, v112, s0
	s_waitcnt lgkmcnt(1)
	v_mfma_f32_32x32x16_bf16 v[48:63], v[146:149], v[130:133], v[48:63]
	s_nop 8
	v_cvt_pk_bf16_f32 v80, v80, s0
	s_waitcnt lgkmcnt(0)
	v_mfma_f32_32x32x16_bf16 v[16:31], v[150:153], v[130:133], v[16:31]
	v_or_b32_e32 v130, s11, v174
	v_ashrrev_i32_e32 v131, 31, v130
	v_lshl_add_u64 v[130:131], v[130:131], 1, v[158:159]
	v_cvt_pk_bf16_f32 v48, v48, s0
	v_mfma_f32_32x32x16_bf16 v[64:79], v[142:145], v[134:137], v[64:79]
	s_nop 6
	v_cvt_pk_bf16_f32 v16, v16, s0
	v_mfma_f32_32x32x16_bf16 v[32:47], v[146:149], v[134:137], v[32:47]
	s_nop 2
	v_cvt_pk_bf16_f32 v64, v64, s0
	v_cvt_pk_bf16_f32 v66, v66, s0
	v_mfma_f32_32x32x16_bf16 v[0:15], v[150:153], v[134:137], v[0:15]
	v_add_u32_e32 v134, s7, v128
	v_or_b32_e32 v132, v134, v181
	s_movk_i32 s7, 0x1800
	v_mad_i64_i32 v[132:133], s[12:13], v132, s7, v[130:131]
	global_store_short v[132:133], v96, off offset:64
	v_or_b32_e32 v96, v134, v182
	global_store_short v[132:133], v112, off
	v_mad_i64_i32 v[132:133], s[12:13], v96, s7, v[130:131]
	v_cvt_pk_bf16_f32 v96, v113, s0
	global_store_short v[132:133], v96, off
	v_cvt_pk_bf16_f32 v96, v97, s0
	global_store_short v[132:133], v96, off offset:64
	v_or_b32_e32 v96, v134, v183
	v_mad_i64_i32 v[96:97], s[12:13], v96, s7, v[130:131]
	v_cvt_pk_bf16_f32 v112, v114, s0
	global_store_short v[96:97], v112, off
	global_store_short v[96:97], v98, off offset:64
	v_or_b32_e32 v96, v134, v184
	v_mad_i64_i32 v[96:97], s[12:13], v96, s7, v[130:131]
	v_cvt_pk_bf16_f32 v98, v115, s0
	global_store_short v[96:97], v98, off
	v_cvt_pk_bf16_f32 v98, v99, s0
	global_store_short v[96:97], v98, off offset:64
	v_or_b32_e32 v96, v134, v185
	v_mad_i64_i32 v[96:97], s[12:13], v96, s7, v[130:131]
	v_cvt_pk_bf16_f32 v98, v116, s0
	global_store_short v[96:97], v98, off
	v_cvt_pk_bf16_f32 v98, v100, s0
	global_store_short v[96:97], v98, off offset:64
	v_or_b32_e32 v96, v134, v186
	v_mad_i64_i32 v[96:97], s[12:13], v96, s7, v[130:131]
	v_cvt_pk_bf16_f32 v98, v117, s0
	global_store_short v[96:97], v98, off
	v_cvt_pk_bf16_f32 v98, v101, s0
	global_store_short v[96:97], v98, off offset:64
	v_or_b32_e32 v96, v134, v187
	v_mad_i64_i32 v[96:97], s[12:13], v96, s7, v[130:131]
	v_cvt_pk_bf16_f32 v98, v118, s0
	global_store_short v[96:97], v98, off
	v_cvt_pk_bf16_f32 v98, v102, s0
	global_store_short v[96:97], v98, off offset:64
	v_or_b32_e32 v96, v134, v188
	v_mad_i64_i32 v[96:97], s[12:13], v96, s7, v[130:131]
	v_cvt_pk_bf16_f32 v98, v119, s0
	global_store_short v[96:97], v98, off
	v_cvt_pk_bf16_f32 v98, v103, s0
	global_store_short v[96:97], v98, off offset:64
	v_or_b32_e32 v96, v134, v189
	v_mad_i64_i32 v[96:97], s[12:13], v96, s7, v[130:131]
	v_cvt_pk_bf16_f32 v98, v120, s0
	global_store_short v[96:97], v98, off
	v_cvt_pk_bf16_f32 v98, v104, s0
	global_store_short v[96:97], v98, off offset:64
	v_or_b32_e32 v96, v134, v190
	v_mad_i64_i32 v[96:97], s[12:13], v96, s7, v[130:131]
	v_cvt_pk_bf16_f32 v98, v121, s0
	global_store_short v[96:97], v98, off
	v_cvt_pk_bf16_f32 v98, v105, s0
	global_store_short v[96:97], v98, off offset:64
	v_or_b32_e32 v96, v134, v191
	v_mad_i64_i32 v[96:97], s[12:13], v96, s7, v[130:131]
	v_cvt_pk_bf16_f32 v98, v122, s0
	global_store_short v[96:97], v98, off
	v_cvt_pk_bf16_f32 v98, v106, s0
	global_store_short v[96:97], v98, off offset:64
	v_or_b32_e32 v96, v134, v192
	v_mad_i64_i32 v[96:97], s[12:13], v96, s7, v[130:131]
	v_cvt_pk_bf16_f32 v98, v123, s0
	global_store_short v[96:97], v98, off
	v_cvt_pk_bf16_f32 v98, v107, s0
	global_store_short v[96:97], v98, off offset:64
	v_or_b32_e32 v96, v134, v193
	v_mad_i64_i32 v[96:97], s[12:13], v96, s7, v[130:131]
	v_cvt_pk_bf16_f32 v98, v124, s0
	global_store_short v[96:97], v98, off
	v_cvt_pk_bf16_f32 v98, v108, s0
	global_store_short v[96:97], v98, off offset:64
	v_or_b32_e32 v96, v134, v194
	v_mad_i64_i32 v[96:97], s[12:13], v96, s7, v[130:131]
	v_cvt_pk_bf16_f32 v98, v125, s0
	global_store_short v[96:97], v98, off
	v_cvt_pk_bf16_f32 v98, v109, s0
	global_store_short v[96:97], v98, off offset:64
	v_or_b32_e32 v96, v134, v195
	v_mad_i64_i32 v[96:97], s[12:13], v96, s7, v[130:131]
	v_cvt_pk_bf16_f32 v98, v126, s0
	global_store_short v[96:97], v98, off
	v_cvt_pk_bf16_f32 v98, v110, s0
	global_store_short v[96:97], v98, off offset:64
	v_or_b32_e32 v96, v134, v196
	v_mad_i64_i32 v[96:97], s[12:13], v96, s7, v[130:131]
	v_cvt_pk_bf16_f32 v98, v127, s0
	global_store_short v[96:97], v98, off
	v_cvt_pk_bf16_f32 v98, v111, s0
	global_store_short v[96:97], v98, off offset:64
	v_or_b32_e32 v98, 32, v134
	v_or_b32_e32 v96, v98, v181
	v_mad_i64_i32 v[96:97], s[12:13], v96, s7, v[130:131]
	global_store_short v[96:97], v64, off offset:64
	v_or_b32_e32 v64, v98, v182
	global_store_short v[96:97], v80, off
	v_mad_i64_i32 v[96:97], s[12:13], v64, s7, v[130:131]
	v_cvt_pk_bf16_f32 v64, v81, s0
	global_store_short v[96:97], v64, off
	v_cvt_pk_bf16_f32 v64, v65, s0
	global_store_short v[96:97], v64, off offset:64
	v_or_b32_e32 v64, v98, v183
	v_mad_i64_i32 v[64:65], s[12:13], v64, s7, v[130:131]
	v_cvt_pk_bf16_f32 v80, v82, s0
	global_store_short v[64:65], v80, off
	global_store_short v[64:65], v66, off offset:64
	v_or_b32_e32 v64, v98, v184
	v_mad_i64_i32 v[64:65], s[12:13], v64, s7, v[130:131]
	v_cvt_pk_bf16_f32 v66, v83, s0
	global_store_short v[64:65], v66, off
	v_cvt_pk_bf16_f32 v66, v67, s0
	global_store_short v[64:65], v66, off offset:64
	v_or_b32_e32 v64, v98, v185
	v_mad_i64_i32 v[64:65], s[12:13], v64, s7, v[130:131]
	v_cvt_pk_bf16_f32 v66, v84, s0
	global_store_short v[64:65], v66, off
	v_cvt_pk_bf16_f32 v66, v68, s0
	global_store_short v[64:65], v66, off offset:64
	v_or_b32_e32 v64, v98, v186
	v_mad_i64_i32 v[64:65], s[12:13], v64, s7, v[130:131]
	v_cvt_pk_bf16_f32 v66, v85, s0
	global_store_short v[64:65], v66, off
	v_cvt_pk_bf16_f32 v66, v69, s0
	global_store_short v[64:65], v66, off offset:64
	v_or_b32_e32 v64, v98, v187
	v_mad_i64_i32 v[64:65], s[12:13], v64, s7, v[130:131]
	v_cvt_pk_bf16_f32 v66, v86, s0
	global_store_short v[64:65], v66, off
	v_cvt_pk_bf16_f32 v66, v70, s0
	global_store_short v[64:65], v66, off offset:64
	v_or_b32_e32 v64, v98, v188
	v_mad_i64_i32 v[64:65], s[12:13], v64, s7, v[130:131]
	v_cvt_pk_bf16_f32 v66, v87, s0
	global_store_short v[64:65], v66, off
	v_cvt_pk_bf16_f32 v66, v71, s0
	global_store_short v[64:65], v66, off offset:64
	v_or_b32_e32 v64, v98, v189
	v_mad_i64_i32 v[64:65], s[12:13], v64, s7, v[130:131]
	v_cvt_pk_bf16_f32 v66, v88, s0
	global_store_short v[64:65], v66, off
	v_cvt_pk_bf16_f32 v66, v72, s0
	global_store_short v[64:65], v66, off offset:64
	v_or_b32_e32 v64, v98, v190
	v_mad_i64_i32 v[64:65], s[12:13], v64, s7, v[130:131]
	v_cvt_pk_bf16_f32 v66, v89, s0
	global_store_short v[64:65], v66, off
	v_cvt_pk_bf16_f32 v66, v73, s0
	global_store_short v[64:65], v66, off offset:64
	v_or_b32_e32 v64, v98, v191
	v_mad_i64_i32 v[64:65], s[12:13], v64, s7, v[130:131]
	v_cvt_pk_bf16_f32 v66, v90, s0
	global_store_short v[64:65], v66, off
	v_cvt_pk_bf16_f32 v66, v74, s0
	global_store_short v[64:65], v66, off offset:64
	v_or_b32_e32 v64, v98, v192
	v_mad_i64_i32 v[64:65], s[12:13], v64, s7, v[130:131]
	v_cvt_pk_bf16_f32 v66, v91, s0
	global_store_short v[64:65], v66, off
	v_cvt_pk_bf16_f32 v66, v75, s0
	global_store_short v[64:65], v66, off offset:64
	v_or_b32_e32 v64, v98, v193
	v_mad_i64_i32 v[64:65], s[12:13], v64, s7, v[130:131]
	v_cvt_pk_bf16_f32 v66, v92, s0
	global_store_short v[64:65], v66, off
	v_cvt_pk_bf16_f32 v66, v76, s0
	global_store_short v[64:65], v66, off offset:64
	v_or_b32_e32 v64, v98, v194
	v_mad_i64_i32 v[64:65], s[12:13], v64, s7, v[130:131]
	v_cvt_pk_bf16_f32 v66, v93, s0
	global_store_short v[64:65], v66, off
	v_cvt_pk_bf16_f32 v66, v77, s0
	global_store_short v[64:65], v66, off offset:64
	v_or_b32_e32 v64, v98, v195
	v_mad_i64_i32 v[64:65], s[12:13], v64, s7, v[130:131]
	v_cvt_pk_bf16_f32 v66, v94, s0
	global_store_short v[64:65], v66, off
	v_cvt_pk_bf16_f32 v66, v78, s0
	global_store_short v[64:65], v66, off offset:64
	v_or_b32_e32 v64, v98, v196
	v_mad_i64_i32 v[64:65], s[12:13], v64, s7, v[130:131]
	v_cvt_pk_bf16_f32 v66, v95, s0
	global_store_short v[64:65], v66, off
	v_cvt_pk_bf16_f32 v66, v79, s0
	global_store_short v[64:65], v66, off offset:64
	v_or_b32_e32 v66, 64, v134
	v_or_b32_e32 v64, v66, v181
	v_mad_i64_i32 v[64:65], s[12:13], v64, s7, v[130:131]
	v_cvt_pk_bf16_f32 v32, v32, s0
	global_store_short v[64:65], v32, off offset:64
	v_or_b32_e32 v32, v66, v182
	global_store_short v[64:65], v48, off
	v_mad_i64_i32 v[64:65], s[12:13], v32, s7, v[130:131]
	v_cvt_pk_bf16_f32 v32, v49, s0
	global_store_short v[64:65], v32, off
	v_cvt_pk_bf16_f32 v32, v33, s0
	global_store_short v[64:65], v32, off offset:64
	v_or_b32_e32 v32, v66, v183
	v_mad_i64_i32 v[32:33], s[12:13], v32, s7, v[130:131]
	v_cvt_pk_bf16_f32 v48, v50, s0
	v_cvt_pk_bf16_f32 v34, v34, s0
	global_store_short v[32:33], v48, off
	global_store_short v[32:33], v34, off offset:64
	v_or_b32_e32 v32, v66, v184
	v_mad_i64_i32 v[32:33], s[12:13], v32, s7, v[130:131]
	v_cvt_pk_bf16_f32 v34, v51, s0
	global_store_short v[32:33], v34, off
	v_cvt_pk_bf16_f32 v34, v35, s0
	global_store_short v[32:33], v34, off offset:64
	v_or_b32_e32 v32, v66, v185
	v_mad_i64_i32 v[32:33], s[12:13], v32, s7, v[130:131]
	v_cvt_pk_bf16_f32 v34, v52, s0
	global_store_short v[32:33], v34, off
	v_cvt_pk_bf16_f32 v34, v36, s0
	global_store_short v[32:33], v34, off offset:64
	v_or_b32_e32 v32, v66, v186
	v_mad_i64_i32 v[32:33], s[12:13], v32, s7, v[130:131]
	v_cvt_pk_bf16_f32 v34, v53, s0
	global_store_short v[32:33], v34, off
	v_cvt_pk_bf16_f32 v34, v37, s0
	global_store_short v[32:33], v34, off offset:64
	v_or_b32_e32 v32, v66, v187
	v_mad_i64_i32 v[32:33], s[12:13], v32, s7, v[130:131]
	v_cvt_pk_bf16_f32 v34, v54, s0
	global_store_short v[32:33], v34, off
	v_cvt_pk_bf16_f32 v34, v38, s0
	global_store_short v[32:33], v34, off offset:64
	v_or_b32_e32 v32, v66, v188
	v_mad_i64_i32 v[32:33], s[12:13], v32, s7, v[130:131]
	v_cvt_pk_bf16_f32 v34, v55, s0
	global_store_short v[32:33], v34, off
	v_cvt_pk_bf16_f32 v34, v39, s0
	global_store_short v[32:33], v34, off offset:64
	v_or_b32_e32 v32, v66, v189
	v_mad_i64_i32 v[32:33], s[12:13], v32, s7, v[130:131]
	v_cvt_pk_bf16_f32 v34, v56, s0
	global_store_short v[32:33], v34, off
	v_cvt_pk_bf16_f32 v34, v40, s0
	global_store_short v[32:33], v34, off offset:64
	v_or_b32_e32 v32, v66, v190
	v_mad_i64_i32 v[32:33], s[12:13], v32, s7, v[130:131]
	v_cvt_pk_bf16_f32 v34, v57, s0
	global_store_short v[32:33], v34, off
	v_cvt_pk_bf16_f32 v34, v41, s0
	global_store_short v[32:33], v34, off offset:64
	v_or_b32_e32 v32, v66, v191
	v_mad_i64_i32 v[32:33], s[12:13], v32, s7, v[130:131]
	v_cvt_pk_bf16_f32 v34, v58, s0
	global_store_short v[32:33], v34, off
	v_cvt_pk_bf16_f32 v34, v42, s0
	global_store_short v[32:33], v34, off offset:64
	v_or_b32_e32 v32, v66, v192
	v_mad_i64_i32 v[32:33], s[12:13], v32, s7, v[130:131]
	v_cvt_pk_bf16_f32 v34, v59, s0
	global_store_short v[32:33], v34, off
	v_cvt_pk_bf16_f32 v34, v43, s0
	global_store_short v[32:33], v34, off offset:64
	v_or_b32_e32 v32, v66, v193
	v_mad_i64_i32 v[32:33], s[12:13], v32, s7, v[130:131]
	v_cvt_pk_bf16_f32 v34, v60, s0
	global_store_short v[32:33], v34, off
	v_cvt_pk_bf16_f32 v34, v44, s0
	global_store_short v[32:33], v34, off offset:64
	v_or_b32_e32 v32, v66, v194
	v_mad_i64_i32 v[32:33], s[12:13], v32, s7, v[130:131]
	v_cvt_pk_bf16_f32 v34, v61, s0
	global_store_short v[32:33], v34, off
	v_cvt_pk_bf16_f32 v34, v45, s0
	global_store_short v[32:33], v34, off offset:64
	v_or_b32_e32 v32, v66, v195
	v_mad_i64_i32 v[32:33], s[12:13], v32, s7, v[130:131]
	v_cvt_pk_bf16_f32 v34, v62, s0
	global_store_short v[32:33], v34, off
	v_cvt_pk_bf16_f32 v34, v46, s0
	global_store_short v[32:33], v34, off offset:64
	v_or_b32_e32 v32, v66, v196
	v_mad_i64_i32 v[32:33], s[12:13], v32, s7, v[130:131]
	v_cvt_pk_bf16_f32 v34, v63, s0
	global_store_short v[32:33], v34, off
	v_cvt_pk_bf16_f32 v34, v47, s0
	global_store_short v[32:33], v34, off offset:64
	v_or_b32_e32 v34, 0x60, v134
	v_or_b32_e32 v32, v34, v181
	v_mad_i64_i32 v[32:33], s[12:13], v32, s7, v[130:131]
	v_cvt_pk_bf16_f32 v0, v0, s0
	global_store_short v[32:33], v0, off offset:64
	v_or_b32_e32 v0, v34, v182
	global_store_short v[32:33], v16, off
	v_mad_i64_i32 v[32:33], s[12:13], v0, s7, v[130:131]
	v_cvt_pk_bf16_f32 v0, v17, s0
	global_store_short v[32:33], v0, off
	v_cvt_pk_bf16_f32 v0, v1, s0
	global_store_short v[32:33], v0, off offset:64
	v_or_b32_e32 v0, v34, v183
	v_mad_i64_i32 v[0:1], s[12:13], v0, s7, v[130:131]
	v_cvt_pk_bf16_f32 v16, v18, s0
	v_cvt_pk_bf16_f32 v2, v2, s0
	global_store_short v[0:1], v16, off
	global_store_short v[0:1], v2, off offset:64
	v_or_b32_e32 v0, v34, v184
	v_mad_i64_i32 v[0:1], s[12:13], v0, s7, v[130:131]
	v_cvt_pk_bf16_f32 v2, v19, s0
	global_store_short v[0:1], v2, off
	v_cvt_pk_bf16_f32 v2, v3, s0
	global_store_short v[0:1], v2, off offset:64
	v_or_b32_e32 v0, v34, v185
	v_mad_i64_i32 v[0:1], s[12:13], v0, s7, v[130:131]
	v_cvt_pk_bf16_f32 v2, v20, s0
	global_store_short v[0:1], v2, off
	v_cvt_pk_bf16_f32 v2, v4, s0
	global_store_short v[0:1], v2, off offset:64
	v_or_b32_e32 v0, v34, v186
	v_mad_i64_i32 v[0:1], s[12:13], v0, s7, v[130:131]
	v_cvt_pk_bf16_f32 v2, v21, s0
	global_store_short v[0:1], v2, off
	v_cvt_pk_bf16_f32 v2, v5, s0
	global_store_short v[0:1], v2, off offset:64
	v_or_b32_e32 v0, v34, v187
	v_mad_i64_i32 v[0:1], s[12:13], v0, s7, v[130:131]
	v_cvt_pk_bf16_f32 v2, v22, s0
	global_store_short v[0:1], v2, off
	v_cvt_pk_bf16_f32 v2, v6, s0
	global_store_short v[0:1], v2, off offset:64
	v_or_b32_e32 v0, v34, v188
	v_mad_i64_i32 v[0:1], s[12:13], v0, s7, v[130:131]
	v_cvt_pk_bf16_f32 v2, v23, s0
	global_store_short v[0:1], v2, off
	v_cvt_pk_bf16_f32 v2, v7, s0
	global_store_short v[0:1], v2, off offset:64
	v_or_b32_e32 v0, v34, v189
	v_mad_i64_i32 v[0:1], s[12:13], v0, s7, v[130:131]
	v_cvt_pk_bf16_f32 v2, v24, s0
	global_store_short v[0:1], v2, off
	v_cvt_pk_bf16_f32 v2, v8, s0
	global_store_short v[0:1], v2, off offset:64
	v_or_b32_e32 v0, v34, v190
	v_mad_i64_i32 v[0:1], s[12:13], v0, s7, v[130:131]
	v_cvt_pk_bf16_f32 v2, v25, s0
	global_store_short v[0:1], v2, off
	v_cvt_pk_bf16_f32 v2, v9, s0
	global_store_short v[0:1], v2, off offset:64
	v_or_b32_e32 v0, v34, v191
	v_mad_i64_i32 v[0:1], s[12:13], v0, s7, v[130:131]
	v_cvt_pk_bf16_f32 v2, v26, s0
	global_store_short v[0:1], v2, off
	v_cvt_pk_bf16_f32 v2, v10, s0
	global_store_short v[0:1], v2, off offset:64
	v_or_b32_e32 v0, v34, v192
	v_mad_i64_i32 v[0:1], s[12:13], v0, s7, v[130:131]
	v_cvt_pk_bf16_f32 v2, v27, s0
	global_store_short v[0:1], v2, off
	v_cvt_pk_bf16_f32 v2, v11, s0
	global_store_short v[0:1], v2, off offset:64
	v_or_b32_e32 v0, v34, v193
	v_mad_i64_i32 v[0:1], s[12:13], v0, s7, v[130:131]
	v_cvt_pk_bf16_f32 v2, v28, s0
	global_store_short v[0:1], v2, off
	v_cvt_pk_bf16_f32 v2, v12, s0
	global_store_short v[0:1], v2, off offset:64
	v_or_b32_e32 v0, v34, v194
	v_mad_i64_i32 v[0:1], s[12:13], v0, s7, v[130:131]
	v_cvt_pk_bf16_f32 v2, v29, s0
	global_store_short v[0:1], v2, off
	v_cvt_pk_bf16_f32 v2, v13, s0
	global_store_short v[0:1], v2, off offset:64
	v_or_b32_e32 v0, v34, v195
	v_mad_i64_i32 v[0:1], s[12:13], v0, s7, v[130:131]
	v_cvt_pk_bf16_f32 v2, v30, s0
	global_store_short v[0:1], v2, off
	v_cvt_pk_bf16_f32 v2, v14, s0
	global_store_short v[0:1], v2, off offset:64
	v_or_b32_e32 v0, v34, v196
	v_mad_i64_i32 v[0:1], s[12:13], v0, s7, v[130:131]
	v_readlane_b32 s7, v252, 7
	s_add_i32 s10, s10, s7
	s_add_i32 s4, s4, s7
	v_readlane_b32 s7, v252, 8
	v_cvt_pk_bf16_f32 v2, v31, s0
	s_add_i32 s6, s6, s7
	global_store_short v[0:1], v2, off
	v_cvt_pk_bf16_f32 v2, v15, s0
	s_cmpk_gt_i32 s10, 0x5f
	global_store_short v[0:1], v2, off offset:64
	s_cbranch_scc0 .LBB0_146

.LBB0_263:
	s_and_b32 s11, s10, 0x18000
	v_add_u32_e32 v222, s11, v180
	s_add_i32 s11, s10, 0xfffe8000
	s_and_b32 s11, s11, 0x18000
	v_or_b32_e32 v223, s11, v179
	v_add_u32_e32 v233, s11, v176
	s_waitcnt lgkmcnt(0)
	v_mfma_f32_32x32x16_bf16 v[112:127], v[150:153], v[142:145], v[112:127]
	v_mfma_f32_32x32x16_bf16 v[96:111], v[150:153], v[130:133], v[96:111]
	v_mfma_f32_32x32x16_bf16 v[80:95], v[146:149], v[142:145], v[80:95]
	v_mfma_f32_32x32x16_bf16 v[64:79], v[146:149], v[130:133], v[64:79]
	s_waitcnt vmcnt(8)
	s_barrier
	v_add_u32_e32 v206, v223, v177
	v_add_u32_e32 v234, v233, v177
	ds_read_b128 v[202:205], v206 offset:16384
	ds_read_b128 v[206:209], v206 offset:18432
	ds_read_b128 v[210:213], v234
	v_mfma_f32_32x32x16_bf16 v[48:63], v[138:141], v[142:145], v[48:63]
	v_mfma_f32_32x32x16_bf16 v[32:47], v[138:141], v[130:133], v[32:47]
	ds_read_b128 v[214:217], v234 offset:2048
	v_readfirstlane_b32 s11, v222
	s_mov_b32 m0, s11
	s_nop 0
	global_load_lds_dwordx4 v[170:171], off
	v_mfma_f32_32x32x16_bf16 v[16:31], v[134:137], v[142:145], v[16:31]
	v_mfma_f32_32x32x16_bf16 v[0:15], v[134:137], v[130:133], v[0:15]
	ds_read_b128 v[224:227], v234 offset:4096
	s_add_i32 s12, s11, 0x2000
	v_lshl_add_u64 v[150:151], v[170:171], 0, s[34:35]
	s_mov_b32 m0, s12
	s_nop 0
	global_load_lds_dwordx4 v[150:151], off
	ds_read_b128 v[234:237], v234 offset:6144
	s_waitcnt lgkmcnt(3)
	v_mfma_f32_32x32x16_bf16 v[112:127], v[210:213], v[202:205], v[112:127]
	v_add_u32_e32 v130, v223, v178
	v_add_u32_e32 v134, v233, v178
	ds_read_b128 v[142:145], v130 offset:16384
	v_mfma_f32_32x32x16_bf16 v[96:111], v[210:213], v[206:209], v[96:111]
	ds_read_b128 v[130:133], v130 offset:18432
	s_add_i32 s12, s11, 0x6000
	s_addk_i32 s11, 0x4000
	s_mov_b32 m0, s11
	s_nop 0
	global_load_lds_dwordx4 v[172:173], off
	s_waitcnt lgkmcnt(4)
	v_mfma_f32_32x32x16_bf16 v[80:95], v[214:217], v[202:205], v[80:95]
	ds_read_b128 v[150:153], v134
	v_mfma_f32_32x32x16_bf16 v[64:79], v[214:217], v[206:209], v[64:79]
	ds_read_b128 v[146:149], v134 offset:2048
	s_waitcnt lgkmcnt(5)
	v_mfma_f32_32x32x16_bf16 v[48:63], v[224:227], v[202:205], v[48:63]
	ds_read_b128 v[138:141], v134 offset:4096
	v_mfma_f32_32x32x16_bf16 v[32:47], v[224:227], v[206:209], v[32:47]
	ds_read_b128 v[134:137], v134 offset:6144
	v_lshl_add_u64 v[222:223], v[172:173], 0, s[34:35]
	s_mov_b32 m0, s12
	s_nop 0
	global_load_lds_dwordx4 v[222:223], off
	s_waitcnt lgkmcnt(6)
	v_mfma_f32_32x32x16_bf16 v[16:31], v[234:237], v[202:205], v[16:31]
	s_add_i32 s10, s10, 0x8000
	v_lshl_add_u64 v[170:171], v[170:171], 0, 64
	v_lshl_add_u64 v[172:173], v[172:173], 0, 64
	s_cmp_eq_u32 s10, 0x100000
	v_mfma_f32_32x32x16_bf16 v[0:15], v[234:237], v[206:209], v[0:15]
	s_cbranch_scc0 .LBB0_263
	s_waitcnt vmcnt(8) lgkmcnt(0)
	s_barrier
	v_add_u32_e32 v202, v179, v177
	v_add_u32_e32 v222, v176, v177
	ds_read_b128 v[170:173], v202 offset:49152
	ds_read_b128 v[202:205], v202 offset:51200
	ds_read_b128 v[206:209], v222 offset:32768
	ds_read_b128 v[210:213], v222 offset:34816
	ds_read_b128 v[214:217], v222 offset:36864
	ds_read_b128 v[224:227], v222 offset:38912
	s_waitcnt lgkmcnt(9)
	v_mfma_f32_32x32x16_bf16 v[112:127], v[150:153], v[142:145], v[112:127]
	v_mfma_f32_32x32x16_bf16 v[96:111], v[150:153], v[130:133], v[96:111]
	s_waitcnt lgkmcnt(8)
	v_mfma_f32_32x32x16_bf16 v[80:95], v[146:149], v[142:145], v[80:95]
	v_mfma_f32_32x32x16_bf16 v[64:79], v[146:149], v[130:133], v[64:79]
	s_waitcnt lgkmcnt(7)
	v_mfma_f32_32x32x16_bf16 v[48:63], v[138:141], v[142:145], v[48:63]
	v_mfma_f32_32x32x16_bf16 v[32:47], v[138:141], v[130:133], v[32:47]
	s_waitcnt lgkmcnt(6)
	v_mfma_f32_32x32x16_bf16 v[16:31], v[134:137], v[142:145], v[16:31]
	v_mfma_f32_32x32x16_bf16 v[0:15], v[134:137], v[130:133], v[0:15]
	v_add_u32_e32 v134, v179, v178
	v_add_u32_e32 v150, v176, v178
	ds_read_b128 v[130:133], v134 offset:49152
	ds_read_b128 v[134:137], v134 offset:51200
	ds_read_b128 v[138:141], v150 offset:32768
	ds_read_b128 v[142:145], v150 offset:34816
	ds_read_b128 v[146:149], v150 offset:36864
	ds_read_b128 v[150:153], v150 offset:38912
	s_waitcnt lgkmcnt(9)
	v_mfma_f32_32x32x16_bf16 v[112:127], v[206:209], v[170:173], v[112:127]
	v_mfma_f32_32x32x16_bf16 v[96:111], v[206:209], v[202:205], v[96:111]
	s_waitcnt lgkmcnt(8)
	v_mfma_f32_32x32x16_bf16 v[80:95], v[210:213], v[170:173], v[80:95]
	v_mfma_f32_32x32x16_bf16 v[64:79], v[210:213], v[202:205], v[64:79]
	s_waitcnt lgkmcnt(7)
	v_mfma_f32_32x32x16_bf16 v[48:63], v[214:217], v[170:173], v[48:63]
	v_mfma_f32_32x32x16_bf16 v[32:47], v[214:217], v[202:205], v[32:47]
	s_waitcnt lgkmcnt(6)
	v_mfma_f32_32x32x16_bf16 v[0:15], v[224:227], v[202:205], v[0:15]
	s_waitcnt vmcnt(4) lgkmcnt(0)
	s_barrier
	v_add_u32_e32 v202, v199, v177
	v_add_u32_e32 v222, v200, v177
	v_mfma_f32_32x32x16_bf16 v[16:31], v[224:227], v[170:173], v[16:31]
	ds_read_b128 v[170:173], v202 offset:16384
	ds_read_b128 v[202:205], v202 offset:18432
	ds_read_b128 v[206:209], v222
	ds_read_b128 v[210:213], v222 offset:2048
	ds_read_b128 v[214:217], v222 offset:4096
	ds_read_b128 v[224:227], v222 offset:6144
	s_waitcnt lgkmcnt(9)
	v_mfma_f32_32x32x16_bf16 v[112:127], v[138:141], v[130:133], v[112:127]
	v_mfma_f32_32x32x16_bf16 v[96:111], v[138:141], v[134:137], v[96:111]
	s_waitcnt lgkmcnt(8)
	v_mfma_f32_32x32x16_bf16 v[80:95], v[142:145], v[130:133], v[80:95]
	v_mfma_f32_32x32x16_bf16 v[64:79], v[142:145], v[134:137], v[64:79]
	s_waitcnt lgkmcnt(7)
	v_mfma_f32_32x32x16_bf16 v[48:63], v[146:149], v[130:133], v[48:63]
	v_mfma_f32_32x32x16_bf16 v[32:47], v[146:149], v[134:137], v[32:47]
	s_waitcnt lgkmcnt(6)
	v_mfma_f32_32x32x16_bf16 v[16:31], v[150:153], v[130:133], v[16:31]
	v_mfma_f32_32x32x16_bf16 v[0:15], v[150:153], v[134:137], v[0:15]
	v_add_u32_e32 v134, v199, v178
	v_add_u32_e32 v150, v200, v178
	ds_read_b128 v[130:133], v134 offset:16384
	ds_read_b128 v[134:137], v134 offset:18432
	ds_read_b128 v[138:141], v150
	ds_read_b128 v[142:145], v150 offset:2048
	ds_read_b128 v[146:149], v150 offset:4096
	ds_read_b128 v[150:153], v150 offset:6144
	s_waitcnt lgkmcnt(9)
	v_mfma_f32_32x32x16_bf16 v[112:127], v[206:209], v[170:173], v[112:127]
	v_mfma_f32_32x32x16_bf16 v[96:111], v[206:209], v[202:205], v[96:111]
	s_waitcnt lgkmcnt(8)
	v_mfma_f32_32x32x16_bf16 v[80:95], v[210:213], v[170:173], v[80:95]
	v_mfma_f32_32x32x16_bf16 v[64:79], v[210:213], v[202:205], v[64:79]
	s_waitcnt lgkmcnt(7)
	v_mfma_f32_32x32x16_bf16 v[48:63], v[214:217], v[170:173], v[48:63]
	v_mfma_f32_32x32x16_bf16 v[32:47], v[214:217], v[202:205], v[32:47]
	s_waitcnt lgkmcnt(6)
	v_mfma_f32_32x32x16_bf16 v[0:15], v[224:227], v[202:205], v[0:15]
	s_waitcnt vmcnt(0) lgkmcnt(0)
	s_barrier
	v_add_u32_e32 v202, v197, v177
	v_add_u32_e32 v222, v198, v177
	v_mfma_f32_32x32x16_bf16 v[16:31], v[224:227], v[170:173], v[16:31]
	ds_read_b128 v[170:173], v202 offset:16384
	ds_read_b128 v[202:205], v202 offset:18432
	ds_read_b128 v[206:209], v222
	ds_read_b128 v[210:213], v222 offset:2048
	ds_read_b128 v[214:217], v222 offset:4096
	ds_read_b128 v[224:227], v222 offset:6144
	s_waitcnt lgkmcnt(9)
	v_mfma_f32_32x32x16_bf16 v[112:127], v[138:141], v[130:133], v[112:127]
	v_mfma_f32_32x32x16_bf16 v[96:111], v[138:141], v[134:137], v[96:111]
	s_waitcnt lgkmcnt(8)
	v_mfma_f32_32x32x16_bf16 v[80:95], v[142:145], v[130:133], v[80:95]
	v_mfma_f32_32x32x16_bf16 v[64:79], v[142:145], v[134:137], v[64:79]
	s_waitcnt lgkmcnt(7)
	v_mfma_f32_32x32x16_bf16 v[48:63], v[146:149], v[130:133], v[48:63]
	v_mfma_f32_32x32x16_bf16 v[32:47], v[146:149], v[134:137], v[32:47]
	s_waitcnt lgkmcnt(6)
	v_mfma_f32_32x32x16_bf16 v[16:31], v[150:153], v[130:133], v[16:31]
	v_mfma_f32_32x32x16_bf16 v[0:15], v[150:153], v[134:137], v[0:15]
	v_add_u32_e32 v134, v197, v178
	v_add_u32_e32 v150, v198, v178
	ds_read_b128 v[130:133], v134 offset:16384
	ds_read_b128 v[134:137], v134 offset:18432
	ds_read_b128 v[138:141], v150
	ds_read_b128 v[142:145], v150 offset:2048
	ds_read_b128 v[146:149], v150 offset:4096
	ds_read_b128 v[150:153], v150 offset:6144
	s_waitcnt lgkmcnt(9)
	v_mfma_f32_32x32x16_bf16 v[112:127], v[206:209], v[170:173], v[112:127]
	v_mfma_f32_32x32x16_bf16 v[96:111], v[206:209], v[202:205], v[96:111]
	s_waitcnt lgkmcnt(8)
	v_mfma_f32_32x32x16_bf16 v[80:95], v[210:213], v[170:173], v[80:95]
	v_mfma_f32_32x32x16_bf16 v[64:79], v[210:213], v[202:205], v[64:79]
	s_waitcnt lgkmcnt(7)
	v_mfma_f32_32x32x16_bf16 v[48:63], v[214:217], v[170:173], v[48:63]
	v_mfma_f32_32x32x16_bf16 v[32:47], v[214:217], v[202:205], v[32:47]
	s_waitcnt lgkmcnt(6)
	v_mfma_f32_32x32x16_bf16 v[16:31], v[224:227], v[170:173], v[16:31]
	v_mfma_f32_32x32x16_bf16 v[0:15], v[224:227], v[202:205], v[0:15]
	s_waitcnt lgkmcnt(3)
	v_mfma_f32_32x32x16_bf16 v[112:127], v[138:141], v[130:133], v[112:127]
	v_mfma_f32_32x32x16_bf16 v[96:111], v[138:141], v[134:137], v[96:111]
	s_nop 10
	v_cvt_pk_bf16_f32 v112, v112, s0
	s_waitcnt lgkmcnt(2)
	v_mfma_f32_32x32x16_bf16 v[80:95], v[142:145], v[130:133], v[80:95]
	v_cvt_pk_bf16_f32 v96, v96, s0
	v_cvt_pk_bf16_f32 v98, v98, s0
	s_waitcnt lgkmcnt(1)
	v_mfma_f32_32x32x16_bf16 v[48:63], v[146:149], v[130:133], v[48:63]
	s_nop 7
	v_cvt_pk_bf16_f32 v80, v80, s0
	s_waitcnt lgkmcnt(0)
	v_mfma_f32_32x32x16_bf16 v[16:31], v[150:153], v[130:133], v[16:31]
	v_add_u32_e32 v132, s5, v128
	v_or_b32_e32 v130, s7, v174
	v_ashrrev_i32_e32 v131, 31, v130
	v_lshl_add_u64 v[130:131], v[130:131], 1, v[158:159]
	v_cvt_pk_bf16_f32 v48, v48, s0
	v_readlane_b32 s5, v252, 7
	s_add_i32 s6, s6, s5
	v_mfma_f32_32x32x16_bf16 v[64:79], v[142:145], v[134:137], v[64:79]
	s_nop 3
	v_cvt_pk_bf16_f32 v16, v16, s0
	s_add_i32 s2, s2, s5
	v_readlane_b32 s5, v252, 8
	s_add_i32 s4, s4, s5
	s_cmp_gt_i32 s6, 31
	s_nop 2
	v_cvt_pk_bf16_f32 v64, v64, s0
	v_mfma_f32_32x32x16_bf16 v[32:47], v[146:149], v[134:137], v[32:47]
	v_cvt_pk_bf16_f32 v66, v66, s0
	v_mfma_f32_32x32x16_bf16 v[0:15], v[150:153], v[134:137], v[0:15]
	v_or_b32_e32 v134, v132, v181
	v_ashrrev_i32_e32 v135, 31, v134
	v_lshlrev_b64 v[134:135], 11, v[134:135]
	v_lshl_add_u64 v[134:135], v[130:131], 0, v[134:135]
	global_store_short v[134:135], v112, off
	global_store_short v[134:135], v96, off offset:64
	v_or_b32_e32 v134, v132, v182
	v_ashrrev_i32_e32 v135, 31, v134
	v_lshlrev_b64 v[134:135], 11, v[134:135]
	v_lshl_add_u64 v[134:135], v[130:131], 0, v[134:135]
	v_cvt_pk_bf16_f32 v96, v113, s0
	global_store_short v[134:135], v96, off
	v_cvt_pk_bf16_f32 v96, v97, s0
	global_store_short v[134:135], v96, off offset:64
	v_or_b32_e32 v96, v132, v183
	v_ashrrev_i32_e32 v97, 31, v96
	v_lshlrev_b64 v[96:97], 11, v[96:97]
	v_lshl_add_u64 v[96:97], v[130:131], 0, v[96:97]
	v_cvt_pk_bf16_f32 v112, v114, s0
	global_store_short v[96:97], v112, off
	global_store_short v[96:97], v98, off offset:64
	v_or_b32_e32 v96, v132, v184
	v_ashrrev_i32_e32 v97, 31, v96
	v_lshlrev_b64 v[96:97], 11, v[96:97]
	v_lshl_add_u64 v[96:97], v[130:131], 0, v[96:97]
	v_cvt_pk_bf16_f32 v98, v115, s0
	global_store_short v[96:97], v98, off
	v_cvt_pk_bf16_f32 v98, v99, s0
	global_store_short v[96:97], v98, off offset:64
	v_or_b32_e32 v96, v132, v185
	v_ashrrev_i32_e32 v97, 31, v96
	v_lshlrev_b64 v[96:97], 11, v[96:97]
	v_lshl_add_u64 v[96:97], v[130:131], 0, v[96:97]
	v_cvt_pk_bf16_f32 v98, v116, s0
	global_store_short v[96:97], v98, off
	v_cvt_pk_bf16_f32 v98, v100, s0
	global_store_short v[96:97], v98, off offset:64
	v_or_b32_e32 v96, v132, v186
	v_ashrrev_i32_e32 v97, 31, v96
	v_lshlrev_b64 v[96:97], 11, v[96:97]
	v_lshl_add_u64 v[96:97], v[130:131], 0, v[96:97]
	v_cvt_pk_bf16_f32 v98, v117, s0
	global_store_short v[96:97], v98, off
	v_cvt_pk_bf16_f32 v98, v101, s0
	global_store_short v[96:97], v98, off offset:64
	v_or_b32_e32 v96, v132, v187
	v_ashrrev_i32_e32 v97, 31, v96
	v_lshlrev_b64 v[96:97], 11, v[96:97]
	v_lshl_add_u64 v[96:97], v[130:131], 0, v[96:97]
	v_cvt_pk_bf16_f32 v98, v118, s0
	global_store_short v[96:97], v98, off
	v_cvt_pk_bf16_f32 v98, v102, s0
	global_store_short v[96:97], v98, off offset:64
	v_or_b32_e32 v96, v132, v188
	v_ashrrev_i32_e32 v97, 31, v96
	v_lshlrev_b64 v[96:97], 11, v[96:97]
	v_lshl_add_u64 v[96:97], v[130:131], 0, v[96:97]
	v_cvt_pk_bf16_f32 v98, v119, s0
	global_store_short v[96:97], v98, off
	v_cvt_pk_bf16_f32 v98, v103, s0
	global_store_short v[96:97], v98, off offset:64
	v_or_b32_e32 v96, v132, v189
	v_ashrrev_i32_e32 v97, 31, v96
	v_lshlrev_b64 v[96:97], 11, v[96:97]
	v_lshl_add_u64 v[96:97], v[130:131], 0, v[96:97]
	v_cvt_pk_bf16_f32 v98, v120, s0
	global_store_short v[96:97], v98, off
	v_cvt_pk_bf16_f32 v98, v104, s0
	global_store_short v[96:97], v98, off offset:64
	v_or_b32_e32 v96, v132, v190
	v_ashrrev_i32_e32 v97, 31, v96
	v_lshlrev_b64 v[96:97], 11, v[96:97]
	v_lshl_add_u64 v[96:97], v[130:131], 0, v[96:97]
	v_cvt_pk_bf16_f32 v98, v121, s0
	global_store_short v[96:97], v98, off
	v_cvt_pk_bf16_f32 v98, v105, s0
	global_store_short v[96:97], v98, off offset:64
	v_or_b32_e32 v96, v132, v191
	v_ashrrev_i32_e32 v97, 31, v96
	v_lshlrev_b64 v[96:97], 11, v[96:97]
	v_lshl_add_u64 v[96:97], v[130:131], 0, v[96:97]
	v_cvt_pk_bf16_f32 v98, v122, s0
	global_store_short v[96:97], v98, off
	v_cvt_pk_bf16_f32 v98, v106, s0
	global_store_short v[96:97], v98, off offset:64
	v_or_b32_e32 v96, v132, v192
	v_ashrrev_i32_e32 v97, 31, v96
	v_lshlrev_b64 v[96:97], 11, v[96:97]
	v_lshl_add_u64 v[96:97], v[130:131], 0, v[96:97]
	v_cvt_pk_bf16_f32 v98, v123, s0
	global_store_short v[96:97], v98, off
	v_cvt_pk_bf16_f32 v98, v107, s0
	global_store_short v[96:97], v98, off offset:64
	v_or_b32_e32 v96, v132, v193
	v_ashrrev_i32_e32 v97, 31, v96
	v_lshlrev_b64 v[96:97], 11, v[96:97]
	v_lshl_add_u64 v[96:97], v[130:131], 0, v[96:97]
	v_cvt_pk_bf16_f32 v98, v124, s0
	global_store_short v[96:97], v98, off
	v_cvt_pk_bf16_f32 v98, v108, s0
	global_store_short v[96:97], v98, off offset:64
	v_or_b32_e32 v96, v132, v194
	v_ashrrev_i32_e32 v97, 31, v96
	v_lshlrev_b64 v[96:97], 11, v[96:97]
	v_lshl_add_u64 v[96:97], v[130:131], 0, v[96:97]
	v_cvt_pk_bf16_f32 v98, v125, s0
	global_store_short v[96:97], v98, off
	v_cvt_pk_bf16_f32 v98, v109, s0
	global_store_short v[96:97], v98, off offset:64
	v_or_b32_e32 v96, v132, v195
	v_ashrrev_i32_e32 v97, 31, v96
	v_lshlrev_b64 v[96:97], 11, v[96:97]
	v_lshl_add_u64 v[96:97], v[130:131], 0, v[96:97]
	v_cvt_pk_bf16_f32 v98, v126, s0
	global_store_short v[96:97], v98, off
	v_cvt_pk_bf16_f32 v98, v110, s0
	global_store_short v[96:97], v98, off offset:64
	v_or_b32_e32 v96, v132, v196
	v_ashrrev_i32_e32 v97, 31, v96
	v_lshlrev_b64 v[96:97], 11, v[96:97]
	v_lshl_add_u64 v[96:97], v[130:131], 0, v[96:97]
	v_cvt_pk_bf16_f32 v98, v127, s0
	global_store_short v[96:97], v98, off
	v_cvt_pk_bf16_f32 v98, v111, s0
	global_store_short v[96:97], v98, off offset:64
	v_or_b32_e32 v98, 32, v132
	v_or_b32_e32 v96, v98, v181
	v_ashrrev_i32_e32 v97, 31, v96
	v_lshlrev_b64 v[96:97], 11, v[96:97]
	v_lshl_add_u64 v[96:97], v[130:131], 0, v[96:97]
	global_store_short v[96:97], v80, off
	global_store_short v[96:97], v64, off offset:64
	v_or_b32_e32 v96, v98, v182
	v_ashrrev_i32_e32 v97, 31, v96
	v_lshlrev_b64 v[96:97], 11, v[96:97]
	v_lshl_add_u64 v[96:97], v[130:131], 0, v[96:97]
	v_cvt_pk_bf16_f32 v64, v81, s0
	global_store_short v[96:97], v64, off
	v_cvt_pk_bf16_f32 v64, v65, s0
	global_store_short v[96:97], v64, off offset:64
	v_or_b32_e32 v64, v98, v183
	v_ashrrev_i32_e32 v65, 31, v64
	v_lshlrev_b64 v[64:65], 11, v[64:65]
	v_lshl_add_u64 v[64:65], v[130:131], 0, v[64:65]
	v_cvt_pk_bf16_f32 v80, v82, s0
	global_store_short v[64:65], v80, off
	global_store_short v[64:65], v66, off offset:64
	v_or_b32_e32 v64, v98, v184
	v_ashrrev_i32_e32 v65, 31, v64
	v_lshlrev_b64 v[64:65], 11, v[64:65]
	v_lshl_add_u64 v[64:65], v[130:131], 0, v[64:65]
	v_cvt_pk_bf16_f32 v66, v83, s0
	global_store_short v[64:65], v66, off
	v_cvt_pk_bf16_f32 v66, v67, s0
	global_store_short v[64:65], v66, off offset:64
	v_or_b32_e32 v64, v98, v185
	v_ashrrev_i32_e32 v65, 31, v64
	v_lshlrev_b64 v[64:65], 11, v[64:65]
	v_lshl_add_u64 v[64:65], v[130:131], 0, v[64:65]
	v_cvt_pk_bf16_f32 v66, v84, s0
	global_store_short v[64:65], v66, off
	v_cvt_pk_bf16_f32 v66, v68, s0
	global_store_short v[64:65], v66, off offset:64
	v_or_b32_e32 v64, v98, v186
	v_ashrrev_i32_e32 v65, 31, v64
	v_lshlrev_b64 v[64:65], 11, v[64:65]
	v_lshl_add_u64 v[64:65], v[130:131], 0, v[64:65]
	v_cvt_pk_bf16_f32 v66, v85, s0
	global_store_short v[64:65], v66, off
	v_cvt_pk_bf16_f32 v66, v69, s0
	global_store_short v[64:65], v66, off offset:64
	v_or_b32_e32 v64, v98, v187
	v_ashrrev_i32_e32 v65, 31, v64
	v_lshlrev_b64 v[64:65], 11, v[64:65]
	v_lshl_add_u64 v[64:65], v[130:131], 0, v[64:65]
	v_cvt_pk_bf16_f32 v66, v86, s0
	global_store_short v[64:65], v66, off
	v_cvt_pk_bf16_f32 v66, v70, s0
	global_store_short v[64:65], v66, off offset:64
	v_or_b32_e32 v64, v98, v188
	v_ashrrev_i32_e32 v65, 31, v64
	v_lshlrev_b64 v[64:65], 11, v[64:65]
	v_lshl_add_u64 v[64:65], v[130:131], 0, v[64:65]
	v_cvt_pk_bf16_f32 v66, v87, s0
	global_store_short v[64:65], v66, off
	v_cvt_pk_bf16_f32 v66, v71, s0
	global_store_short v[64:65], v66, off offset:64
	v_or_b32_e32 v64, v98, v189
	v_ashrrev_i32_e32 v65, 31, v64
	v_lshlrev_b64 v[64:65], 11, v[64:65]
	v_lshl_add_u64 v[64:65], v[130:131], 0, v[64:65]
	v_cvt_pk_bf16_f32 v66, v88, s0
	global_store_short v[64:65], v66, off
	v_cvt_pk_bf16_f32 v66, v72, s0
	global_store_short v[64:65], v66, off offset:64
	v_or_b32_e32 v64, v98, v190
	v_ashrrev_i32_e32 v65, 31, v64
	v_lshlrev_b64 v[64:65], 11, v[64:65]
	v_lshl_add_u64 v[64:65], v[130:131], 0, v[64:65]
	v_cvt_pk_bf16_f32 v66, v89, s0
	global_store_short v[64:65], v66, off
	v_cvt_pk_bf16_f32 v66, v73, s0
	global_store_short v[64:65], v66, off offset:64
	v_or_b32_e32 v64, v98, v191
	v_ashrrev_i32_e32 v65, 31, v64
	v_lshlrev_b64 v[64:65], 11, v[64:65]
	v_lshl_add_u64 v[64:65], v[130:131], 0, v[64:65]
	v_cvt_pk_bf16_f32 v66, v90, s0
	global_store_short v[64:65], v66, off
	v_cvt_pk_bf16_f32 v66, v74, s0
	global_store_short v[64:65], v66, off offset:64
	v_or_b32_e32 v64, v98, v192
	v_ashrrev_i32_e32 v65, 31, v64
	v_lshlrev_b64 v[64:65], 11, v[64:65]
	v_lshl_add_u64 v[64:65], v[130:131], 0, v[64:65]
	v_cvt_pk_bf16_f32 v66, v91, s0
	global_store_short v[64:65], v66, off
	v_cvt_pk_bf16_f32 v66, v75, s0
	global_store_short v[64:65], v66, off offset:64
	v_or_b32_e32 v64, v98, v193
	v_ashrrev_i32_e32 v65, 31, v64
	v_lshlrev_b64 v[64:65], 11, v[64:65]
	v_lshl_add_u64 v[64:65], v[130:131], 0, v[64:65]
	v_cvt_pk_bf16_f32 v66, v92, s0
	global_store_short v[64:65], v66, off
	v_cvt_pk_bf16_f32 v66, v76, s0
	global_store_short v[64:65], v66, off offset:64
	v_or_b32_e32 v64, v98, v194
	v_ashrrev_i32_e32 v65, 31, v64
	v_lshlrev_b64 v[64:65], 11, v[64:65]
	v_lshl_add_u64 v[64:65], v[130:131], 0, v[64:65]
	v_cvt_pk_bf16_f32 v66, v93, s0
	global_store_short v[64:65], v66, off
	v_cvt_pk_bf16_f32 v66, v77, s0
	global_store_short v[64:65], v66, off offset:64
	v_or_b32_e32 v64, v98, v195
	v_ashrrev_i32_e32 v65, 31, v64
	v_lshlrev_b64 v[64:65], 11, v[64:65]
	v_lshl_add_u64 v[64:65], v[130:131], 0, v[64:65]
	v_cvt_pk_bf16_f32 v66, v94, s0
	global_store_short v[64:65], v66, off
	v_cvt_pk_bf16_f32 v66, v78, s0
	global_store_short v[64:65], v66, off offset:64
	v_or_b32_e32 v64, v98, v196
	v_ashrrev_i32_e32 v65, 31, v64
	v_lshlrev_b64 v[64:65], 11, v[64:65]
	v_lshl_add_u64 v[64:65], v[130:131], 0, v[64:65]
	v_cvt_pk_bf16_f32 v66, v95, s0
	global_store_short v[64:65], v66, off
	v_cvt_pk_bf16_f32 v66, v79, s0
	global_store_short v[64:65], v66, off offset:64
	v_or_b32_e32 v66, 64, v132
	v_or_b32_e32 v64, v66, v181
	v_ashrrev_i32_e32 v65, 31, v64
	v_lshlrev_b64 v[64:65], 11, v[64:65]
	v_lshl_add_u64 v[64:65], v[130:131], 0, v[64:65]
	v_cvt_pk_bf16_f32 v32, v32, s0
	global_store_short v[64:65], v48, off
	global_store_short v[64:65], v32, off offset:64
	v_or_b32_e32 v64, v66, v182
	v_ashrrev_i32_e32 v65, 31, v64
	v_lshlrev_b64 v[64:65], 11, v[64:65]
	v_lshl_add_u64 v[64:65], v[130:131], 0, v[64:65]
	v_cvt_pk_bf16_f32 v32, v49, s0
	global_store_short v[64:65], v32, off
	v_cvt_pk_bf16_f32 v32, v33, s0
	global_store_short v[64:65], v32, off offset:64
	v_or_b32_e32 v32, v66, v183
	v_ashrrev_i32_e32 v33, 31, v32
	v_lshlrev_b64 v[32:33], 11, v[32:33]
	v_lshl_add_u64 v[32:33], v[130:131], 0, v[32:33]
	v_cvt_pk_bf16_f32 v48, v50, s0
	v_cvt_pk_bf16_f32 v34, v34, s0
	global_store_short v[32:33], v48, off
	global_store_short v[32:33], v34, off offset:64
	v_or_b32_e32 v32, v66, v184
	v_ashrrev_i32_e32 v33, 31, v32
	v_lshlrev_b64 v[32:33], 11, v[32:33]
	v_lshl_add_u64 v[32:33], v[130:131], 0, v[32:33]
	v_cvt_pk_bf16_f32 v34, v51, s0
	global_store_short v[32:33], v34, off
	v_cvt_pk_bf16_f32 v34, v35, s0
	global_store_short v[32:33], v34, off offset:64
	v_or_b32_e32 v32, v66, v185
	v_ashrrev_i32_e32 v33, 31, v32
	v_lshlrev_b64 v[32:33], 11, v[32:33]
	v_lshl_add_u64 v[32:33], v[130:131], 0, v[32:33]
	v_cvt_pk_bf16_f32 v34, v52, s0
	global_store_short v[32:33], v34, off
	v_cvt_pk_bf16_f32 v34, v36, s0
	global_store_short v[32:33], v34, off offset:64
	v_or_b32_e32 v32, v66, v186
	v_ashrrev_i32_e32 v33, 31, v32
	v_lshlrev_b64 v[32:33], 11, v[32:33]
	v_lshl_add_u64 v[32:33], v[130:131], 0, v[32:33]
	v_cvt_pk_bf16_f32 v34, v53, s0
	global_store_short v[32:33], v34, off
	v_cvt_pk_bf16_f32 v34, v37, s0
	global_store_short v[32:33], v34, off offset:64
	v_or_b32_e32 v32, v66, v187
	v_ashrrev_i32_e32 v33, 31, v32
	v_lshlrev_b64 v[32:33], 11, v[32:33]
	v_lshl_add_u64 v[32:33], v[130:131], 0, v[32:33]
	v_cvt_pk_bf16_f32 v34, v54, s0
	global_store_short v[32:33], v34, off
	v_cvt_pk_bf16_f32 v34, v38, s0
	global_store_short v[32:33], v34, off offset:64
	v_or_b32_e32 v32, v66, v188
	v_ashrrev_i32_e32 v33, 31, v32
	v_lshlrev_b64 v[32:33], 11, v[32:33]
	v_lshl_add_u64 v[32:33], v[130:131], 0, v[32:33]
	v_cvt_pk_bf16_f32 v34, v55, s0
	global_store_short v[32:33], v34, off
	v_cvt_pk_bf16_f32 v34, v39, s0
	global_store_short v[32:33], v34, off offset:64
	v_or_b32_e32 v32, v66, v189
	v_ashrrev_i32_e32 v33, 31, v32
	v_lshlrev_b64 v[32:33], 11, v[32:33]
	v_lshl_add_u64 v[32:33], v[130:131], 0, v[32:33]
	v_cvt_pk_bf16_f32 v34, v56, s0
	global_store_short v[32:33], v34, off
	v_cvt_pk_bf16_f32 v34, v40, s0
	global_store_short v[32:33], v34, off offset:64
	v_or_b32_e32 v32, v66, v190
	v_ashrrev_i32_e32 v33, 31, v32
	v_lshlrev_b64 v[32:33], 11, v[32:33]
	v_lshl_add_u64 v[32:33], v[130:131], 0, v[32:33]
	v_cvt_pk_bf16_f32 v34, v57, s0
	global_store_short v[32:33], v34, off
	v_cvt_pk_bf16_f32 v34, v41, s0
	global_store_short v[32:33], v34, off offset:64
	v_or_b32_e32 v32, v66, v191
	v_ashrrev_i32_e32 v33, 31, v32
	v_lshlrev_b64 v[32:33], 11, v[32:33]
	v_lshl_add_u64 v[32:33], v[130:131], 0, v[32:33]
	v_cvt_pk_bf16_f32 v34, v58, s0
	global_store_short v[32:33], v34, off
	v_cvt_pk_bf16_f32 v34, v42, s0
	global_store_short v[32:33], v34, off offset:64
	v_or_b32_e32 v32, v66, v192
	v_ashrrev_i32_e32 v33, 31, v32
	v_lshlrev_b64 v[32:33], 11, v[32:33]
	v_lshl_add_u64 v[32:33], v[130:131], 0, v[32:33]
	v_cvt_pk_bf16_f32 v34, v59, s0
	global_store_short v[32:33], v34, off
	v_cvt_pk_bf16_f32 v34, v43, s0
	global_store_short v[32:33], v34, off offset:64
	v_or_b32_e32 v32, v66, v193
	v_ashrrev_i32_e32 v33, 31, v32
	v_lshlrev_b64 v[32:33], 11, v[32:33]
	v_lshl_add_u64 v[32:33], v[130:131], 0, v[32:33]
	v_cvt_pk_bf16_f32 v34, v60, s0
	global_store_short v[32:33], v34, off
	v_cvt_pk_bf16_f32 v34, v44, s0
	global_store_short v[32:33], v34, off offset:64
	v_or_b32_e32 v32, v66, v194
	v_ashrrev_i32_e32 v33, 31, v32
	v_lshlrev_b64 v[32:33], 11, v[32:33]
	v_lshl_add_u64 v[32:33], v[130:131], 0, v[32:33]
	v_cvt_pk_bf16_f32 v34, v61, s0
	global_store_short v[32:33], v34, off
	v_cvt_pk_bf16_f32 v34, v45, s0
	global_store_short v[32:33], v34, off offset:64
	v_or_b32_e32 v32, v66, v195
	v_ashrrev_i32_e32 v33, 31, v32
	v_lshlrev_b64 v[32:33], 11, v[32:33]
	v_lshl_add_u64 v[32:33], v[130:131], 0, v[32:33]
	v_cvt_pk_bf16_f32 v34, v62, s0
	global_store_short v[32:33], v34, off
	v_cvt_pk_bf16_f32 v34, v46, s0
	global_store_short v[32:33], v34, off offset:64
	v_or_b32_e32 v32, v66, v196
	v_ashrrev_i32_e32 v33, 31, v32
	v_lshlrev_b64 v[32:33], 11, v[32:33]
	v_lshl_add_u64 v[32:33], v[130:131], 0, v[32:33]
	v_cvt_pk_bf16_f32 v34, v63, s0
	global_store_short v[32:33], v34, off
	v_cvt_pk_bf16_f32 v34, v47, s0
	global_store_short v[32:33], v34, off offset:64
	v_or_b32_e32 v34, 0x60, v132
	v_or_b32_e32 v32, v34, v181
	v_ashrrev_i32_e32 v33, 31, v32
	v_lshlrev_b64 v[32:33], 11, v[32:33]
	v_lshl_add_u64 v[32:33], v[130:131], 0, v[32:33]
	v_cvt_pk_bf16_f32 v0, v0, s0
	global_store_short v[32:33], v16, off
	global_store_short v[32:33], v0, off offset:64
	v_or_b32_e32 v32, v34, v182
	v_ashrrev_i32_e32 v33, 31, v32
	v_lshlrev_b64 v[32:33], 11, v[32:33]
	v_lshl_add_u64 v[32:33], v[130:131], 0, v[32:33]
	v_cvt_pk_bf16_f32 v0, v17, s0
	global_store_short v[32:33], v0, off
	v_cvt_pk_bf16_f32 v0, v1, s0
	global_store_short v[32:33], v0, off offset:64
	v_or_b32_e32 v0, v34, v183
	v_ashrrev_i32_e32 v1, 31, v0
	v_lshlrev_b64 v[0:1], 11, v[0:1]
	v_lshl_add_u64 v[0:1], v[130:131], 0, v[0:1]
	v_cvt_pk_bf16_f32 v16, v18, s0
	v_cvt_pk_bf16_f32 v2, v2, s0
	global_store_short v[0:1], v16, off
	global_store_short v[0:1], v2, off offset:64
	v_or_b32_e32 v0, v34, v184
	v_ashrrev_i32_e32 v1, 31, v0
	v_lshlrev_b64 v[0:1], 11, v[0:1]
	v_lshl_add_u64 v[0:1], v[130:131], 0, v[0:1]
	v_cvt_pk_bf16_f32 v2, v19, s0
	global_store_short v[0:1], v2, off
	v_cvt_pk_bf16_f32 v2, v3, s0
	global_store_short v[0:1], v2, off offset:64
	v_or_b32_e32 v0, v34, v185
	v_ashrrev_i32_e32 v1, 31, v0
	v_lshlrev_b64 v[0:1], 11, v[0:1]
	v_lshl_add_u64 v[0:1], v[130:131], 0, v[0:1]
	v_cvt_pk_bf16_f32 v2, v20, s0
	global_store_short v[0:1], v2, off
	v_cvt_pk_bf16_f32 v2, v4, s0
	global_store_short v[0:1], v2, off offset:64
	v_or_b32_e32 v0, v34, v186
	v_ashrrev_i32_e32 v1, 31, v0
	v_lshlrev_b64 v[0:1], 11, v[0:1]
	v_lshl_add_u64 v[0:1], v[130:131], 0, v[0:1]
	v_cvt_pk_bf16_f32 v2, v21, s0
	global_store_short v[0:1], v2, off
	v_cvt_pk_bf16_f32 v2, v5, s0
	global_store_short v[0:1], v2, off offset:64
	v_or_b32_e32 v0, v34, v187
	v_ashrrev_i32_e32 v1, 31, v0
	v_lshlrev_b64 v[0:1], 11, v[0:1]
	v_lshl_add_u64 v[0:1], v[130:131], 0, v[0:1]
	v_cvt_pk_bf16_f32 v2, v22, s0
	global_store_short v[0:1], v2, off
	v_cvt_pk_bf16_f32 v2, v6, s0
	global_store_short v[0:1], v2, off offset:64
	v_or_b32_e32 v0, v34, v188
	v_ashrrev_i32_e32 v1, 31, v0
	v_lshlrev_b64 v[0:1], 11, v[0:1]
	v_lshl_add_u64 v[0:1], v[130:131], 0, v[0:1]
	v_cvt_pk_bf16_f32 v2, v23, s0
	global_store_short v[0:1], v2, off
	v_cvt_pk_bf16_f32 v2, v7, s0
	global_store_short v[0:1], v2, off offset:64
	v_or_b32_e32 v0, v34, v189
	v_ashrrev_i32_e32 v1, 31, v0
	v_lshlrev_b64 v[0:1], 11, v[0:1]
	v_lshl_add_u64 v[0:1], v[130:131], 0, v[0:1]
	v_cvt_pk_bf16_f32 v2, v24, s0
	global_store_short v[0:1], v2, off
	v_cvt_pk_bf16_f32 v2, v8, s0
	global_store_short v[0:1], v2, off offset:64
	v_or_b32_e32 v0, v34, v190
	v_ashrrev_i32_e32 v1, 31, v0
	v_lshlrev_b64 v[0:1], 11, v[0:1]
	v_lshl_add_u64 v[0:1], v[130:131], 0, v[0:1]
	v_cvt_pk_bf16_f32 v2, v25, s0
	global_store_short v[0:1], v2, off
	v_cvt_pk_bf16_f32 v2, v9, s0
	global_store_short v[0:1], v2, off offset:64
	v_or_b32_e32 v0, v34, v191
	v_ashrrev_i32_e32 v1, 31, v0
	v_lshlrev_b64 v[0:1], 11, v[0:1]
	v_lshl_add_u64 v[0:1], v[130:131], 0, v[0:1]
	v_cvt_pk_bf16_f32 v2, v26, s0
	global_store_short v[0:1], v2, off
	v_cvt_pk_bf16_f32 v2, v10, s0
	global_store_short v[0:1], v2, off offset:64
	v_or_b32_e32 v0, v34, v192
	v_ashrrev_i32_e32 v1, 31, v0
	v_lshlrev_b64 v[0:1], 11, v[0:1]
	v_lshl_add_u64 v[0:1], v[130:131], 0, v[0:1]
	v_cvt_pk_bf16_f32 v2, v27, s0
	global_store_short v[0:1], v2, off
	v_cvt_pk_bf16_f32 v2, v11, s0
	global_store_short v[0:1], v2, off offset:64
	v_or_b32_e32 v0, v34, v193
	v_ashrrev_i32_e32 v1, 31, v0
	v_lshlrev_b64 v[0:1], 11, v[0:1]
	v_lshl_add_u64 v[0:1], v[130:131], 0, v[0:1]
	v_cvt_pk_bf16_f32 v2, v28, s0
	global_store_short v[0:1], v2, off
	v_cvt_pk_bf16_f32 v2, v12, s0
	global_store_short v[0:1], v2, off offset:64
	v_or_b32_e32 v0, v34, v194
	v_ashrrev_i32_e32 v1, 31, v0
	v_lshlrev_b64 v[0:1], 11, v[0:1]
	v_lshl_add_u64 v[0:1], v[130:131], 0, v[0:1]
	v_cvt_pk_bf16_f32 v2, v29, s0
	global_store_short v[0:1], v2, off
	v_cvt_pk_bf16_f32 v2, v13, s0
	global_store_short v[0:1], v2, off offset:64
	v_or_b32_e32 v0, v34, v195
	v_ashrrev_i32_e32 v1, 31, v0
	v_lshlrev_b64 v[0:1], 11, v[0:1]
	v_lshl_add_u64 v[0:1], v[130:131], 0, v[0:1]
	v_cvt_pk_bf16_f32 v2, v30, s0
	global_store_short v[0:1], v2, off
	v_cvt_pk_bf16_f32 v2, v14, s0
	global_store_short v[0:1], v2, off offset:64
	v_or_b32_e32 v0, v34, v196
	v_ashrrev_i32_e32 v1, 31, v0
	v_lshlrev_b64 v[0:1], 11, v[0:1]
	v_lshl_add_u64 v[0:1], v[130:131], 0, v[0:1]
	v_cvt_pk_bf16_f32 v2, v31, s0
	global_store_short v[0:1], v2, off
	v_cvt_pk_bf16_f32 v2, v15, s0
	global_store_short v[0:1], v2, off offset:64
	s_cbranch_scc0 .LBB0_262

.LBB0_330:
	s_and_b32 s3, s2, 0x18000
	v_add_u32_e32 v128, s3, v182
	s_add_i32 s3, s2, 0xfffe8000
	s_and_b32 s3, s3, 0x18000
	v_or_b32_e32 v214, s3, v181
	v_add_u32_e32 v215, s3, v178
	s_waitcnt lgkmcnt(0)
	v_mfma_f32_32x32x16_bf16 v[112:127], v[150:153], v[142:145], v[112:127]
	v_mfma_f32_32x32x16_bf16 v[96:111], v[150:153], v[130:133], v[96:111]
	v_mfma_f32_32x32x16_bf16 v[80:95], v[146:149], v[142:145], v[80:95]
	v_mfma_f32_32x32x16_bf16 v[64:79], v[146:149], v[130:133], v[64:79]
	s_waitcnt vmcnt(8)
	s_barrier
	v_add_u32_e32 v194, v214, v179
	v_add_u32_e32 v210, v215, v179
	ds_read_b128 v[190:193], v194 offset:16384
	ds_read_b128 v[194:197], v194 offset:18432
	ds_read_b128 v[198:201], v210
	v_mfma_f32_32x32x16_bf16 v[48:63], v[138:141], v[142:145], v[48:63]
	v_mfma_f32_32x32x16_bf16 v[32:47], v[138:141], v[130:133], v[32:47]
	ds_read_b128 v[202:205], v210 offset:2048
	v_readfirstlane_b32 s3, v128
	s_mov_b32 m0, s3
	s_nop 0
	global_load_lds_dwordx4 v[172:173], off
	v_mfma_f32_32x32x16_bf16 v[16:31], v[134:137], v[142:145], v[16:31]
	v_mfma_f32_32x32x16_bf16 v[0:15], v[134:137], v[130:133], v[0:15]
	ds_read_b128 v[206:209], v210 offset:4096
	s_add_i32 s24, s3, 0x2000
	v_lshl_add_u64 v[150:151], v[172:173], 0, s[26:27]
	s_mov_b32 m0, s24
	s_nop 0
	global_load_lds_dwordx4 v[150:151], off
	ds_read_b128 v[210:213], v210 offset:6144
	s_waitcnt lgkmcnt(3)
	v_mfma_f32_32x32x16_bf16 v[112:127], v[198:201], v[190:193], v[112:127]
	v_add_u32_e32 v128, v214, v180
	ds_read_b128 v[142:145], v128 offset:16384
	v_mfma_f32_32x32x16_bf16 v[96:111], v[198:201], v[194:197], v[96:111]
	ds_read_b128 v[130:133], v128 offset:18432
	s_add_i32 s24, s3, 0x6000
	s_addk_i32 s3, 0x4000
	s_mov_b32 m0, s3
	s_nop 0
	global_load_lds_dwordx4 v[174:175], off
	s_waitcnt lgkmcnt(4)
	v_mfma_f32_32x32x16_bf16 v[80:95], v[202:205], v[190:193], v[80:95]
	v_add_u32_e32 v128, v215, v180
	ds_read_b128 v[150:153], v128
	v_mfma_f32_32x32x16_bf16 v[64:79], v[202:205], v[194:197], v[64:79]
	ds_read_b128 v[146:149], v128 offset:2048
	s_waitcnt lgkmcnt(5)
	v_mfma_f32_32x32x16_bf16 v[48:63], v[206:209], v[190:193], v[48:63]
	ds_read_b128 v[138:141], v128 offset:4096
	v_mfma_f32_32x32x16_bf16 v[32:47], v[206:209], v[194:197], v[32:47]
	ds_read_b128 v[134:137], v128 offset:6144
	v_lshl_add_u64 v[214:215], v[174:175], 0, s[26:27]
	s_mov_b32 m0, s24
	s_nop 0
	global_load_lds_dwordx4 v[214:215], off
	s_waitcnt lgkmcnt(6)
	v_mfma_f32_32x32x16_bf16 v[16:31], v[210:213], v[190:193], v[16:31]
	s_add_i32 s2, s2, 0x8000
	v_lshl_add_u64 v[172:173], v[172:173], 0, 64
	v_lshl_add_u64 v[174:175], v[174:175], 0, 64
	s_cmp_eq_u32 s2, 0x100000
	v_mfma_f32_32x32x16_bf16 v[0:15], v[210:213], v[194:197], v[0:15]
	s_cbranch_scc0 .LBB0_330
	s_waitcnt vmcnt(8) lgkmcnt(0)
	s_barrier
	v_add_u32_e32 v128, v181, v179
	ds_read_b128 v[172:175], v128 offset:49152
	ds_read_b128 v[190:193], v128 offset:51200
	v_add_u32_e32 v128, v178, v179
	ds_read_b128 v[194:197], v128 offset:32768
	ds_read_b128 v[198:201], v128 offset:34816
	ds_read_b128 v[202:205], v128 offset:36864
	ds_read_b128 v[206:209], v128 offset:38912
	s_waitcnt lgkmcnt(9)
	v_mfma_f32_32x32x16_bf16 v[112:127], v[150:153], v[142:145], v[112:127]
	v_mfma_f32_32x32x16_bf16 v[96:111], v[150:153], v[130:133], v[96:111]
	s_waitcnt lgkmcnt(8)
	v_mfma_f32_32x32x16_bf16 v[80:95], v[146:149], v[142:145], v[80:95]
	v_mfma_f32_32x32x16_bf16 v[64:79], v[146:149], v[130:133], v[64:79]
	s_waitcnt lgkmcnt(7)
	v_mfma_f32_32x32x16_bf16 v[48:63], v[138:141], v[142:145], v[48:63]
	v_mfma_f32_32x32x16_bf16 v[32:47], v[138:141], v[130:133], v[32:47]
	s_waitcnt lgkmcnt(6)
	v_mfma_f32_32x32x16_bf16 v[16:31], v[134:137], v[142:145], v[16:31]
	v_mfma_f32_32x32x16_bf16 v[0:15], v[134:137], v[130:133], v[0:15]
	v_add_u32_e32 v128, v181, v180
	ds_read_b128 v[130:133], v128 offset:49152
	ds_read_b128 v[134:137], v128 offset:51200
	v_add_u32_e32 v128, v178, v180
	ds_read_b128 v[138:141], v128 offset:32768
	ds_read_b128 v[142:145], v128 offset:34816
	ds_read_b128 v[146:149], v128 offset:36864
	ds_read_b128 v[150:153], v128 offset:38912
	s_waitcnt lgkmcnt(9)
	v_mfma_f32_32x32x16_bf16 v[112:127], v[194:197], v[172:175], v[112:127]
	v_mfma_f32_32x32x16_bf16 v[96:111], v[194:197], v[190:193], v[96:111]
	s_waitcnt lgkmcnt(8)
	v_mfma_f32_32x32x16_bf16 v[80:95], v[198:201], v[172:175], v[80:95]
	v_mfma_f32_32x32x16_bf16 v[64:79], v[198:201], v[190:193], v[64:79]
	s_waitcnt lgkmcnt(7)
	v_mfma_f32_32x32x16_bf16 v[48:63], v[202:205], v[172:175], v[48:63]
	v_mfma_f32_32x32x16_bf16 v[32:47], v[202:205], v[190:193], v[32:47]
	s_waitcnt vmcnt(4) lgkmcnt(0)
	s_barrier
	v_add_u32_e32 v128, v187, v179
	s_waitcnt lgkmcnt(6)
	v_mfma_f32_32x32x16_bf16 v[16:31], v[206:209], v[172:175], v[16:31]
	v_mfma_f32_32x32x16_bf16 v[0:15], v[206:209], v[190:193], v[0:15]
	ds_read_b128 v[172:175], v128 offset:16384
	ds_read_b128 v[190:193], v128 offset:18432
	v_add_u32_e32 v128, v188, v179
	ds_read_b128 v[194:197], v128
	ds_read_b128 v[198:201], v128 offset:2048
	ds_read_b128 v[202:205], v128 offset:4096
	ds_read_b128 v[206:209], v128 offset:6144
	s_waitcnt lgkmcnt(9)
	v_mfma_f32_32x32x16_bf16 v[112:127], v[138:141], v[130:133], v[112:127]
	v_mfma_f32_32x32x16_bf16 v[96:111], v[138:141], v[134:137], v[96:111]
	s_waitcnt lgkmcnt(8)
	v_mfma_f32_32x32x16_bf16 v[80:95], v[142:145], v[130:133], v[80:95]
	v_mfma_f32_32x32x16_bf16 v[64:79], v[142:145], v[134:137], v[64:79]
	s_waitcnt lgkmcnt(7)
	v_mfma_f32_32x32x16_bf16 v[48:63], v[146:149], v[130:133], v[48:63]
	v_mfma_f32_32x32x16_bf16 v[32:47], v[146:149], v[134:137], v[32:47]
	s_waitcnt lgkmcnt(6)
	v_mfma_f32_32x32x16_bf16 v[16:31], v[150:153], v[130:133], v[16:31]
	v_mfma_f32_32x32x16_bf16 v[0:15], v[150:153], v[134:137], v[0:15]
	v_add_u32_e32 v128, v187, v180
	ds_read_b128 v[130:133], v128 offset:16384
	ds_read_b128 v[134:137], v128 offset:18432
	v_add_u32_e32 v128, v188, v180
	ds_read_b128 v[138:141], v128
	ds_read_b128 v[142:145], v128 offset:2048
	ds_read_b128 v[146:149], v128 offset:4096
	ds_read_b128 v[150:153], v128 offset:6144
	s_waitcnt lgkmcnt(9)
	v_mfma_f32_32x32x16_bf16 v[112:127], v[194:197], v[172:175], v[112:127]
	v_mfma_f32_32x32x16_bf16 v[96:111], v[194:197], v[190:193], v[96:111]
	s_waitcnt lgkmcnt(8)
	v_mfma_f32_32x32x16_bf16 v[80:95], v[198:201], v[172:175], v[80:95]
	v_mfma_f32_32x32x16_bf16 v[64:79], v[198:201], v[190:193], v[64:79]
	s_waitcnt lgkmcnt(7)
	v_mfma_f32_32x32x16_bf16 v[48:63], v[202:205], v[172:175], v[48:63]
	v_mfma_f32_32x32x16_bf16 v[32:47], v[202:205], v[190:193], v[32:47]
	s_waitcnt vmcnt(0) lgkmcnt(0)
	s_barrier
	v_add_u32_e32 v128, v185, v179
	s_waitcnt lgkmcnt(6)
	v_mfma_f32_32x32x16_bf16 v[16:31], v[206:209], v[172:175], v[16:31]
	v_mfma_f32_32x32x16_bf16 v[0:15], v[206:209], v[190:193], v[0:15]
	ds_read_b128 v[172:175], v128 offset:16384
	ds_read_b128 v[190:193], v128 offset:18432
	v_add_u32_e32 v128, v186, v179
	ds_read_b128 v[194:197], v128
	ds_read_b128 v[198:201], v128 offset:2048
	ds_read_b128 v[202:205], v128 offset:4096
	ds_read_b128 v[206:209], v128 offset:6144
	s_waitcnt lgkmcnt(9)
	v_mfma_f32_32x32x16_bf16 v[112:127], v[138:141], v[130:133], v[112:127]
	v_mfma_f32_32x32x16_bf16 v[96:111], v[138:141], v[134:137], v[96:111]
	s_waitcnt lgkmcnt(8)
	v_mfma_f32_32x32x16_bf16 v[80:95], v[142:145], v[130:133], v[80:95]
	v_mfma_f32_32x32x16_bf16 v[64:79], v[142:145], v[134:137], v[64:79]
	s_waitcnt lgkmcnt(7)
	v_mfma_f32_32x32x16_bf16 v[48:63], v[146:149], v[130:133], v[48:63]
	v_mfma_f32_32x32x16_bf16 v[32:47], v[146:149], v[134:137], v[32:47]
	s_waitcnt lgkmcnt(6)
	v_mfma_f32_32x32x16_bf16 v[16:31], v[150:153], v[130:133], v[16:31]
	v_mfma_f32_32x32x16_bf16 v[0:15], v[150:153], v[134:137], v[0:15]
	v_add_u32_e32 v128, v185, v180
	ds_read_b128 v[130:133], v128 offset:16384
	ds_read_b128 v[138:141], v128 offset:18432
	v_add_u32_e32 v128, v186, v180
	ds_read_b128 v[134:137], v128
	ds_read_b128 v[142:145], v128 offset:2048
	ds_read_b128 v[146:149], v128 offset:4096
	ds_read_b128 v[210:213], v128 offset:6144
	s_waitcnt lgkmcnt(9)
	v_mfma_f32_32x32x16_bf16 v[112:127], v[194:197], v[172:175], v[112:127]
	v_mfma_f32_32x32x16_bf16 v[96:111], v[194:197], v[190:193], v[96:111]
	s_waitcnt lgkmcnt(8)
	v_mfma_f32_32x32x16_bf16 v[80:95], v[198:201], v[172:175], v[80:95]
	v_mfma_f32_32x32x16_bf16 v[64:79], v[198:201], v[190:193], v[64:79]
	s_waitcnt lgkmcnt(7)
	v_mfma_f32_32x32x16_bf16 v[48:63], v[202:205], v[172:175], v[48:63]
	v_mfma_f32_32x32x16_bf16 v[32:47], v[202:205], v[190:193], v[32:47]
	s_waitcnt lgkmcnt(6)
	v_mfma_f32_32x32x16_bf16 v[16:31], v[206:209], v[172:175], v[16:31]
	v_add_u32_e32 v150, s0, v157
	s_movk_i32 s2, 0x2000
	s_movk_i32 s0, 0x1fff
	v_cmp_gt_i32_e32 vcc, s2, v150
	s_movk_i32 s2, 0x7ff
	v_mfma_f32_32x32x16_bf16 v[0:15], v[206:209], v[190:193], v[0:15]
	s_waitcnt lgkmcnt(3)
	v_mfma_f32_32x32x16_bf16 v[112:127], v[134:137], v[130:133], v[112:127]
	v_mfma_f32_32x32x16_bf16 v[96:111], v[134:137], v[138:141], v[96:111]
	v_or_b32_e32 v136, s1, v176
	v_cmp_lt_i32_e64 s[0:1], s0, v150
	v_cmp_lt_i32_e64 s[2:3], s2, v136
	s_waitcnt lgkmcnt(2)
	v_mfma_f32_32x32x16_bf16 v[80:95], v[142:145], v[130:133], v[80:95]
	v_mfma_f32_32x32x16_bf16 v[64:79], v[142:145], v[138:141], v[64:79]
	s_waitcnt lgkmcnt(1)
	v_mfma_f32_32x32x16_bf16 v[48:63], v[146:149], v[130:133], v[48:63]
	v_mfma_f32_32x32x16_bf16 v[32:47], v[146:149], v[138:141], v[32:47]
	s_waitcnt lgkmcnt(0)
	v_mfma_f32_32x32x16_bf16 v[16:31], v[210:213], v[130:133], v[16:31]
	v_or_b32_e32 v130, v150, v183
	v_mfma_f32_32x32x16_bf16 v[0:15], v[210:213], v[138:141], v[0:15]
	s_and_saveexec_b64 s[24:25], s[2:3]
	s_xor_b64 s[2:3], exec, s[24:25]
	s_cbranch_execz .LBB0_461
	v_ashrrev_i32_e32 v134, 8, v150
	v_ashrrev_i32_e32 v135, 31, v134
	s_and_saveexec_b64 s[24:25], vcc
	s_xor_b64 s[24:25], exec, s[24:25]
	v_lshlrev_b64 v[140:141], 18, v[134:135]
	v_and_b32_e32 v128, 0x84, v130
	s_or_saveexec_b64 s[24:25], s[24:25]
	v_mov_b64_e32 v[138:139], 0x100
	s_xor_b64 exec, exec, s[24:25]
	v_add_u32_e32 v128, 0xffffe000, v150
	v_lshrrev_b32_e32 v128, 11, v128
	s_mov_b32 s26, 0x240000
	v_mad_u64_u32 v[140:141], s[26:27], v128, s26, v[166:167]
	v_and_b32_e32 v128, 0x784, v130
	v_add_u32_e32 v128, 0x100, v128
	v_mov_b64_e32 v[138:139], 0x900
	s_or_b64 exec, exec, s[24:25]
	v_add_u32_e32 v132, v136, v184
	v_or_b32_e32 v142, 1, v130
	v_or_b32_e32 v144, 2, v130
	v_or_b32_e32 v146, 3, v130
	v_lshl_add_u64 v[140:141], v[140:141], 1, s[6:7]
	v_mad_u64_u32 v[152:153], s[24:25], v138, v132, 0
	v_ashrrev_i32_e32 v131, 31, v130
	v_ashrrev_i32_e32 v143, 31, v142
	v_ashrrev_i32_e32 v145, 31, v144
	v_ashrrev_i32_e32 v147, 31, v146
	v_lshl_add_u64 v[152:153], v[152:153], 1, v[140:141]
	v_lshlrev_b64 v[136:137], 12, v[130:131]
	v_lshlrev_b64 v[142:143], 12, v[142:143]
	v_lshlrev_b64 v[144:145], 12, v[144:145]
	v_lshlrev_b64 v[146:147], 12, v[146:147]
	v_cvt_pk_bf16_f32 v148, v112, v113
	v_cvt_pk_bf16_f32 v149, v114, v115
	v_mov_b32_e32 v133, v129
	v_lshl_add_u64 v[152:153], v[128:129], 1, v[152:153]
	global_store_dwordx2 v[152:153], v[148:149], off
	v_lshl_add_u64 v[148:149], s[18:19], 0, v[136:137]
	v_lshlrev_b64 v[136:137], 2, v[132:133]
	v_lshl_add_u64 v[152:153], s[18:19], 0, v[142:143]
	v_lshl_add_u64 v[172:173], s[18:19], 0, v[144:145]
	v_lshl_add_u64 v[174:175], s[18:19], 0, v[146:147]
	v_lshl_add_u64 v[142:143], v[148:149], 0, v[136:137]
	v_lshl_add_u64 v[144:145], v[152:153], 0, v[136:137]
	v_lshl_add_u64 v[146:147], v[172:173], 0, v[136:137]
	v_lshl_add_u64 v[148:149], v[174:175], 0, v[136:137]
	s_and_saveexec_b64 s[24:25], vcc
	s_cbranch_execz .LBB0_338
	global_store_dword v[142:143], v112, off nt
	global_store_dword v[144:145], v113, off nt
	global_store_dword v[146:147], v114, off nt
	global_store_dword v[148:149], v115, off nt

.LBB0_1102:
	s_and_b32 s7, s6, 0x18000
	v_add_u32_e32 v222, s7, v180
	s_add_i32 s7, s6, 0xfffe8000
	s_and_b32 s7, s7, 0x18000
	v_or_b32_e32 v223, s7, v179
	v_add_u32_e32 v233, s7, v176
	s_waitcnt lgkmcnt(0)
	v_mfma_f32_32x32x16_bf16 v[112:127], v[150:153], v[142:145], v[112:127]
	v_mfma_f32_32x32x16_bf16 v[96:111], v[150:153], v[130:133], v[96:111]
	v_mfma_f32_32x32x16_bf16 v[80:95], v[146:149], v[142:145], v[80:95]
	v_mfma_f32_32x32x16_bf16 v[64:79], v[146:149], v[130:133], v[64:79]
	s_waitcnt vmcnt(8)
	s_barrier
	v_add_u32_e32 v206, v223, v177
	v_add_u32_e32 v234, v233, v177
	ds_read_b128 v[202:205], v206 offset:16384
	ds_read_b128 v[206:209], v206 offset:18432
	ds_read_b128 v[210:213], v234
	v_mfma_f32_32x32x16_bf16 v[48:63], v[138:141], v[142:145], v[48:63]
	v_mfma_f32_32x32x16_bf16 v[32:47], v[138:141], v[130:133], v[32:47]
	ds_read_b128 v[214:217], v234 offset:2048
	v_readfirstlane_b32 s7, v222
	s_mov_b32 m0, s7
	s_nop 0
	global_load_lds_dwordx4 v[170:171], off
	v_mfma_f32_32x32x16_bf16 v[16:31], v[134:137], v[142:145], v[16:31]
	v_mfma_f32_32x32x16_bf16 v[0:15], v[134:137], v[130:133], v[0:15]
	ds_read_b128 v[224:227], v234 offset:4096
	s_add_i32 s10, s7, 0x2000
	v_lshl_add_u64 v[150:151], v[170:171], 0, s[34:35]
	s_mov_b32 m0, s10
	s_nop 0
	global_load_lds_dwordx4 v[150:151], off
	ds_read_b128 v[234:237], v234 offset:6144
	s_waitcnt lgkmcnt(3)
	v_mfma_f32_32x32x16_bf16 v[112:127], v[210:213], v[202:205], v[112:127]
	v_add_u32_e32 v130, v223, v178
	v_add_u32_e32 v134, v233, v178
	ds_read_b128 v[142:145], v130 offset:16384
	v_mfma_f32_32x32x16_bf16 v[96:111], v[210:213], v[206:209], v[96:111]
	ds_read_b128 v[130:133], v130 offset:18432
	s_add_i32 s10, s7, 0x6000
	s_addk_i32 s7, 0x4000
	s_mov_b32 m0, s7
	s_nop 0
	global_load_lds_dwordx4 v[172:173], off
	s_waitcnt lgkmcnt(4)
	v_mfma_f32_32x32x16_bf16 v[80:95], v[214:217], v[202:205], v[80:95]
	ds_read_b128 v[150:153], v134
	v_mfma_f32_32x32x16_bf16 v[64:79], v[214:217], v[206:209], v[64:79]
	ds_read_b128 v[146:149], v134 offset:2048
	s_waitcnt lgkmcnt(5)
	v_mfma_f32_32x32x16_bf16 v[48:63], v[224:227], v[202:205], v[48:63]
	ds_read_b128 v[138:141], v134 offset:4096
	v_mfma_f32_32x32x16_bf16 v[32:47], v[224:227], v[206:209], v[32:47]
	ds_read_b128 v[134:137], v134 offset:6144
	v_lshl_add_u64 v[222:223], v[172:173], 0, s[34:35]
	s_mov_b32 m0, s10
	s_nop 0
	global_load_lds_dwordx4 v[222:223], off
	s_waitcnt lgkmcnt(6)
	v_mfma_f32_32x32x16_bf16 v[16:31], v[234:237], v[202:205], v[16:31]
	s_add_i32 s6, s6, 0x8000
	v_lshl_add_u64 v[170:171], v[170:171], 0, 64
	v_lshl_add_u64 v[172:173], v[172:173], 0, 64
	s_cmp_eq_u32 s6, 0x100000
	v_mfma_f32_32x32x16_bf16 v[0:15], v[234:237], v[206:209], v[0:15]
	s_cbranch_scc0 .LBB0_1102
	s_waitcnt vmcnt(8) lgkmcnt(0)
	s_barrier
	v_add_u32_e32 v202, v179, v177
	v_add_u32_e32 v222, v176, v177
	ds_read_b128 v[170:173], v202 offset:49152
	ds_read_b128 v[202:205], v202 offset:51200
	ds_read_b128 v[206:209], v222 offset:32768
	ds_read_b128 v[210:213], v222 offset:34816
	ds_read_b128 v[214:217], v222 offset:36864
	ds_read_b128 v[224:227], v222 offset:38912
	s_waitcnt lgkmcnt(9)
	v_mfma_f32_32x32x16_bf16 v[112:127], v[150:153], v[142:145], v[112:127]
	v_mfma_f32_32x32x16_bf16 v[96:111], v[150:153], v[130:133], v[96:111]
	s_waitcnt lgkmcnt(8)
	v_mfma_f32_32x32x16_bf16 v[80:95], v[146:149], v[142:145], v[80:95]
	v_mfma_f32_32x32x16_bf16 v[64:79], v[146:149], v[130:133], v[64:79]
	s_waitcnt lgkmcnt(7)
	v_mfma_f32_32x32x16_bf16 v[48:63], v[138:141], v[142:145], v[48:63]
	v_mfma_f32_32x32x16_bf16 v[32:47], v[138:141], v[130:133], v[32:47]
	s_waitcnt lgkmcnt(6)
	v_mfma_f32_32x32x16_bf16 v[16:31], v[134:137], v[142:145], v[16:31]
	v_mfma_f32_32x32x16_bf16 v[0:15], v[134:137], v[130:133], v[0:15]
	v_add_u32_e32 v134, v179, v178
	v_add_u32_e32 v150, v176, v178
	ds_read_b128 v[130:133], v134 offset:49152
	ds_read_b128 v[134:137], v134 offset:51200
	ds_read_b128 v[138:141], v150 offset:32768
	ds_read_b128 v[142:145], v150 offset:34816
	ds_read_b128 v[146:149], v150 offset:36864
	ds_read_b128 v[150:153], v150 offset:38912
	s_waitcnt lgkmcnt(9)
	v_mfma_f32_32x32x16_bf16 v[112:127], v[206:209], v[170:173], v[112:127]
	v_mfma_f32_32x32x16_bf16 v[96:111], v[206:209], v[202:205], v[96:111]
	s_waitcnt lgkmcnt(8)
	v_mfma_f32_32x32x16_bf16 v[80:95], v[210:213], v[170:173], v[80:95]
	v_mfma_f32_32x32x16_bf16 v[64:79], v[210:213], v[202:205], v[64:79]
	s_waitcnt lgkmcnt(7)
	v_mfma_f32_32x32x16_bf16 v[48:63], v[214:217], v[170:173], v[48:63]
	v_mfma_f32_32x32x16_bf16 v[32:47], v[214:217], v[202:205], v[32:47]
	s_waitcnt lgkmcnt(6)
	v_mfma_f32_32x32x16_bf16 v[0:15], v[224:227], v[202:205], v[0:15]
	s_waitcnt vmcnt(4) lgkmcnt(0)
	s_barrier
	v_add_u32_e32 v202, v199, v177
	v_add_u32_e32 v222, v200, v177
	v_mfma_f32_32x32x16_bf16 v[16:31], v[224:227], v[170:173], v[16:31]
	ds_read_b128 v[170:173], v202 offset:16384
	ds_read_b128 v[202:205], v202 offset:18432
	ds_read_b128 v[206:209], v222
	ds_read_b128 v[210:213], v222 offset:2048
	ds_read_b128 v[214:217], v222 offset:4096
	ds_read_b128 v[224:227], v222 offset:6144
	s_waitcnt lgkmcnt(9)
	v_mfma_f32_32x32x16_bf16 v[112:127], v[138:141], v[130:133], v[112:127]
	v_mfma_f32_32x32x16_bf16 v[96:111], v[138:141], v[134:137], v[96:111]
	s_waitcnt lgkmcnt(8)
	v_mfma_f32_32x32x16_bf16 v[80:95], v[142:145], v[130:133], v[80:95]
	v_mfma_f32_32x32x16_bf16 v[64:79], v[142:145], v[134:137], v[64:79]
	s_waitcnt lgkmcnt(7)
	v_mfma_f32_32x32x16_bf16 v[48:63], v[146:149], v[130:133], v[48:63]
	v_mfma_f32_32x32x16_bf16 v[32:47], v[146:149], v[134:137], v[32:47]
	s_waitcnt lgkmcnt(6)
	v_mfma_f32_32x32x16_bf16 v[16:31], v[150:153], v[130:133], v[16:31]
	v_mfma_f32_32x32x16_bf16 v[0:15], v[150:153], v[134:137], v[0:15]
	v_add_u32_e32 v134, v199, v178
	v_add_u32_e32 v150, v200, v178
	ds_read_b128 v[130:133], v134 offset:16384
	ds_read_b128 v[134:137], v134 offset:18432
	ds_read_b128 v[138:141], v150
	ds_read_b128 v[142:145], v150 offset:2048
	ds_read_b128 v[146:149], v150 offset:4096
	ds_read_b128 v[150:153], v150 offset:6144
	s_waitcnt lgkmcnt(9)
	v_mfma_f32_32x32x16_bf16 v[112:127], v[206:209], v[170:173], v[112:127]
	v_mfma_f32_32x32x16_bf16 v[96:111], v[206:209], v[202:205], v[96:111]
	s_waitcnt lgkmcnt(8)
	v_mfma_f32_32x32x16_bf16 v[80:95], v[210:213], v[170:173], v[80:95]
	v_mfma_f32_32x32x16_bf16 v[64:79], v[210:213], v[202:205], v[64:79]
	s_waitcnt lgkmcnt(7)
	v_mfma_f32_32x32x16_bf16 v[48:63], v[214:217], v[170:173], v[48:63]
	v_mfma_f32_32x32x16_bf16 v[32:47], v[214:217], v[202:205], v[32:47]
	s_waitcnt lgkmcnt(6)
	v_mfma_f32_32x32x16_bf16 v[0:15], v[224:227], v[202:205], v[0:15]
	s_waitcnt vmcnt(0) lgkmcnt(0)
	s_barrier
	v_add_u32_e32 v202, v197, v177
	v_add_u32_e32 v222, v198, v177
	v_mfma_f32_32x32x16_bf16 v[16:31], v[224:227], v[170:173], v[16:31]
	ds_read_b128 v[170:173], v202 offset:16384
	ds_read_b128 v[202:205], v202 offset:18432
	ds_read_b128 v[206:209], v222
	ds_read_b128 v[210:213], v222 offset:2048
	ds_read_b128 v[214:217], v222 offset:4096
	ds_read_b128 v[224:227], v222 offset:6144
	s_waitcnt lgkmcnt(9)
	v_mfma_f32_32x32x16_bf16 v[112:127], v[138:141], v[130:133], v[112:127]
	v_mfma_f32_32x32x16_bf16 v[96:111], v[138:141], v[134:137], v[96:111]
	s_waitcnt lgkmcnt(8)
	v_mfma_f32_32x32x16_bf16 v[80:95], v[142:145], v[130:133], v[80:95]
	v_mfma_f32_32x32x16_bf16 v[64:79], v[142:145], v[134:137], v[64:79]
	s_waitcnt lgkmcnt(7)
	v_mfma_f32_32x32x16_bf16 v[48:63], v[146:149], v[130:133], v[48:63]
	v_mfma_f32_32x32x16_bf16 v[32:47], v[146:149], v[134:137], v[32:47]
	s_waitcnt lgkmcnt(6)
	v_mfma_f32_32x32x16_bf16 v[16:31], v[150:153], v[130:133], v[16:31]
	v_mfma_f32_32x32x16_bf16 v[0:15], v[150:153], v[134:137], v[0:15]
	v_add_u32_e32 v134, v197, v178
	v_add_u32_e32 v150, v198, v178
	ds_read_b128 v[130:133], v134 offset:16384
	ds_read_b128 v[134:137], v134 offset:18432
	ds_read_b128 v[138:141], v150
	ds_read_b128 v[142:145], v150 offset:2048
	ds_read_b128 v[146:149], v150 offset:4096
	ds_read_b128 v[150:153], v150 offset:6144
	s_waitcnt lgkmcnt(9)
	v_mfma_f32_32x32x16_bf16 v[112:127], v[206:209], v[170:173], v[112:127]
	v_mfma_f32_32x32x16_bf16 v[96:111], v[206:209], v[202:205], v[96:111]
	s_waitcnt lgkmcnt(8)
	v_mfma_f32_32x32x16_bf16 v[80:95], v[210:213], v[170:173], v[80:95]
	v_mfma_f32_32x32x16_bf16 v[64:79], v[210:213], v[202:205], v[64:79]
	s_waitcnt lgkmcnt(7)
	v_mfma_f32_32x32x16_bf16 v[48:63], v[214:217], v[170:173], v[48:63]
	v_mfma_f32_32x32x16_bf16 v[32:47], v[214:217], v[202:205], v[32:47]
	s_waitcnt lgkmcnt(6)
	v_mfma_f32_32x32x16_bf16 v[16:31], v[224:227], v[170:173], v[16:31]
	v_mfma_f32_32x32x16_bf16 v[0:15], v[224:227], v[202:205], v[0:15]
	s_waitcnt lgkmcnt(3)
	v_mfma_f32_32x32x16_bf16 v[112:127], v[138:141], v[130:133], v[112:127]
	v_mfma_f32_32x32x16_bf16 v[96:111], v[138:141], v[134:137], v[96:111]
	s_nop 10
	v_cvt_pk_bf16_f32 v112, v112, s0
	s_waitcnt lgkmcnt(2)
	v_mfma_f32_32x32x16_bf16 v[80:95], v[142:145], v[130:133], v[80:95]
	v_cvt_pk_bf16_f32 v96, v96, s0
	v_cvt_pk_bf16_f32 v98, v98, s0
	s_waitcnt lgkmcnt(1)
	v_mfma_f32_32x32x16_bf16 v[48:63], v[146:149], v[130:133], v[48:63]
	s_nop 7
	v_cvt_pk_bf16_f32 v80, v80, s0
	s_waitcnt lgkmcnt(0)
	v_mfma_f32_32x32x16_bf16 v[16:31], v[150:153], v[130:133], v[16:31]
	v_add_u32_e32 v132, s3, v128
	v_or_b32_e32 v130, s5, v174
	v_ashrrev_i32_e32 v131, 31, v130
	v_lshl_add_u64 v[130:131], v[130:131], 1, v[158:159]
	v_cvt_pk_bf16_f32 v48, v48, s0
	v_readlane_b32 s3, v252, 7
	s_add_i32 s4, s4, s3
	v_mfma_f32_32x32x16_bf16 v[64:79], v[142:145], v[134:137], v[64:79]
	s_nop 3
	v_cvt_pk_bf16_f32 v16, v16, s0
	v_mfma_f32_32x32x16_bf16 v[32:47], v[146:149], v[134:137], v[32:47]
	s_nop 5
	v_cvt_pk_bf16_f32 v64, v64, s0
	v_cvt_pk_bf16_f32 v66, v66, s0
	v_mfma_f32_32x32x16_bf16 v[0:15], v[150:153], v[134:137], v[0:15]
	v_or_b32_e32 v134, v132, v181
	v_ashrrev_i32_e32 v135, 31, v134
	v_lshlrev_b64 v[134:135], 11, v[134:135]
	v_lshl_add_u64 v[134:135], v[130:131], 0, v[134:135]
	global_store_short v[134:135], v112, off
	global_store_short v[134:135], v96, off offset:64
	v_or_b32_e32 v134, v132, v182
	v_ashrrev_i32_e32 v135, 31, v134
	v_lshlrev_b64 v[134:135], 11, v[134:135]
	v_lshl_add_u64 v[134:135], v[130:131], 0, v[134:135]
	v_cvt_pk_bf16_f32 v96, v113, s0
	global_store_short v[134:135], v96, off
	v_cvt_pk_bf16_f32 v96, v97, s0
	global_store_short v[134:135], v96, off offset:64
	v_or_b32_e32 v96, v132, v183
	v_ashrrev_i32_e32 v97, 31, v96
	v_lshlrev_b64 v[96:97], 11, v[96:97]
	v_lshl_add_u64 v[96:97], v[130:131], 0, v[96:97]
	v_cvt_pk_bf16_f32 v112, v114, s0
	global_store_short v[96:97], v112, off
	global_store_short v[96:97], v98, off offset:64
	v_or_b32_e32 v96, v132, v184
	v_ashrrev_i32_e32 v97, 31, v96
	v_lshlrev_b64 v[96:97], 11, v[96:97]
	v_lshl_add_u64 v[96:97], v[130:131], 0, v[96:97]
	v_cvt_pk_bf16_f32 v98, v115, s0
	global_store_short v[96:97], v98, off
	v_cvt_pk_bf16_f32 v98, v99, s0
	global_store_short v[96:97], v98, off offset:64
	v_or_b32_e32 v96, v132, v185
	v_ashrrev_i32_e32 v97, 31, v96
	v_lshlrev_b64 v[96:97], 11, v[96:97]
	v_lshl_add_u64 v[96:97], v[130:131], 0, v[96:97]
	v_cvt_pk_bf16_f32 v98, v116, s0
	global_store_short v[96:97], v98, off
	v_cvt_pk_bf16_f32 v98, v100, s0
	global_store_short v[96:97], v98, off offset:64
	v_or_b32_e32 v96, v132, v186
	v_ashrrev_i32_e32 v97, 31, v96
	v_lshlrev_b64 v[96:97], 11, v[96:97]
	v_lshl_add_u64 v[96:97], v[130:131], 0, v[96:97]
	v_cvt_pk_bf16_f32 v98, v117, s0
	global_store_short v[96:97], v98, off
	v_cvt_pk_bf16_f32 v98, v101, s0
	global_store_short v[96:97], v98, off offset:64
	v_or_b32_e32 v96, v132, v187
	v_ashrrev_i32_e32 v97, 31, v96
	v_lshlrev_b64 v[96:97], 11, v[96:97]
	v_lshl_add_u64 v[96:97], v[130:131], 0, v[96:97]
	v_cvt_pk_bf16_f32 v98, v118, s0
	global_store_short v[96:97], v98, off
	v_cvt_pk_bf16_f32 v98, v102, s0
	global_store_short v[96:97], v98, off offset:64
	v_or_b32_e32 v96, v132, v188
	v_ashrrev_i32_e32 v97, 31, v96
	v_lshlrev_b64 v[96:97], 11, v[96:97]
	v_lshl_add_u64 v[96:97], v[130:131], 0, v[96:97]
	v_cvt_pk_bf16_f32 v98, v119, s0
	global_store_short v[96:97], v98, off
	v_cvt_pk_bf16_f32 v98, v103, s0
	global_store_short v[96:97], v98, off offset:64
	v_or_b32_e32 v96, v132, v189
	v_ashrrev_i32_e32 v97, 31, v96
	v_lshlrev_b64 v[96:97], 11, v[96:97]
	v_lshl_add_u64 v[96:97], v[130:131], 0, v[96:97]
	v_cvt_pk_bf16_f32 v98, v120, s0
	global_store_short v[96:97], v98, off
	v_cvt_pk_bf16_f32 v98, v104, s0
	global_store_short v[96:97], v98, off offset:64
	v_or_b32_e32 v96, v132, v190
	v_ashrrev_i32_e32 v97, 31, v96
	v_lshlrev_b64 v[96:97], 11, v[96:97]
	v_lshl_add_u64 v[96:97], v[130:131], 0, v[96:97]
	v_cvt_pk_bf16_f32 v98, v121, s0
	global_store_short v[96:97], v98, off
	v_cvt_pk_bf16_f32 v98, v105, s0
	global_store_short v[96:97], v98, off offset:64
	v_or_b32_e32 v96, v132, v191
	v_ashrrev_i32_e32 v97, 31, v96
	v_lshlrev_b64 v[96:97], 11, v[96:97]
	v_lshl_add_u64 v[96:97], v[130:131], 0, v[96:97]
	v_cvt_pk_bf16_f32 v98, v122, s0
	global_store_short v[96:97], v98, off
	v_cvt_pk_bf16_f32 v98, v106, s0
	global_store_short v[96:97], v98, off offset:64
	v_or_b32_e32 v96, v132, v192
	v_ashrrev_i32_e32 v97, 31, v96
	v_lshlrev_b64 v[96:97], 11, v[96:97]
	v_lshl_add_u64 v[96:97], v[130:131], 0, v[96:97]
	v_cvt_pk_bf16_f32 v98, v123, s0
	global_store_short v[96:97], v98, off
	v_cvt_pk_bf16_f32 v98, v107, s0
	global_store_short v[96:97], v98, off offset:64
	v_or_b32_e32 v96, v132, v193
	v_ashrrev_i32_e32 v97, 31, v96
	v_lshlrev_b64 v[96:97], 11, v[96:97]
	v_lshl_add_u64 v[96:97], v[130:131], 0, v[96:97]
	v_cvt_pk_bf16_f32 v98, v124, s0
	global_store_short v[96:97], v98, off
	v_cvt_pk_bf16_f32 v98, v108, s0
	global_store_short v[96:97], v98, off offset:64
	v_or_b32_e32 v96, v132, v194
	v_ashrrev_i32_e32 v97, 31, v96
	v_lshlrev_b64 v[96:97], 11, v[96:97]
	v_lshl_add_u64 v[96:97], v[130:131], 0, v[96:97]
	v_cvt_pk_bf16_f32 v98, v125, s0
	global_store_short v[96:97], v98, off
	v_cvt_pk_bf16_f32 v98, v109, s0
	global_store_short v[96:97], v98, off offset:64
	v_or_b32_e32 v96, v132, v195
	v_ashrrev_i32_e32 v97, 31, v96
	v_lshlrev_b64 v[96:97], 11, v[96:97]
	v_lshl_add_u64 v[96:97], v[130:131], 0, v[96:97]
	v_cvt_pk_bf16_f32 v98, v126, s0
	global_store_short v[96:97], v98, off
	v_cvt_pk_bf16_f32 v98, v110, s0
	global_store_short v[96:97], v98, off offset:64
	v_or_b32_e32 v96, v132, v196
	v_ashrrev_i32_e32 v97, 31, v96
	v_lshlrev_b64 v[96:97], 11, v[96:97]
	v_lshl_add_u64 v[96:97], v[130:131], 0, v[96:97]
	v_cvt_pk_bf16_f32 v98, v127, s0
	global_store_short v[96:97], v98, off
	v_cvt_pk_bf16_f32 v98, v111, s0
	global_store_short v[96:97], v98, off offset:64
	v_or_b32_e32 v98, 32, v132
	v_or_b32_e32 v96, v98, v181
	v_ashrrev_i32_e32 v97, 31, v96
	v_lshlrev_b64 v[96:97], 11, v[96:97]
	v_lshl_add_u64 v[96:97], v[130:131], 0, v[96:97]
	global_store_short v[96:97], v80, off
	global_store_short v[96:97], v64, off offset:64
	v_or_b32_e32 v96, v98, v182
	v_ashrrev_i32_e32 v97, 31, v96
	v_lshlrev_b64 v[96:97], 11, v[96:97]
	v_lshl_add_u64 v[96:97], v[130:131], 0, v[96:97]
	v_cvt_pk_bf16_f32 v64, v81, s0
	global_store_short v[96:97], v64, off
	v_cvt_pk_bf16_f32 v64, v65, s0
	global_store_short v[96:97], v64, off offset:64
	v_or_b32_e32 v64, v98, v183
	v_ashrrev_i32_e32 v65, 31, v64
	v_lshlrev_b64 v[64:65], 11, v[64:65]
	v_lshl_add_u64 v[64:65], v[130:131], 0, v[64:65]
	v_cvt_pk_bf16_f32 v80, v82, s0
	global_store_short v[64:65], v80, off
	global_store_short v[64:65], v66, off offset:64
	v_or_b32_e32 v64, v98, v184
	v_ashrrev_i32_e32 v65, 31, v64
	v_lshlrev_b64 v[64:65], 11, v[64:65]
	v_lshl_add_u64 v[64:65], v[130:131], 0, v[64:65]
	v_cvt_pk_bf16_f32 v66, v83, s0
	global_store_short v[64:65], v66, off
	v_cvt_pk_bf16_f32 v66, v67, s0
	global_store_short v[64:65], v66, off offset:64
	v_or_b32_e32 v64, v98, v185
	v_ashrrev_i32_e32 v65, 31, v64
	v_lshlrev_b64 v[64:65], 11, v[64:65]
	v_lshl_add_u64 v[64:65], v[130:131], 0, v[64:65]
	v_cvt_pk_bf16_f32 v66, v84, s0
	global_store_short v[64:65], v66, off
	v_cvt_pk_bf16_f32 v66, v68, s0
	global_store_short v[64:65], v66, off offset:64
	v_or_b32_e32 v64, v98, v186
	v_ashrrev_i32_e32 v65, 31, v64
	v_lshlrev_b64 v[64:65], 11, v[64:65]
	v_lshl_add_u64 v[64:65], v[130:131], 0, v[64:65]
	v_cvt_pk_bf16_f32 v66, v85, s0
	global_store_short v[64:65], v66, off
	v_cvt_pk_bf16_f32 v66, v69, s0
	global_store_short v[64:65], v66, off offset:64
	v_or_b32_e32 v64, v98, v187
	v_ashrrev_i32_e32 v65, 31, v64
	v_lshlrev_b64 v[64:65], 11, v[64:65]
	v_lshl_add_u64 v[64:65], v[130:131], 0, v[64:65]
	v_cvt_pk_bf16_f32 v66, v86, s0
	global_store_short v[64:65], v66, off
	v_cvt_pk_bf16_f32 v66, v70, s0
	global_store_short v[64:65], v66, off offset:64
	v_or_b32_e32 v64, v98, v188
	v_ashrrev_i32_e32 v65, 31, v64
	v_lshlrev_b64 v[64:65], 11, v[64:65]
	v_lshl_add_u64 v[64:65], v[130:131], 0, v[64:65]
	v_cvt_pk_bf16_f32 v66, v87, s0
	global_store_short v[64:65], v66, off
	v_cvt_pk_bf16_f32 v66, v71, s0
	global_store_short v[64:65], v66, off offset:64
	v_or_b32_e32 v64, v98, v189
	v_ashrrev_i32_e32 v65, 31, v64
	v_lshlrev_b64 v[64:65], 11, v[64:65]
	v_lshl_add_u64 v[64:65], v[130:131], 0, v[64:65]
	v_cvt_pk_bf16_f32 v66, v88, s0
	global_store_short v[64:65], v66, off
	v_cvt_pk_bf16_f32 v66, v72, s0
	global_store_short v[64:65], v66, off offset:64
	v_or_b32_e32 v64, v98, v190
	v_ashrrev_i32_e32 v65, 31, v64
	v_lshlrev_b64 v[64:65], 11, v[64:65]
	v_lshl_add_u64 v[64:65], v[130:131], 0, v[64:65]
	v_cvt_pk_bf16_f32 v66, v89, s0
	global_store_short v[64:65], v66, off
	v_cvt_pk_bf16_f32 v66, v73, s0
	global_store_short v[64:65], v66, off offset:64
	v_or_b32_e32 v64, v98, v191
	v_ashrrev_i32_e32 v65, 31, v64
	v_lshlrev_b64 v[64:65], 11, v[64:65]
	v_lshl_add_u64 v[64:65], v[130:131], 0, v[64:65]
	v_cvt_pk_bf16_f32 v66, v90, s0
	global_store_short v[64:65], v66, off
	v_cvt_pk_bf16_f32 v66, v74, s0
	global_store_short v[64:65], v66, off offset:64
	v_or_b32_e32 v64, v98, v192
	v_ashrrev_i32_e32 v65, 31, v64
	v_lshlrev_b64 v[64:65], 11, v[64:65]
	v_lshl_add_u64 v[64:65], v[130:131], 0, v[64:65]
	v_cvt_pk_bf16_f32 v66, v91, s0
	global_store_short v[64:65], v66, off
	v_cvt_pk_bf16_f32 v66, v75, s0
	global_store_short v[64:65], v66, off offset:64
	v_or_b32_e32 v64, v98, v193
	v_ashrrev_i32_e32 v65, 31, v64
	v_lshlrev_b64 v[64:65], 11, v[64:65]
	v_lshl_add_u64 v[64:65], v[130:131], 0, v[64:65]
	v_cvt_pk_bf16_f32 v66, v92, s0
	global_store_short v[64:65], v66, off
	v_cvt_pk_bf16_f32 v66, v76, s0
	global_store_short v[64:65], v66, off offset:64
	v_or_b32_e32 v64, v98, v194
	v_ashrrev_i32_e32 v65, 31, v64
	v_lshlrev_b64 v[64:65], 11, v[64:65]
	v_lshl_add_u64 v[64:65], v[130:131], 0, v[64:65]
	v_cvt_pk_bf16_f32 v66, v93, s0
	global_store_short v[64:65], v66, off
	v_cvt_pk_bf16_f32 v66, v77, s0
	global_store_short v[64:65], v66, off offset:64
	v_or_b32_e32 v64, v98, v195
	v_ashrrev_i32_e32 v65, 31, v64
	v_lshlrev_b64 v[64:65], 11, v[64:65]
	v_lshl_add_u64 v[64:65], v[130:131], 0, v[64:65]
	v_cvt_pk_bf16_f32 v66, v94, s0
	global_store_short v[64:65], v66, off
	v_cvt_pk_bf16_f32 v66, v78, s0
	global_store_short v[64:65], v66, off offset:64
	v_or_b32_e32 v64, v98, v196
	v_ashrrev_i32_e32 v65, 31, v64
	v_lshlrev_b64 v[64:65], 11, v[64:65]
	v_lshl_add_u64 v[64:65], v[130:131], 0, v[64:65]
	v_cvt_pk_bf16_f32 v66, v95, s0
	global_store_short v[64:65], v66, off
	v_cvt_pk_bf16_f32 v66, v79, s0
	global_store_short v[64:65], v66, off offset:64
	v_or_b32_e32 v66, 64, v132
	v_or_b32_e32 v64, v66, v181
	v_ashrrev_i32_e32 v65, 31, v64
	v_lshlrev_b64 v[64:65], 11, v[64:65]
	v_lshl_add_u64 v[64:65], v[130:131], 0, v[64:65]
	v_cvt_pk_bf16_f32 v32, v32, s0
	global_store_short v[64:65], v48, off
	global_store_short v[64:65], v32, off offset:64
	v_or_b32_e32 v64, v66, v182
	v_ashrrev_i32_e32 v65, 31, v64
	v_lshlrev_b64 v[64:65], 11, v[64:65]
	v_lshl_add_u64 v[64:65], v[130:131], 0, v[64:65]
	v_cvt_pk_bf16_f32 v32, v49, s0
	global_store_short v[64:65], v32, off
	v_cvt_pk_bf16_f32 v32, v33, s0
	global_store_short v[64:65], v32, off offset:64
	v_or_b32_e32 v32, v66, v183
	v_ashrrev_i32_e32 v33, 31, v32
	v_lshlrev_b64 v[32:33], 11, v[32:33]
	v_lshl_add_u64 v[32:33], v[130:131], 0, v[32:33]
	v_cvt_pk_bf16_f32 v48, v50, s0
	v_cvt_pk_bf16_f32 v34, v34, s0
	global_store_short v[32:33], v48, off
	global_store_short v[32:33], v34, off offset:64
	v_or_b32_e32 v32, v66, v184
	v_ashrrev_i32_e32 v33, 31, v32
	v_lshlrev_b64 v[32:33], 11, v[32:33]
	v_lshl_add_u64 v[32:33], v[130:131], 0, v[32:33]
	v_cvt_pk_bf16_f32 v34, v51, s0
	global_store_short v[32:33], v34, off
	v_cvt_pk_bf16_f32 v34, v35, s0
	global_store_short v[32:33], v34, off offset:64
	v_or_b32_e32 v32, v66, v185
	v_ashrrev_i32_e32 v33, 31, v32
	v_lshlrev_b64 v[32:33], 11, v[32:33]
	v_lshl_add_u64 v[32:33], v[130:131], 0, v[32:33]
	v_cvt_pk_bf16_f32 v34, v52, s0
	global_store_short v[32:33], v34, off
	v_cvt_pk_bf16_f32 v34, v36, s0
	global_store_short v[32:33], v34, off offset:64
	v_or_b32_e32 v32, v66, v186
	v_ashrrev_i32_e32 v33, 31, v32
	v_lshlrev_b64 v[32:33], 11, v[32:33]
	v_lshl_add_u64 v[32:33], v[130:131], 0, v[32:33]
	v_cvt_pk_bf16_f32 v34, v53, s0
	global_store_short v[32:33], v34, off
	v_cvt_pk_bf16_f32 v34, v37, s0
	global_store_short v[32:33], v34, off offset:64
	v_or_b32_e32 v32, v66, v187
	v_ashrrev_i32_e32 v33, 31, v32
	v_lshlrev_b64 v[32:33], 11, v[32:33]
	v_lshl_add_u64 v[32:33], v[130:131], 0, v[32:33]
	v_cvt_pk_bf16_f32 v34, v54, s0
	global_store_short v[32:33], v34, off
	v_cvt_pk_bf16_f32 v34, v38, s0
	global_store_short v[32:33], v34, off offset:64
	v_or_b32_e32 v32, v66, v188
	v_ashrrev_i32_e32 v33, 31, v32
	v_lshlrev_b64 v[32:33], 11, v[32:33]
	v_lshl_add_u64 v[32:33], v[130:131], 0, v[32:33]
	v_cvt_pk_bf16_f32 v34, v55, s0
	global_store_short v[32:33], v34, off
	v_cvt_pk_bf16_f32 v34, v39, s0
	global_store_short v[32:33], v34, off offset:64
	v_or_b32_e32 v32, v66, v189
	v_ashrrev_i32_e32 v33, 31, v32
	v_lshlrev_b64 v[32:33], 11, v[32:33]
	v_lshl_add_u64 v[32:33], v[130:131], 0, v[32:33]
	v_cvt_pk_bf16_f32 v34, v56, s0
	global_store_short v[32:33], v34, off
	v_cvt_pk_bf16_f32 v34, v40, s0
	global_store_short v[32:33], v34, off offset:64
	v_or_b32_e32 v32, v66, v190
	v_ashrrev_i32_e32 v33, 31, v32
	v_lshlrev_b64 v[32:33], 11, v[32:33]
	v_lshl_add_u64 v[32:33], v[130:131], 0, v[32:33]
	v_cvt_pk_bf16_f32 v34, v57, s0
	global_store_short v[32:33], v34, off
	v_cvt_pk_bf16_f32 v34, v41, s0
	global_store_short v[32:33], v34, off offset:64
	v_or_b32_e32 v32, v66, v191
	v_ashrrev_i32_e32 v33, 31, v32
	v_lshlrev_b64 v[32:33], 11, v[32:33]
	v_lshl_add_u64 v[32:33], v[130:131], 0, v[32:33]
	v_cvt_pk_bf16_f32 v34, v58, s0
	global_store_short v[32:33], v34, off
	v_cvt_pk_bf16_f32 v34, v42, s0
	global_store_short v[32:33], v34, off offset:64
	v_or_b32_e32 v32, v66, v192
	v_ashrrev_i32_e32 v33, 31, v32
	v_lshlrev_b64 v[32:33], 11, v[32:33]
	v_lshl_add_u64 v[32:33], v[130:131], 0, v[32:33]
	v_cvt_pk_bf16_f32 v34, v59, s0
	global_store_short v[32:33], v34, off
	v_cvt_pk_bf16_f32 v34, v43, s0
	global_store_short v[32:33], v34, off offset:64
	v_or_b32_e32 v32, v66, v193
	v_ashrrev_i32_e32 v33, 31, v32
	v_lshlrev_b64 v[32:33], 11, v[32:33]
	v_lshl_add_u64 v[32:33], v[130:131], 0, v[32:33]
	v_cvt_pk_bf16_f32 v34, v60, s0
	global_store_short v[32:33], v34, off
	v_cvt_pk_bf16_f32 v34, v44, s0
	global_store_short v[32:33], v34, off offset:64
	v_or_b32_e32 v32, v66, v194
	v_ashrrev_i32_e32 v33, 31, v32
	v_lshlrev_b64 v[32:33], 11, v[32:33]
	v_lshl_add_u64 v[32:33], v[130:131], 0, v[32:33]
	v_cvt_pk_bf16_f32 v34, v61, s0
	global_store_short v[32:33], v34, off
	v_cvt_pk_bf16_f32 v34, v45, s0
	global_store_short v[32:33], v34, off offset:64
	v_or_b32_e32 v32, v66, v195
	v_ashrrev_i32_e32 v33, 31, v32
	v_lshlrev_b64 v[32:33], 11, v[32:33]
	v_lshl_add_u64 v[32:33], v[130:131], 0, v[32:33]
	v_cvt_pk_bf16_f32 v34, v62, s0
	global_store_short v[32:33], v34, off
	v_cvt_pk_bf16_f32 v34, v46, s0
	global_store_short v[32:33], v34, off offset:64
	v_or_b32_e32 v32, v66, v196
	v_ashrrev_i32_e32 v33, 31, v32
	v_lshlrev_b64 v[32:33], 11, v[32:33]
	v_lshl_add_u64 v[32:33], v[130:131], 0, v[32:33]
	v_cvt_pk_bf16_f32 v34, v63, s0
	global_store_short v[32:33], v34, off
	v_cvt_pk_bf16_f32 v34, v47, s0
	global_store_short v[32:33], v34, off offset:64
	v_or_b32_e32 v34, 0x60, v132
	v_or_b32_e32 v32, v34, v181
	v_ashrrev_i32_e32 v33, 31, v32
	v_lshlrev_b64 v[32:33], 11, v[32:33]
	v_lshl_add_u64 v[32:33], v[130:131], 0, v[32:33]
	v_cvt_pk_bf16_f32 v0, v0, s0
	global_store_short v[32:33], v16, off
	global_store_short v[32:33], v0, off offset:64
	v_or_b32_e32 v32, v34, v182
	v_ashrrev_i32_e32 v33, 31, v32
	v_lshlrev_b64 v[32:33], 11, v[32:33]
	v_lshl_add_u64 v[32:33], v[130:131], 0, v[32:33]
	v_cvt_pk_bf16_f32 v0, v17, s0
	global_store_short v[32:33], v0, off
	v_cvt_pk_bf16_f32 v0, v1, s0
	global_store_short v[32:33], v0, off offset:64
	v_or_b32_e32 v0, v34, v183
	v_ashrrev_i32_e32 v1, 31, v0
	v_lshlrev_b64 v[0:1], 11, v[0:1]
	v_lshl_add_u64 v[0:1], v[130:131], 0, v[0:1]
	v_cvt_pk_bf16_f32 v16, v18, s0
	v_cvt_pk_bf16_f32 v2, v2, s0
	global_store_short v[0:1], v16, off
	global_store_short v[0:1], v2, off offset:64
	v_or_b32_e32 v0, v34, v184
	v_ashrrev_i32_e32 v1, 31, v0
	v_lshlrev_b64 v[0:1], 11, v[0:1]
	v_lshl_add_u64 v[0:1], v[130:131], 0, v[0:1]
	v_cvt_pk_bf16_f32 v2, v19, s0
	global_store_short v[0:1], v2, off
	v_cvt_pk_bf16_f32 v2, v3, s0
	global_store_short v[0:1], v2, off offset:64
	v_or_b32_e32 v0, v34, v185
	v_ashrrev_i32_e32 v1, 31, v0
	v_lshlrev_b64 v[0:1], 11, v[0:1]
	v_lshl_add_u64 v[0:1], v[130:131], 0, v[0:1]
	v_cvt_pk_bf16_f32 v2, v20, s0
	global_store_short v[0:1], v2, off
	v_cvt_pk_bf16_f32 v2, v4, s0
	global_store_short v[0:1], v2, off offset:64
	v_or_b32_e32 v0, v34, v186
	v_ashrrev_i32_e32 v1, 31, v0
	v_lshlrev_b64 v[0:1], 11, v[0:1]
	v_lshl_add_u64 v[0:1], v[130:131], 0, v[0:1]
	v_cvt_pk_bf16_f32 v2, v21, s0
	global_store_short v[0:1], v2, off
	v_cvt_pk_bf16_f32 v2, v5, s0
	global_store_short v[0:1], v2, off offset:64
	v_or_b32_e32 v0, v34, v187
	v_ashrrev_i32_e32 v1, 31, v0
	v_lshlrev_b64 v[0:1], 11, v[0:1]
	v_lshl_add_u64 v[0:1], v[130:131], 0, v[0:1]
	v_cvt_pk_bf16_f32 v2, v22, s0
	global_store_short v[0:1], v2, off
	v_cvt_pk_bf16_f32 v2, v6, s0
	global_store_short v[0:1], v2, off offset:64
	v_or_b32_e32 v0, v34, v188
	v_ashrrev_i32_e32 v1, 31, v0
	v_lshlrev_b64 v[0:1], 11, v[0:1]
	v_lshl_add_u64 v[0:1], v[130:131], 0, v[0:1]
	v_cvt_pk_bf16_f32 v2, v23, s0
	global_store_short v[0:1], v2, off
	v_cvt_pk_bf16_f32 v2, v7, s0
	global_store_short v[0:1], v2, off offset:64
	v_or_b32_e32 v0, v34, v189
	v_ashrrev_i32_e32 v1, 31, v0
	v_lshlrev_b64 v[0:1], 11, v[0:1]
	v_lshl_add_u64 v[0:1], v[130:131], 0, v[0:1]
	v_cvt_pk_bf16_f32 v2, v24, s0
	global_store_short v[0:1], v2, off
	v_cvt_pk_bf16_f32 v2, v8, s0
	global_store_short v[0:1], v2, off offset:64
	v_or_b32_e32 v0, v34, v190
	v_ashrrev_i32_e32 v1, 31, v0
	v_lshlrev_b64 v[0:1], 11, v[0:1]
	v_lshl_add_u64 v[0:1], v[130:131], 0, v[0:1]
	v_cvt_pk_bf16_f32 v2, v25, s0
	global_store_short v[0:1], v2, off
	v_cvt_pk_bf16_f32 v2, v9, s0
	global_store_short v[0:1], v2, off offset:64
	v_or_b32_e32 v0, v34, v191
	v_ashrrev_i32_e32 v1, 31, v0
	v_lshlrev_b64 v[0:1], 11, v[0:1]
	v_lshl_add_u64 v[0:1], v[130:131], 0, v[0:1]
	v_cvt_pk_bf16_f32 v2, v26, s0
	global_store_short v[0:1], v2, off
	v_cvt_pk_bf16_f32 v2, v10, s0
	global_store_short v[0:1], v2, off offset:64
	v_or_b32_e32 v0, v34, v192
	v_ashrrev_i32_e32 v1, 31, v0
	v_lshlrev_b64 v[0:1], 11, v[0:1]
	v_lshl_add_u64 v[0:1], v[130:131], 0, v[0:1]
	v_cvt_pk_bf16_f32 v2, v27, s0
	global_store_short v[0:1], v2, off
	v_cvt_pk_bf16_f32 v2, v11, s0
	global_store_short v[0:1], v2, off offset:64
	v_or_b32_e32 v0, v34, v193
	v_ashrrev_i32_e32 v1, 31, v0
	v_lshlrev_b64 v[0:1], 11, v[0:1]
	v_lshl_add_u64 v[0:1], v[130:131], 0, v[0:1]
	v_cvt_pk_bf16_f32 v2, v28, s0
	global_store_short v[0:1], v2, off
	v_cvt_pk_bf16_f32 v2, v12, s0
	global_store_short v[0:1], v2, off offset:64
	v_or_b32_e32 v0, v34, v194
	v_ashrrev_i32_e32 v1, 31, v0
	v_lshlrev_b64 v[0:1], 11, v[0:1]
	v_lshl_add_u64 v[0:1], v[130:131], 0, v[0:1]
	v_cvt_pk_bf16_f32 v2, v29, s0
	global_store_short v[0:1], v2, off
	v_cvt_pk_bf16_f32 v2, v13, s0
	global_store_short v[0:1], v2, off offset:64
	v_or_b32_e32 v0, v34, v195
	v_ashrrev_i32_e32 v1, 31, v0
	v_lshlrev_b64 v[0:1], 11, v[0:1]
	v_lshl_add_u64 v[0:1], v[130:131], 0, v[0:1]
	v_cvt_pk_bf16_f32 v2, v30, s0
	global_store_short v[0:1], v2, off
	v_cvt_pk_bf16_f32 v2, v14, s0
	global_store_short v[0:1], v2, off offset:64
	v_or_b32_e32 v0, v34, v196
	v_ashrrev_i32_e32 v1, 31, v0
	v_lshlrev_b64 v[0:1], 11, v[0:1]
	v_lshl_add_u64 v[0:1], v[130:131], 0, v[0:1]
	v_cvt_pk_bf16_f32 v2, v31, s0
	global_store_short v[0:1], v2, off
	v_cvt_pk_bf16_f32 v2, v15, s0
	s_add_i32 s0, s0, s3
	v_readlane_b32 s3, v252, 8
	s_add_i32 s2, s2, s3
	s_cmp_gt_i32 s4, 31
	global_store_short v[0:1], v2, off offset:64
	s_cbranch_scc0 .LBB0_1101

.LBB0_1161:
	s_and_b32 s21, s20, 0x18000
	v_add_u32_e32 v128, s21, v203
	s_add_i32 s21, s20, 0xfffe8000
	s_and_b32 s21, s21, 0x18000
	v_or_b32_e32 v222, s21, v202
	v_add_u32_e32 v223, s21, v199
	s_waitcnt lgkmcnt(0)
	v_mfma_f32_32x32x16_bf16 v[112:127], v[150:153], v[142:145], v[112:127]
	v_mfma_f32_32x32x16_bf16 v[96:111], v[150:153], v[130:133], v[96:111]
	v_mfma_f32_32x32x16_bf16 v[80:95], v[146:149], v[142:145], v[80:95]
	v_mfma_f32_32x32x16_bf16 v[64:79], v[146:149], v[130:133], v[64:79]
	s_waitcnt vmcnt(8)
	s_barrier
	v_add_u32_e32 v180, v222, v200
	v_add_u32_e32 v224, v223, v200
	ds_read_b128 v[176:179], v180 offset:16384
	ds_read_b128 v[180:183], v180 offset:18432
	ds_read_b128 v[184:187], v224
	v_mfma_f32_32x32x16_bf16 v[48:63], v[138:141], v[142:145], v[48:63]
	v_mfma_f32_32x32x16_bf16 v[32:47], v[138:141], v[130:133], v[32:47]
	ds_read_b128 v[188:191], v224 offset:2048
	v_readfirstlane_b32 s21, v128
	s_mov_b32 m0, s21
	s_nop 0
	global_load_lds_dwordx4 v[172:173], off
	v_mfma_f32_32x32x16_bf16 v[16:31], v[134:137], v[142:145], v[16:31]
	v_mfma_f32_32x32x16_bf16 v[0:15], v[134:137], v[130:133], v[0:15]
	ds_read_b128 v[192:195], v224 offset:4096
	s_add_i32 s22, s21, 0x2000
	v_lshl_add_u64 v[150:151], v[172:173], 0, s[26:27]
	s_mov_b32 m0, s22
	s_nop 0
	global_load_lds_dwordx4 v[150:151], off
	ds_read_b128 v[240:243], v224 offset:6144
	s_waitcnt lgkmcnt(3)
	v_mfma_f32_32x32x16_bf16 v[112:127], v[184:187], v[176:179], v[112:127]
	v_add_u32_e32 v128, v222, v201
	ds_read_b128 v[142:145], v128 offset:16384
	v_mfma_f32_32x32x16_bf16 v[96:111], v[184:187], v[180:183], v[96:111]
	ds_read_b128 v[130:133], v128 offset:18432
	s_add_i32 s22, s21, 0x6000
	s_addk_i32 s21, 0x4000
	s_mov_b32 m0, s21
	s_nop 0
	global_load_lds_dwordx4 v[174:175], off
	s_waitcnt lgkmcnt(4)
	v_mfma_f32_32x32x16_bf16 v[80:95], v[188:191], v[176:179], v[80:95]
	v_add_u32_e32 v128, v223, v201
	ds_read_b128 v[150:153], v128
	v_mfma_f32_32x32x16_bf16 v[64:79], v[188:191], v[180:183], v[64:79]
	ds_read_b128 v[146:149], v128 offset:2048
	s_waitcnt lgkmcnt(5)
	v_mfma_f32_32x32x16_bf16 v[48:63], v[192:195], v[176:179], v[48:63]
	ds_read_b128 v[138:141], v128 offset:4096
	v_mfma_f32_32x32x16_bf16 v[32:47], v[192:195], v[180:183], v[32:47]
	ds_read_b128 v[134:137], v128 offset:6144
	v_lshl_add_u64 v[224:225], v[174:175], 0, s[26:27]
	s_mov_b32 m0, s22
	s_nop 0
	global_load_lds_dwordx4 v[224:225], off
	s_waitcnt lgkmcnt(6)
	v_mfma_f32_32x32x16_bf16 v[16:31], v[240:243], v[176:179], v[16:31]
	s_add_i32 s20, s20, 0x8000
	v_lshl_add_u64 v[172:173], v[172:173], 0, 64
	v_lshl_add_u64 v[174:175], v[174:175], 0, 64
	s_cmp_eq_u32 s20, 0x100000
	v_mfma_f32_32x32x16_bf16 v[0:15], v[240:243], v[180:183], v[0:15]
	s_cbranch_scc0 .LBB0_1161
	s_waitcnt vmcnt(8) lgkmcnt(0)
	s_barrier
	v_add_u32_e32 v128, v202, v200
	ds_read_b128 v[172:175], v128 offset:49152
	ds_read_b128 v[176:179], v128 offset:51200
	v_add_u32_e32 v128, v199, v200
	ds_read_b128 v[180:183], v128 offset:32768
	ds_read_b128 v[184:187], v128 offset:34816
	ds_read_b128 v[188:191], v128 offset:36864
	ds_read_b128 v[192:195], v128 offset:38912
	s_waitcnt lgkmcnt(9)
	v_mfma_f32_32x32x16_bf16 v[112:127], v[150:153], v[142:145], v[112:127]
	v_mfma_f32_32x32x16_bf16 v[96:111], v[150:153], v[130:133], v[96:111]
	s_waitcnt lgkmcnt(8)
	v_mfma_f32_32x32x16_bf16 v[80:95], v[146:149], v[142:145], v[80:95]
	v_mfma_f32_32x32x16_bf16 v[64:79], v[146:149], v[130:133], v[64:79]
	s_waitcnt lgkmcnt(7)
	v_mfma_f32_32x32x16_bf16 v[48:63], v[138:141], v[142:145], v[48:63]
	v_mfma_f32_32x32x16_bf16 v[32:47], v[138:141], v[130:133], v[32:47]
	s_waitcnt lgkmcnt(6)
	v_mfma_f32_32x32x16_bf16 v[16:31], v[134:137], v[142:145], v[16:31]
	v_mfma_f32_32x32x16_bf16 v[0:15], v[134:137], v[130:133], v[0:15]
	v_add_u32_e32 v128, v202, v201
	ds_read_b128 v[130:133], v128 offset:49152
	ds_read_b128 v[134:137], v128 offset:51200
	v_add_u32_e32 v128, v199, v201
	ds_read_b128 v[138:141], v128 offset:32768
	ds_read_b128 v[142:145], v128 offset:34816
	ds_read_b128 v[146:149], v128 offset:36864
	ds_read_b128 v[150:153], v128 offset:38912
	s_waitcnt lgkmcnt(9)
	v_mfma_f32_32x32x16_bf16 v[112:127], v[180:183], v[172:175], v[112:127]
	v_mfma_f32_32x32x16_bf16 v[96:111], v[180:183], v[176:179], v[96:111]
	s_waitcnt lgkmcnt(8)
	v_mfma_f32_32x32x16_bf16 v[80:95], v[184:187], v[172:175], v[80:95]
	v_mfma_f32_32x32x16_bf16 v[64:79], v[184:187], v[176:179], v[64:79]
	s_waitcnt lgkmcnt(7)
	v_mfma_f32_32x32x16_bf16 v[48:63], v[188:191], v[172:175], v[48:63]
	v_mfma_f32_32x32x16_bf16 v[32:47], v[188:191], v[176:179], v[32:47]
	s_waitcnt vmcnt(4) lgkmcnt(0)
	s_barrier
	v_add_u32_e32 v128, v236, v200
	s_waitcnt lgkmcnt(6)
	v_mfma_f32_32x32x16_bf16 v[16:31], v[192:195], v[172:175], v[16:31]
	v_mfma_f32_32x32x16_bf16 v[0:15], v[192:195], v[176:179], v[0:15]
	ds_read_b128 v[172:175], v128 offset:16384
	ds_read_b128 v[176:179], v128 offset:18432
	v_add_u32_e32 v128, v237, v200
	ds_read_b128 v[180:183], v128
	ds_read_b128 v[184:187], v128 offset:2048
	ds_read_b128 v[188:191], v128 offset:4096
	ds_read_b128 v[192:195], v128 offset:6144
	s_waitcnt lgkmcnt(9)
	v_mfma_f32_32x32x16_bf16 v[112:127], v[138:141], v[130:133], v[112:127]
	v_mfma_f32_32x32x16_bf16 v[96:111], v[138:141], v[134:137], v[96:111]
	s_waitcnt lgkmcnt(8)
	v_mfma_f32_32x32x16_bf16 v[80:95], v[142:145], v[130:133], v[80:95]
	v_mfma_f32_32x32x16_bf16 v[64:79], v[142:145], v[134:137], v[64:79]
	s_waitcnt lgkmcnt(7)
	v_mfma_f32_32x32x16_bf16 v[48:63], v[146:149], v[130:133], v[48:63]
	v_mfma_f32_32x32x16_bf16 v[32:47], v[146:149], v[134:137], v[32:47]
	s_waitcnt lgkmcnt(6)
	v_mfma_f32_32x32x16_bf16 v[16:31], v[150:153], v[130:133], v[16:31]
	v_mfma_f32_32x32x16_bf16 v[0:15], v[150:153], v[134:137], v[0:15]
	v_add_u32_e32 v128, v236, v201
	ds_read_b128 v[130:133], v128 offset:16384
	ds_read_b128 v[134:137], v128 offset:18432
	v_add_u32_e32 v128, v237, v201
	ds_read_b128 v[138:141], v128
	ds_read_b128 v[142:145], v128 offset:2048
	ds_read_b128 v[146:149], v128 offset:4096
	ds_read_b128 v[150:153], v128 offset:6144
	s_waitcnt lgkmcnt(9)
	v_mfma_f32_32x32x16_bf16 v[112:127], v[180:183], v[172:175], v[112:127]
	v_mfma_f32_32x32x16_bf16 v[96:111], v[180:183], v[176:179], v[96:111]
	s_waitcnt lgkmcnt(8)
	v_mfma_f32_32x32x16_bf16 v[80:95], v[184:187], v[172:175], v[80:95]
	v_mfma_f32_32x32x16_bf16 v[64:79], v[184:187], v[176:179], v[64:79]
	s_waitcnt lgkmcnt(7)
	v_mfma_f32_32x32x16_bf16 v[48:63], v[188:191], v[172:175], v[48:63]
	v_mfma_f32_32x32x16_bf16 v[32:47], v[188:191], v[176:179], v[32:47]
	s_waitcnt vmcnt(0) lgkmcnt(0)
	s_barrier
	v_add_u32_e32 v128, v234, v200
	s_waitcnt lgkmcnt(6)
	v_mfma_f32_32x32x16_bf16 v[16:31], v[192:195], v[172:175], v[16:31]
	v_mfma_f32_32x32x16_bf16 v[0:15], v[192:195], v[176:179], v[0:15]
	ds_read_b128 v[172:175], v128 offset:16384
	ds_read_b128 v[176:179], v128 offset:18432
	v_add_u32_e32 v128, v235, v200
	ds_read_b128 v[180:183], v128
	ds_read_b128 v[184:187], v128 offset:2048
	ds_read_b128 v[188:191], v128 offset:4096
	ds_read_b128 v[192:195], v128 offset:6144
	s_waitcnt lgkmcnt(9)
	v_mfma_f32_32x32x16_bf16 v[112:127], v[138:141], v[130:133], v[112:127]
	v_mfma_f32_32x32x16_bf16 v[96:111], v[138:141], v[134:137], v[96:111]
	s_waitcnt lgkmcnt(8)
	v_mfma_f32_32x32x16_bf16 v[80:95], v[142:145], v[130:133], v[80:95]
	v_mfma_f32_32x32x16_bf16 v[64:79], v[142:145], v[134:137], v[64:79]
	s_waitcnt lgkmcnt(7)
	v_mfma_f32_32x32x16_bf16 v[48:63], v[146:149], v[130:133], v[48:63]
	v_mfma_f32_32x32x16_bf16 v[32:47], v[146:149], v[134:137], v[32:47]
	s_waitcnt lgkmcnt(6)
	v_mfma_f32_32x32x16_bf16 v[16:31], v[150:153], v[130:133], v[16:31]
	v_mfma_f32_32x32x16_bf16 v[0:15], v[150:153], v[134:137], v[0:15]
	v_add_u32_e32 v128, v234, v201
	ds_read_b128 v[130:133], v128 offset:16384
	ds_read_b128 v[136:139], v128 offset:18432
	v_add_u32_e32 v128, v235, v201
	ds_read_b128 v[140:143], v128
	ds_read_b128 v[144:147], v128 offset:2048
	ds_read_b128 v[148:151], v128 offset:4096
	ds_read_b128 v[240:243], v128 offset:6144
	s_waitcnt lgkmcnt(9)
	v_mfma_f32_32x32x16_bf16 v[112:127], v[180:183], v[172:175], v[112:127]
	v_mfma_f32_32x32x16_bf16 v[96:111], v[180:183], v[176:179], v[96:111]
	s_waitcnt lgkmcnt(8)
	v_mfma_f32_32x32x16_bf16 v[80:95], v[184:187], v[172:175], v[80:95]
	v_mfma_f32_32x32x16_bf16 v[64:79], v[184:187], v[176:179], v[64:79]
	s_waitcnt lgkmcnt(7)
	v_mfma_f32_32x32x16_bf16 v[48:63], v[188:191], v[172:175], v[48:63]
	v_mfma_f32_32x32x16_bf16 v[32:47], v[188:191], v[176:179], v[32:47]
	s_waitcnt lgkmcnt(6)
	v_mfma_f32_32x32x16_bf16 v[16:31], v[192:195], v[172:175], v[16:31]
	v_or_b32_e32 v134, s1, v196
	s_movk_i32 s1, 0x1840
	v_cmp_gt_i32_e32 vcc, s1, v134
	v_mfma_f32_32x32x16_bf16 v[0:15], v[192:195], v[176:179], v[0:15]
	s_waitcnt lgkmcnt(3)
	v_mfma_f32_32x32x16_bf16 v[112:127], v[140:143], v[130:133], v[112:127]
	v_mfma_f32_32x32x16_bf16 v[96:111], v[140:143], v[136:139], v[96:111]
	s_waitcnt lgkmcnt(2)
	v_mfma_f32_32x32x16_bf16 v[80:95], v[144:147], v[130:133], v[80:95]
	v_mfma_f32_32x32x16_bf16 v[64:79], v[144:147], v[136:139], v[64:79]
	s_waitcnt lgkmcnt(1)
	v_mfma_f32_32x32x16_bf16 v[48:63], v[148:151], v[130:133], v[48:63]
	v_mfma_f32_32x32x16_bf16 v[32:47], v[148:151], v[136:139], v[32:47]
	s_waitcnt lgkmcnt(0)
	v_mfma_f32_32x32x16_bf16 v[16:31], v[240:243], v[130:133], v[16:31]
	v_mfma_f32_32x32x16_bf16 v[0:15], v[240:243], v[136:139], v[0:15]
	s_and_saveexec_b64 s[20:21], vcc
	s_cbranch_execz .LBB0_1159
	v_add_u32_e32 v239, s0, v159
	s_movk_i32 s0, 0x7ff
	v_cmp_lt_i32_e32 vcc, s0, v134
	s_and_saveexec_b64 s[0:1], vcc
	s_xor_b64 s[22:23], exec, s[0:1]
	s_cbranch_execz .LBB0_1816
	s_cmpk_lt_u32 s24, 0x1800
	v_or_b32_e32 v130, v134, v197
	s_mov_b64 s[0:1], -1
	s_cbranch_scc0 .LBB0_1302
	v_add_u32_e32 v128, 0xfffff800, v130
	v_lshlrev_b64 v[132:133], 2, v[128:129]
	v_lshl_add_u64 v[134:135], s[16:17], 0, v[132:133]
	v_add_co_u32_e32 v136, vcc, 0x4000, v134
	v_lshl_add_u64 v[132:133], s[18:19], 0, v[132:133]
	s_nop 0
	v_addc_co_u32_e32 v137, vcc, 0, v135, vcc
	v_add_co_u32_e32 v138, vcc, 0x8000, v134
	v_mov_b32_e32 v131, v113
	s_nop 0
	v_addc_co_u32_e32 v139, vcc, 0, v135, vcc
	global_load_dword v188, v[134:135], off
	s_nop 0
	global_load_dword v134, v[136:137], off
	global_load_dword v186, v[138:139], off
	global_load_dword v190, v[132:133], off
	v_ashrrev_i32_e32 v132, 7, v239
	v_ashrrev_i32_e32 v133, 31, v132
	v_lshlrev_b64 v[136:137], 15, v[132:133]
	v_lshl_add_u64 v[178:179], s[2:3], 0, v[136:137]
	v_lshl_add_u64 v[136:137], v[128:129], 1, v[178:179]
	s_and_saveexec_b64 s[0:1], s[6:7]
	s_xor_b64 s[0:1], exec, s[0:1]
	s_cbranch_execz .LBB0_1167
	v_add_co_u32_e32 v138, vcc, 0x4000, v136
	v_cvt_pk_bf16_f32 v131, v30, s0
	s_nop 0
	v_addc_co_u32_e32 v139, vcc, 0, v137, vcc
	global_store_short v[138:139], v131, off
	v_mov_b32_e32 v131, v31

.LBB0_2226:
	s_and_b32 s9, s8, 0x18000
	v_add_u32_e32 v222, s9, v180
	s_add_i32 s9, s8, 0xfffe8000
	s_and_b32 s9, s9, 0x18000
	v_or_b32_e32 v223, s9, v179
	v_add_u32_e32 v233, s9, v176
	s_waitcnt lgkmcnt(0)
	v_mfma_f32_32x32x16_bf16 v[112:127], v[150:153], v[142:145], v[112:127]
	v_mfma_f32_32x32x16_bf16 v[96:111], v[150:153], v[130:133], v[96:111]
	v_mfma_f32_32x32x16_bf16 v[80:95], v[146:149], v[142:145], v[80:95]
	v_mfma_f32_32x32x16_bf16 v[64:79], v[146:149], v[130:133], v[64:79]
	s_waitcnt vmcnt(8)
	s_barrier
	v_add_u32_e32 v206, v223, v177
	v_add_u32_e32 v234, v233, v177
	ds_read_b128 v[202:205], v206 offset:16384
	ds_read_b128 v[206:209], v206 offset:18432
	ds_read_b128 v[210:213], v234
	v_mfma_f32_32x32x16_bf16 v[48:63], v[138:141], v[142:145], v[48:63]
	v_mfma_f32_32x32x16_bf16 v[32:47], v[138:141], v[130:133], v[32:47]
	ds_read_b128 v[214:217], v234 offset:2048
	v_readfirstlane_b32 s9, v222
	s_mov_b32 m0, s9
	s_nop 0
	global_load_lds_dwordx4 v[170:171], off
	v_mfma_f32_32x32x16_bf16 v[16:31], v[134:137], v[142:145], v[16:31]
	v_mfma_f32_32x32x16_bf16 v[0:15], v[134:137], v[130:133], v[0:15]
	ds_read_b128 v[224:227], v234 offset:4096
	s_add_i32 s10, s9, 0x2000
	v_lshl_add_u64 v[150:151], v[170:171], 0, s[12:13]
	s_mov_b32 m0, s10
	s_nop 0
	global_load_lds_dwordx4 v[150:151], off
	ds_read_b128 v[234:237], v234 offset:6144
	s_waitcnt lgkmcnt(3)
	v_mfma_f32_32x32x16_bf16 v[112:127], v[210:213], v[202:205], v[112:127]
	v_add_u32_e32 v130, v223, v178
	v_add_u32_e32 v134, v233, v178
	ds_read_b128 v[142:145], v130 offset:16384
	v_mfma_f32_32x32x16_bf16 v[96:111], v[210:213], v[206:209], v[96:111]
	ds_read_b128 v[130:133], v130 offset:18432
	s_add_i32 s10, s9, 0x6000
	s_addk_i32 s9, 0x4000
	s_mov_b32 m0, s9
	s_nop 0
	global_load_lds_dwordx4 v[172:173], off
	s_waitcnt lgkmcnt(4)
	v_mfma_f32_32x32x16_bf16 v[80:95], v[214:217], v[202:205], v[80:95]
	ds_read_b128 v[150:153], v134
	v_mfma_f32_32x32x16_bf16 v[64:79], v[214:217], v[206:209], v[64:79]
	ds_read_b128 v[146:149], v134 offset:2048
	s_waitcnt lgkmcnt(5)
	v_mfma_f32_32x32x16_bf16 v[48:63], v[224:227], v[202:205], v[48:63]
	ds_read_b128 v[138:141], v134 offset:4096
	v_mfma_f32_32x32x16_bf16 v[32:47], v[224:227], v[206:209], v[32:47]
	ds_read_b128 v[134:137], v134 offset:6144
	v_lshl_add_u64 v[222:223], v[172:173], 0, s[12:13]
	s_mov_b32 m0, s10
	s_nop 0
	global_load_lds_dwordx4 v[222:223], off
	s_waitcnt lgkmcnt(6)
	v_mfma_f32_32x32x16_bf16 v[16:31], v[234:237], v[202:205], v[16:31]
	s_add_i32 s8, s8, 0x8000
	v_lshl_add_u64 v[170:171], v[170:171], 0, 64
	v_lshl_add_u64 v[172:173], v[172:173], 0, 64
	s_cmp_eq_u32 s8, 0x200000
	v_mfma_f32_32x32x16_bf16 v[0:15], v[234:237], v[206:209], v[0:15]
	s_cbranch_scc0 .LBB0_2226
	s_waitcnt vmcnt(8) lgkmcnt(0)
	s_barrier
	v_add_u32_e32 v202, v179, v177
	v_add_u32_e32 v222, v176, v177
	ds_read_b128 v[170:173], v202 offset:49152
	ds_read_b128 v[202:205], v202 offset:51200
	ds_read_b128 v[206:209], v222 offset:32768
	ds_read_b128 v[210:213], v222 offset:34816
	ds_read_b128 v[214:217], v222 offset:36864
	ds_read_b128 v[224:227], v222 offset:38912
	s_waitcnt lgkmcnt(9)
	v_mfma_f32_32x32x16_bf16 v[112:127], v[150:153], v[142:145], v[112:127]
	v_mfma_f32_32x32x16_bf16 v[96:111], v[150:153], v[130:133], v[96:111]
	s_waitcnt lgkmcnt(8)
	v_mfma_f32_32x32x16_bf16 v[80:95], v[146:149], v[142:145], v[80:95]
	v_mfma_f32_32x32x16_bf16 v[64:79], v[146:149], v[130:133], v[64:79]
	s_waitcnt lgkmcnt(7)
	v_mfma_f32_32x32x16_bf16 v[48:63], v[138:141], v[142:145], v[48:63]
	v_mfma_f32_32x32x16_bf16 v[32:47], v[138:141], v[130:133], v[32:47]
	s_waitcnt lgkmcnt(6)
	v_mfma_f32_32x32x16_bf16 v[16:31], v[134:137], v[142:145], v[16:31]
	v_mfma_f32_32x32x16_bf16 v[0:15], v[134:137], v[130:133], v[0:15]
	v_add_u32_e32 v134, v179, v178
	v_add_u32_e32 v150, v176, v178
	ds_read_b128 v[130:133], v134 offset:49152
	ds_read_b128 v[134:137], v134 offset:51200
	ds_read_b128 v[138:141], v150 offset:32768
	ds_read_b128 v[142:145], v150 offset:34816
	ds_read_b128 v[146:149], v150 offset:36864
	ds_read_b128 v[150:153], v150 offset:38912
	s_waitcnt lgkmcnt(9)
	v_mfma_f32_32x32x16_bf16 v[112:127], v[206:209], v[170:173], v[112:127]
	v_mfma_f32_32x32x16_bf16 v[96:111], v[206:209], v[202:205], v[96:111]
	s_waitcnt lgkmcnt(8)
	v_mfma_f32_32x32x16_bf16 v[80:95], v[210:213], v[170:173], v[80:95]
	v_mfma_f32_32x32x16_bf16 v[64:79], v[210:213], v[202:205], v[64:79]
	s_waitcnt lgkmcnt(7)
	v_mfma_f32_32x32x16_bf16 v[48:63], v[214:217], v[170:173], v[48:63]
	v_mfma_f32_32x32x16_bf16 v[32:47], v[214:217], v[202:205], v[32:47]
	s_waitcnt lgkmcnt(6)
	v_mfma_f32_32x32x16_bf16 v[0:15], v[224:227], v[202:205], v[0:15]
	s_waitcnt vmcnt(4) lgkmcnt(0)
	s_barrier
	v_add_u32_e32 v202, v199, v177
	v_add_u32_e32 v222, v200, v177
	v_mfma_f32_32x32x16_bf16 v[16:31], v[224:227], v[170:173], v[16:31]
	ds_read_b128 v[170:173], v202 offset:16384
	ds_read_b128 v[202:205], v202 offset:18432
	ds_read_b128 v[206:209], v222
	ds_read_b128 v[210:213], v222 offset:2048
	ds_read_b128 v[214:217], v222 offset:4096
	ds_read_b128 v[224:227], v222 offset:6144
	s_waitcnt lgkmcnt(9)
	v_mfma_f32_32x32x16_bf16 v[112:127], v[138:141], v[130:133], v[112:127]
	v_mfma_f32_32x32x16_bf16 v[96:111], v[138:141], v[134:137], v[96:111]
	s_waitcnt lgkmcnt(8)
	v_mfma_f32_32x32x16_bf16 v[80:95], v[142:145], v[130:133], v[80:95]
	v_mfma_f32_32x32x16_bf16 v[64:79], v[142:145], v[134:137], v[64:79]
	s_waitcnt lgkmcnt(7)
	v_mfma_f32_32x32x16_bf16 v[48:63], v[146:149], v[130:133], v[48:63]
	v_mfma_f32_32x32x16_bf16 v[32:47], v[146:149], v[134:137], v[32:47]
	s_waitcnt lgkmcnt(6)
	v_mfma_f32_32x32x16_bf16 v[16:31], v[150:153], v[130:133], v[16:31]
	v_mfma_f32_32x32x16_bf16 v[0:15], v[150:153], v[134:137], v[0:15]
	v_add_u32_e32 v134, v199, v178
	v_add_u32_e32 v150, v200, v178
	ds_read_b128 v[130:133], v134 offset:16384
	ds_read_b128 v[134:137], v134 offset:18432
	ds_read_b128 v[138:141], v150
	ds_read_b128 v[142:145], v150 offset:2048
	ds_read_b128 v[146:149], v150 offset:4096
	ds_read_b128 v[150:153], v150 offset:6144
	s_waitcnt lgkmcnt(9)
	v_mfma_f32_32x32x16_bf16 v[112:127], v[206:209], v[170:173], v[112:127]
	v_mfma_f32_32x32x16_bf16 v[96:111], v[206:209], v[202:205], v[96:111]
	s_waitcnt lgkmcnt(8)
	v_mfma_f32_32x32x16_bf16 v[80:95], v[210:213], v[170:173], v[80:95]
	v_mfma_f32_32x32x16_bf16 v[64:79], v[210:213], v[202:205], v[64:79]
	s_waitcnt lgkmcnt(7)
	v_mfma_f32_32x32x16_bf16 v[48:63], v[214:217], v[170:173], v[48:63]
	v_mfma_f32_32x32x16_bf16 v[32:47], v[214:217], v[202:205], v[32:47]
	s_waitcnt lgkmcnt(6)
	v_mfma_f32_32x32x16_bf16 v[0:15], v[224:227], v[202:205], v[0:15]
	s_waitcnt vmcnt(0) lgkmcnt(0)
	s_barrier
	v_add_u32_e32 v202, v197, v177
	v_add_u32_e32 v222, v198, v177
	v_mfma_f32_32x32x16_bf16 v[16:31], v[224:227], v[170:173], v[16:31]
	ds_read_b128 v[170:173], v202 offset:16384
	ds_read_b128 v[202:205], v202 offset:18432
	ds_read_b128 v[206:209], v222
	ds_read_b128 v[210:213], v222 offset:2048
	ds_read_b128 v[214:217], v222 offset:4096
	ds_read_b128 v[224:227], v222 offset:6144
	s_waitcnt lgkmcnt(9)
	v_mfma_f32_32x32x16_bf16 v[112:127], v[138:141], v[130:133], v[112:127]
	v_mfma_f32_32x32x16_bf16 v[96:111], v[138:141], v[134:137], v[96:111]
	s_waitcnt lgkmcnt(8)
	v_mfma_f32_32x32x16_bf16 v[80:95], v[142:145], v[130:133], v[80:95]
	v_mfma_f32_32x32x16_bf16 v[64:79], v[142:145], v[134:137], v[64:79]
	s_waitcnt lgkmcnt(7)
	v_mfma_f32_32x32x16_bf16 v[48:63], v[146:149], v[130:133], v[48:63]
	v_mfma_f32_32x32x16_bf16 v[32:47], v[146:149], v[134:137], v[32:47]
	s_waitcnt lgkmcnt(6)
	v_mfma_f32_32x32x16_bf16 v[16:31], v[150:153], v[130:133], v[16:31]
	v_mfma_f32_32x32x16_bf16 v[0:15], v[150:153], v[134:137], v[0:15]
	v_add_u32_e32 v134, v197, v178
	v_add_u32_e32 v150, v198, v178
	ds_read_b128 v[130:133], v134 offset:16384
	ds_read_b128 v[134:137], v134 offset:18432
	ds_read_b128 v[138:141], v150
	ds_read_b128 v[142:145], v150 offset:2048
	ds_read_b128 v[146:149], v150 offset:4096
	ds_read_b128 v[150:153], v150 offset:6144
	s_waitcnt lgkmcnt(9)
	v_mfma_f32_32x32x16_bf16 v[112:127], v[206:209], v[170:173], v[112:127]
	v_mfma_f32_32x32x16_bf16 v[96:111], v[206:209], v[202:205], v[96:111]
	s_waitcnt lgkmcnt(8)
	v_mfma_f32_32x32x16_bf16 v[80:95], v[210:213], v[170:173], v[80:95]
	v_mfma_f32_32x32x16_bf16 v[64:79], v[210:213], v[202:205], v[64:79]
	s_waitcnt lgkmcnt(7)
	v_mfma_f32_32x32x16_bf16 v[48:63], v[214:217], v[170:173], v[48:63]
	v_mfma_f32_32x32x16_bf16 v[32:47], v[214:217], v[202:205], v[32:47]
	s_waitcnt lgkmcnt(6)
	v_mfma_f32_32x32x16_bf16 v[16:31], v[224:227], v[170:173], v[16:31]
	v_mfma_f32_32x32x16_bf16 v[0:15], v[224:227], v[202:205], v[0:15]
	s_waitcnt lgkmcnt(3)
	v_mfma_f32_32x32x16_bf16 v[112:127], v[138:141], v[130:133], v[112:127]
	s_waitcnt lgkmcnt(2)
	v_mfma_f32_32x32x16_bf16 v[80:95], v[142:145], v[130:133], v[80:95]
	s_waitcnt lgkmcnt(1)
	v_mfma_f32_32x32x16_bf16 v[48:63], v[146:149], v[130:133], v[48:63]
	s_waitcnt lgkmcnt(0)
	v_mfma_f32_32x32x16_bf16 v[16:31], v[150:153], v[130:133], v[16:31]
	v_add_u32_e32 v132, s6, v174
	v_or_b32_e32 v130, s7, v128
	v_ashrrev_i32_e32 v131, 31, v130
	v_lshl_add_u64 v[130:131], v[130:131], 1, v[158:159]
	v_readlane_b32 s6, v252, 7
	s_add_i32 s4, s4, s6
	s_add_i32 s2, s2, s6
	v_mfma_f32_32x32x16_bf16 v[96:111], v[138:141], v[134:137], v[96:111]
	v_or_b32_e32 v138, v132, v181
	v_ashrrev_i32_e32 v139, 31, v138
	v_readlane_b32 s6, v252, 8
	s_add_i32 s5, s5, s6
	s_cmp_gt_i32 s4, 31
	v_mfma_f32_32x32x16_bf16 v[64:79], v[142:145], v[134:137], v[64:79]
	v_mfma_f32_32x32x16_bf16 v[32:47], v[146:149], v[134:137], v[32:47]
	v_mfma_f32_32x32x16_bf16 v[0:15], v[150:153], v[134:137], v[0:15]
	v_and_b32_e32 v134, 0xff, v138
	v_lshl_add_u32 v134, v134, 2, v250
	ds_read_b96 v[134:136], v134
	v_lshlrev_b64 v[138:139], 11, v[138:139]
	v_lshl_add_u64 v[138:139], v[130:131], 0, v[138:139]
	s_waitcnt lgkmcnt(0)
	v_mul_f32_e32 v112, v112, v134
	v_mul_f32_e32 v96, v96, v134
	v_cvt_pk_bf16_f32 v112, v112, s0
	v_cvt_pk_bf16_f32 v96, v96, s0
	global_store_short v[138:139], v112, off
	global_store_short v[138:139], v96, off offset:64
	v_or_b32_e32 v138, v132, v182
	v_ashrrev_i32_e32 v139, 31, v138
	v_lshlrev_b64 v[138:139], 11, v[138:139]
	v_mul_f32_e32 v96, v113, v135
	v_lshl_add_u64 v[138:139], v[130:131], 0, v[138:139]
	v_cvt_pk_bf16_f32 v96, v96, s0
	global_store_short v[138:139], v96, off
	v_mul_f32_e32 v96, v97, v135
	v_cvt_pk_bf16_f32 v96, v96, s0
	global_store_short v[138:139], v96, off offset:64
	v_or_b32_e32 v96, v132, v183
	v_ashrrev_i32_e32 v97, 31, v96
	v_lshlrev_b64 v[96:97], 11, v[96:97]
	v_mul_f32_e32 v112, v114, v136
	v_mul_f32_e32 v98, v98, v136
	v_lshl_add_u64 v[96:97], v[130:131], 0, v[96:97]
	v_cvt_pk_bf16_f32 v112, v112, s0
	v_cvt_pk_bf16_f32 v98, v98, s0
	global_store_short v[96:97], v112, off
	global_store_short v[96:97], v98, off offset:64
	v_or_b32_e32 v96, v132, v184
	v_ashrrev_i32_e32 v97, 31, v96
	v_and_b32_e32 v112, 0xff, v96
	v_lshl_add_u32 v112, v112, 2, v250
	ds_read_b32 v98, v112
	v_lshlrev_b64 v[96:97], 11, v[96:97]
	v_lshl_add_u64 v[96:97], v[130:131], 0, v[96:97]
	s_waitcnt lgkmcnt(0)
	v_mul_f32_e32 v112, v115, v98
	v_cvt_pk_bf16_f32 v112, v112, s0
	global_store_short v[96:97], v112, off
	v_mul_f32_e32 v98, v99, v98
	v_or_b32_e32 v112, v132, v185
	v_cvt_pk_bf16_f32 v98, v98, s0
	v_ashrrev_i32_e32 v113, 31, v112
	global_store_short v[96:97], v98, off offset:64
	v_and_b32_e32 v96, 0xff, v112
	v_lshl_add_u32 v96, v96, 2, v250
	ds_read_b96 v[96:98], v96
	v_lshlrev_b64 v[112:113], 11, v[112:113]
	v_lshl_add_u64 v[112:113], v[130:131], 0, v[112:113]
	s_waitcnt lgkmcnt(0)
	v_mul_f32_e32 v99, v116, v96
	v_mul_f32_e32 v96, v100, v96
	v_cvt_pk_bf16_f32 v99, v99, s0
	v_cvt_pk_bf16_f32 v96, v96, s0
	global_store_short v[112:113], v99, off
	global_store_short v[112:113], v96, off offset:64
	v_or_b32_e32 v112, v132, v186
	v_ashrrev_i32_e32 v113, 31, v112
	v_lshlrev_b64 v[112:113], 11, v[112:113]
	v_mul_f32_e32 v96, v117, v97
	v_lshl_add_u64 v[112:113], v[130:131], 0, v[112:113]
	v_cvt_pk_bf16_f32 v96, v96, s0
	global_store_short v[112:113], v96, off
	v_mul_f32_e32 v96, v101, v97
	v_cvt_pk_bf16_f32 v96, v96, s0
	global_store_short v[112:113], v96, off offset:64
	v_or_b32_e32 v96, v132, v187
	v_ashrrev_i32_e32 v97, 31, v96
	v_lshlrev_b64 v[96:97], 11, v[96:97]
	v_mul_f32_e32 v99, v118, v98
	v_mul_f32_e32 v98, v102, v98
	v_lshl_add_u64 v[96:97], v[130:131], 0, v[96:97]
	v_cvt_pk_bf16_f32 v99, v99, s0
	v_cvt_pk_bf16_f32 v98, v98, s0
	global_store_short v[96:97], v99, off
	global_store_short v[96:97], v98, off offset:64
	v_or_b32_e32 v96, v132, v188
	v_ashrrev_i32_e32 v97, 31, v96
	v_and_b32_e32 v98, 0xff, v96
	v_lshl_add_u32 v98, v98, 2, v250
	ds_read_b32 v98, v98
	v_lshlrev_b64 v[96:97], 11, v[96:97]
	v_or_b32_e32 v100, v132, v189
	v_lshl_add_u64 v[96:97], v[130:131], 0, v[96:97]
	v_ashrrev_i32_e32 v101, 31, v100
	s_waitcnt lgkmcnt(0)
	v_mul_f32_e32 v99, v119, v98
	v_mul_f32_e32 v98, v103, v98
	v_cvt_pk_bf16_f32 v99, v99, s0
	v_cvt_pk_bf16_f32 v98, v98, s0
	global_store_short v[96:97], v99, off
	global_store_short v[96:97], v98, off offset:64
	v_and_b32_e32 v96, 0xff, v100
	v_lshl_add_u32 v96, v96, 2, v250
	ds_read_b96 v[96:98], v96
	v_lshlrev_b64 v[100:101], 11, v[100:101]
	v_lshl_add_u64 v[100:101], v[130:131], 0, v[100:101]
	s_waitcnt lgkmcnt(0)
	v_mul_f32_e32 v99, v120, v96
	v_mul_f32_e32 v96, v104, v96
	v_cvt_pk_bf16_f32 v99, v99, s0
	v_cvt_pk_bf16_f32 v96, v96, s0
	global_store_short v[100:101], v99, off
	global_store_short v[100:101], v96, off offset:64
	v_or_b32_e32 v100, v132, v190
	v_ashrrev_i32_e32 v101, 31, v100
	v_lshlrev_b64 v[100:101], 11, v[100:101]
	v_mul_f32_e32 v96, v121, v97
	v_lshl_add_u64 v[100:101], v[130:131], 0, v[100:101]
	v_cvt_pk_bf16_f32 v96, v96, s0
	global_store_short v[100:101], v96, off
	v_mul_f32_e32 v96, v105, v97
	v_cvt_pk_bf16_f32 v96, v96, s0
	global_store_short v[100:101], v96, off offset:64
	v_or_b32_e32 v96, v132, v191
	v_ashrrev_i32_e32 v97, 31, v96
	v_lshlrev_b64 v[96:97], 11, v[96:97]
	v_mul_f32_e32 v99, v122, v98
	v_mul_f32_e32 v98, v106, v98
	v_lshl_add_u64 v[96:97], v[130:131], 0, v[96:97]
	v_cvt_pk_bf16_f32 v99, v99, s0
	v_cvt_pk_bf16_f32 v98, v98, s0
	global_store_short v[96:97], v99, off
	global_store_short v[96:97], v98, off offset:64
	v_or_b32_e32 v96, v132, v192
	v_ashrrev_i32_e32 v97, 31, v96
	v_and_b32_e32 v98, 0xff, v96
	v_lshl_add_u32 v98, v98, 2, v250
	ds_read_b32 v98, v98
	v_lshlrev_b64 v[96:97], 11, v[96:97]
	v_or_b32_e32 v100, v132, v193
	v_lshl_add_u64 v[96:97], v[130:131], 0, v[96:97]
	v_ashrrev_i32_e32 v101, 31, v100
	s_waitcnt lgkmcnt(0)
	v_mul_f32_e32 v99, v123, v98
	v_mul_f32_e32 v98, v107, v98
	v_cvt_pk_bf16_f32 v99, v99, s0
	v_cvt_pk_bf16_f32 v98, v98, s0
	global_store_short v[96:97], v99, off
	global_store_short v[96:97], v98, off offset:64
	v_and_b32_e32 v96, 0xff, v100
	v_lshl_add_u32 v96, v96, 2, v250
	ds_read_b96 v[96:98], v96
	v_lshlrev_b64 v[100:101], 11, v[100:101]
	v_lshl_add_u64 v[100:101], v[130:131], 0, v[100:101]
	s_waitcnt lgkmcnt(0)
	v_mul_f32_e32 v99, v124, v96
	v_mul_f32_e32 v96, v108, v96
	v_cvt_pk_bf16_f32 v99, v99, s0
	v_cvt_pk_bf16_f32 v96, v96, s0
	global_store_short v[100:101], v99, off
	global_store_short v[100:101], v96, off offset:64
	v_or_b32_e32 v100, v132, v194
	v_ashrrev_i32_e32 v101, 31, v100
	v_lshlrev_b64 v[100:101], 11, v[100:101]
	v_mul_f32_e32 v96, v125, v97
	v_lshl_add_u64 v[100:101], v[130:131], 0, v[100:101]
	v_cvt_pk_bf16_f32 v96, v96, s0
	global_store_short v[100:101], v96, off
	v_mul_f32_e32 v96, v109, v97
	v_cvt_pk_bf16_f32 v96, v96, s0
	global_store_short v[100:101], v96, off offset:64
	v_or_b32_e32 v96, v132, v195
	v_ashrrev_i32_e32 v97, 31, v96
	v_lshlrev_b64 v[96:97], 11, v[96:97]
	v_mul_f32_e32 v99, v126, v98
	v_mul_f32_e32 v98, v110, v98
	v_lshl_add_u64 v[96:97], v[130:131], 0, v[96:97]
	v_cvt_pk_bf16_f32 v99, v99, s0
	v_cvt_pk_bf16_f32 v98, v98, s0
	global_store_short v[96:97], v99, off
	global_store_short v[96:97], v98, off offset:64
	v_or_b32_e32 v96, v132, v196
	v_ashrrev_i32_e32 v97, 31, v96
	v_and_b32_e32 v98, 0xff, v96
	v_lshl_add_u32 v98, v98, 2, v250
	ds_read_b32 v98, v98
	v_lshlrev_b64 v[96:97], 11, v[96:97]
	v_lshl_add_u64 v[96:97], v[130:131], 0, v[96:97]
	s_waitcnt lgkmcnt(0)
	v_mul_f32_e32 v99, v127, v98
	v_mul_f32_e32 v98, v111, v98
	v_cvt_pk_bf16_f32 v99, v99, s0
	v_cvt_pk_bf16_f32 v98, v98, s0
	global_store_short v[96:97], v99, off
	global_store_short v[96:97], v98, off offset:64
	v_or_b32_e32 v96, 32, v132
	v_or_b32_e32 v102, v96, v181
	v_ashrrev_i32_e32 v103, 31, v102
	v_and_b32_e32 v98, 0xff, v102
	v_lshl_add_u32 v98, v98, 2, v250
	ds_read_b96 v[98:100], v98
	v_lshlrev_b64 v[102:103], 11, v[102:103]
	v_lshl_add_u64 v[102:103], v[130:131], 0, v[102:103]
	s_waitcnt lgkmcnt(0)
	v_mul_f32_e32 v80, v80, v98
	v_mul_f32_e32 v64, v64, v98
	v_cvt_pk_bf16_f32 v80, v80, s0
	v_cvt_pk_bf16_f32 v64, v64, s0
	global_store_short v[102:103], v80, off
	global_store_short v[102:103], v64, off offset:64
	v_or_b32_e32 v102, v96, v182
	v_ashrrev_i32_e32 v103, 31, v102
	v_lshlrev_b64 v[102:103], 11, v[102:103]
	v_mul_f32_e32 v64, v81, v99
	v_lshl_add_u64 v[102:103], v[130:131], 0, v[102:103]
	v_cvt_pk_bf16_f32 v64, v64, s0
	global_store_short v[102:103], v64, off
	v_mul_f32_e32 v64, v65, v99
	v_cvt_pk_bf16_f32 v64, v64, s0
	global_store_short v[102:103], v64, off offset:64
	v_or_b32_e32 v64, v96, v183
	v_ashrrev_i32_e32 v65, 31, v64
	v_lshlrev_b64 v[64:65], 11, v[64:65]
	v_mul_f32_e32 v80, v82, v100
	v_mul_f32_e32 v66, v66, v100
	v_lshl_add_u64 v[64:65], v[130:131], 0, v[64:65]
	v_cvt_pk_bf16_f32 v80, v80, s0
	v_cvt_pk_bf16_f32 v66, v66, s0
	global_store_short v[64:65], v80, off
	global_store_short v[64:65], v66, off offset:64
	v_or_b32_e32 v64, v96, v184
	v_ashrrev_i32_e32 v65, 31, v64
	v_and_b32_e32 v80, 0xff, v64
	v_lshl_add_u32 v80, v80, 2, v250
	ds_read_b32 v66, v80
	v_lshlrev_b64 v[64:65], 11, v[64:65]
	v_lshl_add_u64 v[64:65], v[130:131], 0, v[64:65]
	s_waitcnt lgkmcnt(0)
	v_mul_f32_e32 v80, v83, v66
	v_cvt_pk_bf16_f32 v80, v80, s0
	global_store_short v[64:65], v80, off
	v_mul_f32_e32 v66, v67, v66
	v_or_b32_e32 v80, v96, v185
	v_cvt_pk_bf16_f32 v66, v66, s0
	v_ashrrev_i32_e32 v81, 31, v80
	global_store_short v[64:65], v66, off offset:64
	v_and_b32_e32 v64, 0xff, v80
	v_lshl_add_u32 v64, v64, 2, v250
	ds_read_b96 v[64:66], v64
	v_lshlrev_b64 v[80:81], 11, v[80:81]
	v_lshl_add_u64 v[80:81], v[130:131], 0, v[80:81]
	s_waitcnt lgkmcnt(0)
	v_mul_f32_e32 v67, v84, v64
	v_mul_f32_e32 v64, v68, v64
	v_cvt_pk_bf16_f32 v67, v67, s0
	v_cvt_pk_bf16_f32 v64, v64, s0
	global_store_short v[80:81], v67, off
	global_store_short v[80:81], v64, off offset:64
	v_or_b32_e32 v80, v96, v186
	v_ashrrev_i32_e32 v81, 31, v80
	v_lshlrev_b64 v[80:81], 11, v[80:81]
	v_mul_f32_e32 v64, v85, v65
	v_lshl_add_u64 v[80:81], v[130:131], 0, v[80:81]
	v_cvt_pk_bf16_f32 v64, v64, s0
	global_store_short v[80:81], v64, off
	v_mul_f32_e32 v64, v69, v65
	v_cvt_pk_bf16_f32 v64, v64, s0
	global_store_short v[80:81], v64, off offset:64
	v_or_b32_e32 v64, v96, v187
	v_ashrrev_i32_e32 v65, 31, v64
	v_lshlrev_b64 v[64:65], 11, v[64:65]
	v_mul_f32_e32 v67, v86, v66
	v_mul_f32_e32 v66, v70, v66
	v_lshl_add_u64 v[64:65], v[130:131], 0, v[64:65]
	v_cvt_pk_bf16_f32 v67, v67, s0
	v_cvt_pk_bf16_f32 v66, v66, s0
	global_store_short v[64:65], v67, off
	global_store_short v[64:65], v66, off offset:64
	v_or_b32_e32 v64, v96, v188
	v_ashrrev_i32_e32 v65, 31, v64
	v_and_b32_e32 v66, 0xff, v64
	v_lshl_add_u32 v66, v66, 2, v250
	ds_read_b32 v66, v66
	v_lshlrev_b64 v[64:65], 11, v[64:65]
	v_or_b32_e32 v68, v96, v189
	v_lshl_add_u64 v[64:65], v[130:131], 0, v[64:65]
	v_ashrrev_i32_e32 v69, 31, v68
	s_waitcnt lgkmcnt(0)
	v_mul_f32_e32 v67, v87, v66
	v_mul_f32_e32 v66, v71, v66
	v_cvt_pk_bf16_f32 v67, v67, s0
	v_cvt_pk_bf16_f32 v66, v66, s0
	global_store_short v[64:65], v67, off
	global_store_short v[64:65], v66, off offset:64
	v_and_b32_e32 v64, 0xff, v68
	v_lshl_add_u32 v64, v64, 2, v250
	ds_read_b96 v[64:66], v64
	v_lshlrev_b64 v[68:69], 11, v[68:69]
	v_lshl_add_u64 v[68:69], v[130:131], 0, v[68:69]
	s_waitcnt lgkmcnt(0)
	v_mul_f32_e32 v67, v88, v64
	v_mul_f32_e32 v64, v72, v64
	v_cvt_pk_bf16_f32 v67, v67, s0
	v_cvt_pk_bf16_f32 v64, v64, s0
	global_store_short v[68:69], v67, off
	global_store_short v[68:69], v64, off offset:64
	v_or_b32_e32 v68, v96, v190
	v_ashrrev_i32_e32 v69, 31, v68
	v_lshlrev_b64 v[68:69], 11, v[68:69]
	v_mul_f32_e32 v64, v89, v65
	v_lshl_add_u64 v[68:69], v[130:131], 0, v[68:69]
	v_cvt_pk_bf16_f32 v64, v64, s0
	global_store_short v[68:69], v64, off
	v_mul_f32_e32 v64, v73, v65
	v_cvt_pk_bf16_f32 v64, v64, s0
	global_store_short v[68:69], v64, off offset:64
	v_or_b32_e32 v64, v96, v191
	v_ashrrev_i32_e32 v65, 31, v64
	v_lshlrev_b64 v[64:65], 11, v[64:65]
	v_mul_f32_e32 v67, v90, v66
	v_mul_f32_e32 v66, v74, v66
	v_lshl_add_u64 v[64:65], v[130:131], 0, v[64:65]
	v_cvt_pk_bf16_f32 v67, v67, s0
	v_cvt_pk_bf16_f32 v66, v66, s0
	global_store_short v[64:65], v67, off
	global_store_short v[64:65], v66, off offset:64
	v_or_b32_e32 v64, v96, v192
	v_ashrrev_i32_e32 v65, 31, v64
	v_and_b32_e32 v66, 0xff, v64
	v_lshl_add_u32 v66, v66, 2, v250
	ds_read_b32 v66, v66
	v_lshlrev_b64 v[64:65], 11, v[64:65]
	v_or_b32_e32 v68, v96, v193
	v_lshl_add_u64 v[64:65], v[130:131], 0, v[64:65]
	v_ashrrev_i32_e32 v69, 31, v68
	s_waitcnt lgkmcnt(0)
	v_mul_f32_e32 v67, v91, v66
	v_mul_f32_e32 v66, v75, v66
	v_cvt_pk_bf16_f32 v67, v67, s0
	v_cvt_pk_bf16_f32 v66, v66, s0
	global_store_short v[64:65], v67, off
	global_store_short v[64:65], v66, off offset:64
	v_and_b32_e32 v64, 0xff, v68
	v_lshl_add_u32 v64, v64, 2, v250
	ds_read_b96 v[64:66], v64
	v_lshlrev_b64 v[68:69], 11, v[68:69]
	v_lshl_add_u64 v[68:69], v[130:131], 0, v[68:69]
	s_waitcnt lgkmcnt(0)
	v_mul_f32_e32 v67, v92, v64
	v_mul_f32_e32 v64, v76, v64
	v_cvt_pk_bf16_f32 v67, v67, s0
	v_cvt_pk_bf16_f32 v64, v64, s0
	global_store_short v[68:69], v67, off
	global_store_short v[68:69], v64, off offset:64
	v_or_b32_e32 v68, v96, v194
	v_ashrrev_i32_e32 v69, 31, v68
	v_lshlrev_b64 v[68:69], 11, v[68:69]
	v_mul_f32_e32 v64, v93, v65
	v_lshl_add_u64 v[68:69], v[130:131], 0, v[68:69]
	v_cvt_pk_bf16_f32 v64, v64, s0
	global_store_short v[68:69], v64, off
	v_mul_f32_e32 v64, v77, v65
	v_cvt_pk_bf16_f32 v64, v64, s0
	global_store_short v[68:69], v64, off offset:64
	v_or_b32_e32 v64, v96, v195
	v_ashrrev_i32_e32 v65, 31, v64
	v_lshlrev_b64 v[64:65], 11, v[64:65]
	v_mul_f32_e32 v67, v94, v66
	v_mul_f32_e32 v66, v78, v66
	v_lshl_add_u64 v[64:65], v[130:131], 0, v[64:65]
	v_cvt_pk_bf16_f32 v67, v67, s0
	v_cvt_pk_bf16_f32 v66, v66, s0
	global_store_short v[64:65], v67, off
	global_store_short v[64:65], v66, off offset:64
	v_or_b32_e32 v64, v96, v196
	v_ashrrev_i32_e32 v65, 31, v64
	v_and_b32_e32 v66, 0xff, v64
	v_lshl_add_u32 v66, v66, 2, v250
	ds_read_b32 v66, v66
	v_lshlrev_b64 v[64:65], 11, v[64:65]
	v_lshl_add_u64 v[64:65], v[130:131], 0, v[64:65]
	s_waitcnt lgkmcnt(0)
	v_mul_f32_e32 v67, v95, v66
	v_mul_f32_e32 v66, v79, v66
	v_cvt_pk_bf16_f32 v67, v67, s0
	v_cvt_pk_bf16_f32 v66, v66, s0
	global_store_short v[64:65], v67, off
	global_store_short v[64:65], v66, off offset:64
	v_or_b32_e32 v64, 64, v132
	v_or_b32_e32 v70, v64, v181
	v_ashrrev_i32_e32 v71, 31, v70
	v_and_b32_e32 v66, 0xff, v70
	v_lshl_add_u32 v66, v66, 2, v250
	ds_read_b96 v[66:68], v66
	v_lshlrev_b64 v[70:71], 11, v[70:71]
	v_lshl_add_u64 v[70:71], v[130:131], 0, v[70:71]
	s_waitcnt lgkmcnt(0)
	v_mul_f32_e32 v48, v48, v66
	v_mul_f32_e32 v32, v32, v66
	v_cvt_pk_bf16_f32 v48, v48, s0
	v_cvt_pk_bf16_f32 v32, v32, s0
	global_store_short v[70:71], v48, off
	global_store_short v[70:71], v32, off offset:64
	v_or_b32_e32 v70, v64, v182
	v_ashrrev_i32_e32 v71, 31, v70
	v_lshlrev_b64 v[70:71], 11, v[70:71]
	v_mul_f32_e32 v32, v49, v67
	v_lshl_add_u64 v[70:71], v[130:131], 0, v[70:71]
	v_cvt_pk_bf16_f32 v32, v32, s0
	global_store_short v[70:71], v32, off
	v_mul_f32_e32 v32, v33, v67
	v_cvt_pk_bf16_f32 v32, v32, s0
	global_store_short v[70:71], v32, off offset:64
	v_or_b32_e32 v32, v64, v183
	v_ashrrev_i32_e32 v33, 31, v32
	v_lshlrev_b64 v[32:33], 11, v[32:33]
	v_mul_f32_e32 v48, v50, v68
	v_mul_f32_e32 v34, v34, v68
	v_lshl_add_u64 v[32:33], v[130:131], 0, v[32:33]
	v_cvt_pk_bf16_f32 v48, v48, s0
	v_cvt_pk_bf16_f32 v34, v34, s0
	global_store_short v[32:33], v48, off
	global_store_short v[32:33], v34, off offset:64
	v_or_b32_e32 v32, v64, v184
	v_ashrrev_i32_e32 v33, 31, v32
	v_and_b32_e32 v48, 0xff, v32
	v_lshl_add_u32 v48, v48, 2, v250
	ds_read_b32 v34, v48
	v_lshlrev_b64 v[32:33], 11, v[32:33]
	v_lshl_add_u64 v[32:33], v[130:131], 0, v[32:33]
	s_waitcnt lgkmcnt(0)
	v_mul_f32_e32 v48, v51, v34
	v_cvt_pk_bf16_f32 v48, v48, s0
	global_store_short v[32:33], v48, off
	v_mul_f32_e32 v34, v35, v34
	v_or_b32_e32 v48, v64, v185
	v_cvt_pk_bf16_f32 v34, v34, s0
	v_ashrrev_i32_e32 v49, 31, v48
	global_store_short v[32:33], v34, off offset:64
	v_and_b32_e32 v32, 0xff, v48
	v_lshl_add_u32 v32, v32, 2, v250
	ds_read_b96 v[32:34], v32
	v_lshlrev_b64 v[48:49], 11, v[48:49]
	v_lshl_add_u64 v[48:49], v[130:131], 0, v[48:49]
	s_waitcnt lgkmcnt(0)
	v_mul_f32_e32 v35, v52, v32
	v_mul_f32_e32 v32, v36, v32
	v_cvt_pk_bf16_f32 v35, v35, s0
	v_cvt_pk_bf16_f32 v32, v32, s0
	global_store_short v[48:49], v35, off
	global_store_short v[48:49], v32, off offset:64
	v_or_b32_e32 v48, v64, v186
	v_ashrrev_i32_e32 v49, 31, v48
	v_lshlrev_b64 v[48:49], 11, v[48:49]
	v_mul_f32_e32 v32, v53, v33
	v_lshl_add_u64 v[48:49], v[130:131], 0, v[48:49]
	v_cvt_pk_bf16_f32 v32, v32, s0
	global_store_short v[48:49], v32, off
	v_mul_f32_e32 v32, v37, v33
	v_cvt_pk_bf16_f32 v32, v32, s0
	global_store_short v[48:49], v32, off offset:64
	v_or_b32_e32 v32, v64, v187
	v_ashrrev_i32_e32 v33, 31, v32
	v_lshlrev_b64 v[32:33], 11, v[32:33]
	v_mul_f32_e32 v35, v54, v34
	v_mul_f32_e32 v34, v38, v34
	v_lshl_add_u64 v[32:33], v[130:131], 0, v[32:33]
	v_cvt_pk_bf16_f32 v35, v35, s0
	v_cvt_pk_bf16_f32 v34, v34, s0
	global_store_short v[32:33], v35, off
	global_store_short v[32:33], v34, off offset:64
	v_or_b32_e32 v32, v64, v188
	v_ashrrev_i32_e32 v33, 31, v32
	v_and_b32_e32 v34, 0xff, v32
	v_lshl_add_u32 v34, v34, 2, v250
	ds_read_b32 v34, v34
	v_lshlrev_b64 v[32:33], 11, v[32:33]
	v_or_b32_e32 v36, v64, v189
	v_lshl_add_u64 v[32:33], v[130:131], 0, v[32:33]
	v_ashrrev_i32_e32 v37, 31, v36
	s_waitcnt lgkmcnt(0)
	v_mul_f32_e32 v35, v55, v34
	v_mul_f32_e32 v34, v39, v34
	v_cvt_pk_bf16_f32 v35, v35, s0
	v_cvt_pk_bf16_f32 v34, v34, s0
	global_store_short v[32:33], v35, off
	global_store_short v[32:33], v34, off offset:64
	v_and_b32_e32 v32, 0xff, v36
	v_lshl_add_u32 v32, v32, 2, v250
	ds_read_b96 v[32:34], v32
	v_lshlrev_b64 v[36:37], 11, v[36:37]
	v_lshl_add_u64 v[36:37], v[130:131], 0, v[36:37]
	s_waitcnt lgkmcnt(0)
	v_mul_f32_e32 v35, v56, v32
	v_mul_f32_e32 v32, v40, v32
	v_cvt_pk_bf16_f32 v35, v35, s0
	v_cvt_pk_bf16_f32 v32, v32, s0
	global_store_short v[36:37], v35, off
	global_store_short v[36:37], v32, off offset:64
	v_or_b32_e32 v36, v64, v190
	v_ashrrev_i32_e32 v37, 31, v36
	v_lshlrev_b64 v[36:37], 11, v[36:37]
	v_mul_f32_e32 v32, v57, v33
	v_lshl_add_u64 v[36:37], v[130:131], 0, v[36:37]
	v_cvt_pk_bf16_f32 v32, v32, s0
	global_store_short v[36:37], v32, off
	v_mul_f32_e32 v32, v41, v33
	v_cvt_pk_bf16_f32 v32, v32, s0
	global_store_short v[36:37], v32, off offset:64
	v_or_b32_e32 v32, v64, v191
	v_ashrrev_i32_e32 v33, 31, v32
	v_lshlrev_b64 v[32:33], 11, v[32:33]
	v_mul_f32_e32 v35, v58, v34
	v_mul_f32_e32 v34, v42, v34
	v_lshl_add_u64 v[32:33], v[130:131], 0, v[32:33]
	v_cvt_pk_bf16_f32 v35, v35, s0
	v_cvt_pk_bf16_f32 v34, v34, s0
	global_store_short v[32:33], v35, off
	global_store_short v[32:33], v34, off offset:64
	v_or_b32_e32 v32, v64, v192
	v_ashrrev_i32_e32 v33, 31, v32
	v_and_b32_e32 v34, 0xff, v32
	v_lshl_add_u32 v34, v34, 2, v250
	ds_read_b32 v34, v34
	v_lshlrev_b64 v[32:33], 11, v[32:33]
	v_or_b32_e32 v36, v64, v193
	v_lshl_add_u64 v[32:33], v[130:131], 0, v[32:33]
	v_ashrrev_i32_e32 v37, 31, v36
	s_waitcnt lgkmcnt(0)
	v_mul_f32_e32 v35, v59, v34
	v_mul_f32_e32 v34, v43, v34
	v_cvt_pk_bf16_f32 v35, v35, s0
	v_cvt_pk_bf16_f32 v34, v34, s0
	global_store_short v[32:33], v35, off
	global_store_short v[32:33], v34, off offset:64
	v_and_b32_e32 v32, 0xff, v36
	v_lshl_add_u32 v32, v32, 2, v250
	ds_read_b96 v[32:34], v32
	v_lshlrev_b64 v[36:37], 11, v[36:37]
	v_lshl_add_u64 v[36:37], v[130:131], 0, v[36:37]
	s_waitcnt lgkmcnt(0)
	v_mul_f32_e32 v35, v60, v32
	v_mul_f32_e32 v32, v44, v32
	v_cvt_pk_bf16_f32 v35, v35, s0
	v_cvt_pk_bf16_f32 v32, v32, s0
	global_store_short v[36:37], v35, off
	global_store_short v[36:37], v32, off offset:64
	v_or_b32_e32 v36, v64, v194
	v_ashrrev_i32_e32 v37, 31, v36
	v_lshlrev_b64 v[36:37], 11, v[36:37]
	v_mul_f32_e32 v32, v61, v33
	v_lshl_add_u64 v[36:37], v[130:131], 0, v[36:37]
	v_cvt_pk_bf16_f32 v32, v32, s0
	global_store_short v[36:37], v32, off
	v_mul_f32_e32 v32, v45, v33
	v_cvt_pk_bf16_f32 v32, v32, s0
	global_store_short v[36:37], v32, off offset:64
	v_or_b32_e32 v32, v64, v195
	v_ashrrev_i32_e32 v33, 31, v32
	v_lshlrev_b64 v[32:33], 11, v[32:33]
	v_mul_f32_e32 v35, v62, v34
	v_mul_f32_e32 v34, v46, v34
	v_lshl_add_u64 v[32:33], v[130:131], 0, v[32:33]
	v_cvt_pk_bf16_f32 v35, v35, s0
	v_cvt_pk_bf16_f32 v34, v34, s0
	global_store_short v[32:33], v35, off
	global_store_short v[32:33], v34, off offset:64
	v_or_b32_e32 v32, v64, v196
	v_ashrrev_i32_e32 v33, 31, v32
	v_and_b32_e32 v34, 0xff, v32
	v_lshl_add_u32 v34, v34, 2, v250
	ds_read_b32 v34, v34
	v_lshlrev_b64 v[32:33], 11, v[32:33]
	v_lshl_add_u64 v[32:33], v[130:131], 0, v[32:33]
	s_waitcnt lgkmcnt(0)
	v_mul_f32_e32 v35, v63, v34
	v_mul_f32_e32 v34, v47, v34
	v_cvt_pk_bf16_f32 v35, v35, s0
	v_cvt_pk_bf16_f32 v34, v34, s0
	global_store_short v[32:33], v35, off
	global_store_short v[32:33], v34, off offset:64
	v_or_b32_e32 v32, 0x60, v132
	v_or_b32_e32 v38, v32, v181
	v_ashrrev_i32_e32 v39, 31, v38
	v_and_b32_e32 v34, 0xff, v38
	v_lshl_add_u32 v34, v34, 2, v250
	ds_read_b96 v[34:36], v34
	v_lshlrev_b64 v[38:39], 11, v[38:39]
	v_lshl_add_u64 v[38:39], v[130:131], 0, v[38:39]
	s_waitcnt lgkmcnt(0)
	v_mul_f32_e32 v16, v16, v34
	v_mul_f32_e32 v0, v0, v34
	v_cvt_pk_bf16_f32 v16, v16, s0
	v_cvt_pk_bf16_f32 v0, v0, s0
	global_store_short v[38:39], v16, off
	global_store_short v[38:39], v0, off offset:64
	v_or_b32_e32 v38, v32, v182
	v_ashrrev_i32_e32 v39, 31, v38
	v_lshlrev_b64 v[38:39], 11, v[38:39]
	v_mul_f32_e32 v0, v17, v35
	v_lshl_add_u64 v[38:39], v[130:131], 0, v[38:39]
	v_cvt_pk_bf16_f32 v0, v0, s0
	global_store_short v[38:39], v0, off
	v_mul_f32_e32 v0, v1, v35
	v_cvt_pk_bf16_f32 v0, v0, s0
	global_store_short v[38:39], v0, off offset:64
	v_or_b32_e32 v0, v32, v183
	v_ashrrev_i32_e32 v1, 31, v0
	v_lshlrev_b64 v[0:1], 11, v[0:1]
	v_mul_f32_e32 v16, v18, v36
	v_mul_f32_e32 v2, v2, v36
	v_lshl_add_u64 v[0:1], v[130:131], 0, v[0:1]
	v_cvt_pk_bf16_f32 v16, v16, s0
	v_cvt_pk_bf16_f32 v2, v2, s0
	global_store_short v[0:1], v16, off
	global_store_short v[0:1], v2, off offset:64
	v_or_b32_e32 v0, v32, v184
	v_ashrrev_i32_e32 v1, 31, v0
	v_and_b32_e32 v16, 0xff, v0
	v_lshl_add_u32 v16, v16, 2, v250
	ds_read_b32 v2, v16
	v_lshlrev_b64 v[0:1], 11, v[0:1]
	v_lshl_add_u64 v[0:1], v[130:131], 0, v[0:1]
	s_waitcnt lgkmcnt(0)
	v_mul_f32_e32 v16, v19, v2
	v_cvt_pk_bf16_f32 v16, v16, s0
	global_store_short v[0:1], v16, off
	v_mul_f32_e32 v2, v3, v2
	v_or_b32_e32 v16, v32, v185
	v_cvt_pk_bf16_f32 v2, v2, s0
	v_ashrrev_i32_e32 v17, 31, v16
	global_store_short v[0:1], v2, off offset:64
	v_and_b32_e32 v0, 0xff, v16
	v_lshl_add_u32 v0, v0, 2, v250
	ds_read_b96 v[0:2], v0
	v_lshlrev_b64 v[16:17], 11, v[16:17]
	v_lshl_add_u64 v[16:17], v[130:131], 0, v[16:17]
	s_waitcnt lgkmcnt(0)
	v_mul_f32_e32 v3, v20, v0
	v_mul_f32_e32 v0, v4, v0
	v_cvt_pk_bf16_f32 v3, v3, s0
	v_cvt_pk_bf16_f32 v0, v0, s0
	global_store_short v[16:17], v3, off
	global_store_short v[16:17], v0, off offset:64
	v_or_b32_e32 v16, v32, v186
	v_ashrrev_i32_e32 v17, 31, v16
	v_lshlrev_b64 v[16:17], 11, v[16:17]
	v_mul_f32_e32 v0, v21, v1
	v_lshl_add_u64 v[16:17], v[130:131], 0, v[16:17]
	v_cvt_pk_bf16_f32 v0, v0, s0
	global_store_short v[16:17], v0, off
	v_mul_f32_e32 v0, v5, v1
	v_cvt_pk_bf16_f32 v0, v0, s0
	global_store_short v[16:17], v0, off offset:64
	v_or_b32_e32 v0, v32, v187
	v_ashrrev_i32_e32 v1, 31, v0
	v_lshlrev_b64 v[0:1], 11, v[0:1]
	v_mul_f32_e32 v3, v22, v2
	v_mul_f32_e32 v2, v6, v2
	v_lshl_add_u64 v[0:1], v[130:131], 0, v[0:1]
	v_cvt_pk_bf16_f32 v3, v3, s0
	v_cvt_pk_bf16_f32 v2, v2, s0
	global_store_short v[0:1], v3, off
	global_store_short v[0:1], v2, off offset:64
	v_or_b32_e32 v0, v32, v188
	v_ashrrev_i32_e32 v1, 31, v0
	v_and_b32_e32 v2, 0xff, v0
	v_lshl_add_u32 v2, v2, 2, v250
	ds_read_b32 v2, v2
	v_lshlrev_b64 v[0:1], 11, v[0:1]
	v_or_b32_e32 v4, v32, v189
	v_lshl_add_u64 v[0:1], v[130:131], 0, v[0:1]
	v_ashrrev_i32_e32 v5, 31, v4
	s_waitcnt lgkmcnt(0)
	v_mul_f32_e32 v3, v23, v2
	v_mul_f32_e32 v2, v7, v2
	v_cvt_pk_bf16_f32 v3, v3, s0
	v_cvt_pk_bf16_f32 v2, v2, s0
	global_store_short v[0:1], v3, off
	global_store_short v[0:1], v2, off offset:64
	v_and_b32_e32 v0, 0xff, v4
	v_lshl_add_u32 v0, v0, 2, v250
	ds_read_b96 v[0:2], v0
	v_lshlrev_b64 v[4:5], 11, v[4:5]
	v_lshl_add_u64 v[4:5], v[130:131], 0, v[4:5]
	s_waitcnt lgkmcnt(0)
	v_mul_f32_e32 v3, v24, v0
	v_mul_f32_e32 v0, v8, v0
	v_cvt_pk_bf16_f32 v3, v3, s0
	v_cvt_pk_bf16_f32 v0, v0, s0
	global_store_short v[4:5], v3, off
	global_store_short v[4:5], v0, off offset:64
	v_or_b32_e32 v4, v32, v190
	v_ashrrev_i32_e32 v5, 31, v4
	v_lshlrev_b64 v[4:5], 11, v[4:5]
	v_mul_f32_e32 v0, v25, v1
	v_lshl_add_u64 v[4:5], v[130:131], 0, v[4:5]
	v_cvt_pk_bf16_f32 v0, v0, s0
	global_store_short v[4:5], v0, off
	v_mul_f32_e32 v0, v9, v1
	v_cvt_pk_bf16_f32 v0, v0, s0
	global_store_short v[4:5], v0, off offset:64
	v_or_b32_e32 v0, v32, v191
	v_ashrrev_i32_e32 v1, 31, v0
	v_lshlrev_b64 v[0:1], 11, v[0:1]
	v_mul_f32_e32 v3, v26, v2
	v_mul_f32_e32 v2, v10, v2
	v_lshl_add_u64 v[0:1], v[130:131], 0, v[0:1]
	v_cvt_pk_bf16_f32 v3, v3, s0
	v_cvt_pk_bf16_f32 v2, v2, s0
	global_store_short v[0:1], v3, off
	global_store_short v[0:1], v2, off offset:64
	v_or_b32_e32 v0, v32, v192
	v_ashrrev_i32_e32 v1, 31, v0
	v_and_b32_e32 v2, 0xff, v0
	v_lshl_add_u32 v2, v2, 2, v250
	ds_read_b32 v2, v2
	v_lshlrev_b64 v[0:1], 11, v[0:1]
	v_or_b32_e32 v4, v32, v193
	v_lshl_add_u64 v[0:1], v[130:131], 0, v[0:1]
	v_ashrrev_i32_e32 v5, 31, v4
	s_waitcnt lgkmcnt(0)
	v_mul_f32_e32 v3, v27, v2
	v_mul_f32_e32 v2, v11, v2
	v_cvt_pk_bf16_f32 v3, v3, s0
	v_cvt_pk_bf16_f32 v2, v2, s0
	global_store_short v[0:1], v3, off
	global_store_short v[0:1], v2, off offset:64
	v_and_b32_e32 v0, 0xff, v4
	v_lshl_add_u32 v0, v0, 2, v250
	ds_read_b96 v[0:2], v0
	v_lshlrev_b64 v[4:5], 11, v[4:5]
	v_lshl_add_u64 v[4:5], v[130:131], 0, v[4:5]
	s_waitcnt lgkmcnt(0)
	v_mul_f32_e32 v3, v28, v0
	v_mul_f32_e32 v0, v12, v0
	v_cvt_pk_bf16_f32 v3, v3, s0
	v_cvt_pk_bf16_f32 v0, v0, s0
	global_store_short v[4:5], v3, off
	global_store_short v[4:5], v0, off offset:64
	v_or_b32_e32 v4, v32, v194
	v_ashrrev_i32_e32 v5, 31, v4
	v_lshlrev_b64 v[4:5], 11, v[4:5]
	v_mul_f32_e32 v0, v29, v1
	v_lshl_add_u64 v[4:5], v[130:131], 0, v[4:5]
	v_cvt_pk_bf16_f32 v0, v0, s0
	global_store_short v[4:5], v0, off
	v_mul_f32_e32 v0, v13, v1
	v_cvt_pk_bf16_f32 v0, v0, s0
	global_store_short v[4:5], v0, off offset:64
	v_or_b32_e32 v0, v32, v195
	v_ashrrev_i32_e32 v1, 31, v0
	v_lshlrev_b64 v[0:1], 11, v[0:1]
	v_mul_f32_e32 v3, v30, v2
	v_mul_f32_e32 v2, v14, v2
	v_lshl_add_u64 v[0:1], v[130:131], 0, v[0:1]
	v_cvt_pk_bf16_f32 v3, v3, s0
	v_cvt_pk_bf16_f32 v2, v2, s0
	global_store_short v[0:1], v3, off
	global_store_short v[0:1], v2, off offset:64
	v_or_b32_e32 v0, v32, v196
	v_ashrrev_i32_e32 v1, 31, v0
	v_and_b32_e32 v2, 0xff, v0
	v_lshl_add_u32 v2, v2, 2, v250
	ds_read_b32 v2, v2
	v_lshlrev_b64 v[0:1], 11, v[0:1]
	v_lshl_add_u64 v[0:1], v[130:131], 0, v[0:1]
	s_waitcnt lgkmcnt(0)
	v_mul_f32_e32 v3, v31, v2
	v_mul_f32_e32 v2, v15, v2
	v_cvt_pk_bf16_f32 v3, v3, s0
	v_cvt_pk_bf16_f32 v2, v2, s0
	global_store_short v[0:1], v3, off
	global_store_short v[0:1], v2, off offset:64
	s_cbranch_scc0 .LBB0_2225

.LBB0_2340:
	s_and_b32 s19, s18, 0x18000
	v_add_u32_e32 v187, s19, v180
	s_add_i32 s19, s18, 0xfffe8000
	s_and_b32 s19, s19, 0x18000
	v_or_b32_e32 v212, s19, v179
	v_add_u32_e32 v213, s19, v176
	s_waitcnt lgkmcnt(0)
	v_mfma_f32_32x32x16_bf16 v[112:127], v[150:153], v[142:145], v[112:127]
	v_mfma_f32_32x32x16_bf16 v[96:111], v[150:153], v[130:133], v[96:111]
	v_mfma_f32_32x32x16_bf16 v[80:95], v[146:149], v[142:145], v[80:95]
	v_mfma_f32_32x32x16_bf16 v[64:79], v[146:149], v[130:133], v[64:79]
	s_waitcnt vmcnt(8)
	s_barrier
	v_add_u32_e32 v192, v212, v177
	v_add_u32_e32 v208, v213, v177
	ds_read_b128 v[188:191], v192 offset:16384
	ds_read_b128 v[192:195], v192 offset:18432
	ds_read_b128 v[196:199], v208
	v_mfma_f32_32x32x16_bf16 v[48:63], v[138:141], v[142:145], v[48:63]
	v_mfma_f32_32x32x16_bf16 v[32:47], v[138:141], v[130:133], v[32:47]
	ds_read_b128 v[200:203], v208 offset:2048
	v_readfirstlane_b32 s19, v187
	s_mov_b32 m0, s19
	s_nop 0
	global_load_lds_dwordx4 v[170:171], off
	v_mfma_f32_32x32x16_bf16 v[16:31], v[134:137], v[142:145], v[16:31]
	v_mfma_f32_32x32x16_bf16 v[0:15], v[134:137], v[130:133], v[0:15]
	ds_read_b128 v[204:207], v208 offset:4096
	s_add_i32 s20, s19, 0x2000
	v_lshl_add_u64 v[150:151], v[170:171], 0, s[34:35]
	s_mov_b32 m0, s20
	s_nop 0
	global_load_lds_dwordx4 v[150:151], off
	ds_read_b128 v[208:211], v208 offset:6144
	s_waitcnt lgkmcnt(3)
	v_mfma_f32_32x32x16_bf16 v[112:127], v[196:199], v[188:191], v[112:127]
	v_add_u32_e32 v130, v212, v178
	v_add_u32_e32 v134, v213, v178
	ds_read_b128 v[142:145], v130 offset:16384
	v_mfma_f32_32x32x16_bf16 v[96:111], v[196:199], v[192:195], v[96:111]
	ds_read_b128 v[130:133], v130 offset:18432
	s_add_i32 s20, s19, 0x6000
	s_addk_i32 s19, 0x4000
	s_mov_b32 m0, s19
	s_nop 0
	global_load_lds_dwordx4 v[172:173], off
	s_waitcnt lgkmcnt(4)
	v_mfma_f32_32x32x16_bf16 v[80:95], v[200:203], v[188:191], v[80:95]
	ds_read_b128 v[150:153], v134
	v_mfma_f32_32x32x16_bf16 v[64:79], v[200:203], v[192:195], v[64:79]
	ds_read_b128 v[146:149], v134 offset:2048
	s_waitcnt lgkmcnt(5)
	v_mfma_f32_32x32x16_bf16 v[48:63], v[204:207], v[188:191], v[48:63]
	ds_read_b128 v[138:141], v134 offset:4096
	v_mfma_f32_32x32x16_bf16 v[32:47], v[204:207], v[192:195], v[32:47]
	ds_read_b128 v[134:137], v134 offset:6144
	v_lshl_add_u64 v[212:213], v[172:173], 0, s[34:35]
	s_mov_b32 m0, s20
	s_nop 0
	global_load_lds_dwordx4 v[212:213], off
	s_waitcnt lgkmcnt(6)
	v_mfma_f32_32x32x16_bf16 v[16:31], v[208:211], v[188:191], v[16:31]
	s_add_i32 s18, s18, 0x8000
	v_lshl_add_u64 v[170:171], v[170:171], 0, 64
	v_lshl_add_u64 v[172:173], v[172:173], 0, 64
	s_cmp_eq_u32 s18, 0x100000
	v_mfma_f32_32x32x16_bf16 v[0:15], v[208:211], v[192:195], v[0:15]
	s_cbranch_scc0 .LBB0_2340
	s_waitcnt vmcnt(8) lgkmcnt(0)
	s_barrier
	v_add_u32_e32 v187, v179, v177
	ds_read_b128 v[170:173], v187 offset:49152
	ds_read_b128 v[188:191], v187 offset:51200
	v_add_u32_e32 v187, v176, v177
	ds_read_b128 v[192:195], v187 offset:32768
	ds_read_b128 v[196:199], v187 offset:34816
	ds_read_b128 v[200:203], v187 offset:36864
	ds_read_b128 v[204:207], v187 offset:38912
	s_waitcnt lgkmcnt(9)
	v_mfma_f32_32x32x16_bf16 v[112:127], v[150:153], v[142:145], v[112:127]
	v_mfma_f32_32x32x16_bf16 v[96:111], v[150:153], v[130:133], v[96:111]
	s_waitcnt lgkmcnt(8)
	v_mfma_f32_32x32x16_bf16 v[80:95], v[146:149], v[142:145], v[80:95]
	v_mfma_f32_32x32x16_bf16 v[64:79], v[146:149], v[130:133], v[64:79]
	s_waitcnt lgkmcnt(7)
	v_mfma_f32_32x32x16_bf16 v[48:63], v[138:141], v[142:145], v[48:63]
	v_mfma_f32_32x32x16_bf16 v[32:47], v[138:141], v[130:133], v[32:47]
	s_waitcnt lgkmcnt(6)
	v_mfma_f32_32x32x16_bf16 v[16:31], v[134:137], v[142:145], v[16:31]
	v_mfma_f32_32x32x16_bf16 v[0:15], v[134:137], v[130:133], v[0:15]
	v_add_u32_e32 v134, v179, v178
	v_add_u32_e32 v150, v176, v178
	ds_read_b128 v[130:133], v134 offset:49152
	ds_read_b128 v[134:137], v134 offset:51200
	ds_read_b128 v[138:141], v150 offset:32768
	ds_read_b128 v[142:145], v150 offset:34816
	ds_read_b128 v[146:149], v150 offset:36864
	ds_read_b128 v[150:153], v150 offset:38912
	s_waitcnt lgkmcnt(9)
	v_mfma_f32_32x32x16_bf16 v[112:127], v[192:195], v[170:173], v[112:127]
	v_mfma_f32_32x32x16_bf16 v[96:111], v[192:195], v[188:191], v[96:111]
	s_waitcnt lgkmcnt(8)
	v_mfma_f32_32x32x16_bf16 v[80:95], v[196:199], v[170:173], v[80:95]
	v_mfma_f32_32x32x16_bf16 v[64:79], v[196:199], v[188:191], v[64:79]
	s_waitcnt lgkmcnt(7)
	v_mfma_f32_32x32x16_bf16 v[48:63], v[200:203], v[170:173], v[48:63]
	v_mfma_f32_32x32x16_bf16 v[32:47], v[200:203], v[188:191], v[32:47]
	s_waitcnt vmcnt(4) lgkmcnt(0)
	s_barrier
	v_add_u32_e32 v187, v184, v177
	s_waitcnt lgkmcnt(6)
	v_mfma_f32_32x32x16_bf16 v[16:31], v[204:207], v[170:173], v[16:31]
	v_mfma_f32_32x32x16_bf16 v[0:15], v[204:207], v[188:191], v[0:15]
	ds_read_b128 v[170:173], v187 offset:16384
	ds_read_b128 v[188:191], v187 offset:18432
	v_add_u32_e32 v187, v185, v177
	ds_read_b128 v[192:195], v187
	ds_read_b128 v[196:199], v187 offset:2048
	ds_read_b128 v[200:203], v187 offset:4096
	ds_read_b128 v[204:207], v187 offset:6144
	s_waitcnt lgkmcnt(9)
	v_mfma_f32_32x32x16_bf16 v[112:127], v[138:141], v[130:133], v[112:127]
	v_mfma_f32_32x32x16_bf16 v[96:111], v[138:141], v[134:137], v[96:111]
	s_waitcnt lgkmcnt(8)
	v_mfma_f32_32x32x16_bf16 v[80:95], v[142:145], v[130:133], v[80:95]
	v_mfma_f32_32x32x16_bf16 v[64:79], v[142:145], v[134:137], v[64:79]
	s_waitcnt lgkmcnt(7)
	v_mfma_f32_32x32x16_bf16 v[48:63], v[146:149], v[130:133], v[48:63]
	v_mfma_f32_32x32x16_bf16 v[32:47], v[146:149], v[134:137], v[32:47]
	s_waitcnt lgkmcnt(6)
	v_mfma_f32_32x32x16_bf16 v[16:31], v[150:153], v[130:133], v[16:31]
	v_mfma_f32_32x32x16_bf16 v[0:15], v[150:153], v[134:137], v[0:15]
	v_add_u32_e32 v134, v184, v178
	v_add_u32_e32 v150, v185, v178
	ds_read_b128 v[130:133], v134 offset:16384
	ds_read_b128 v[134:137], v134 offset:18432
	ds_read_b128 v[138:141], v150
	ds_read_b128 v[142:145], v150 offset:2048
	ds_read_b128 v[146:149], v150 offset:4096
	ds_read_b128 v[150:153], v150 offset:6144
	s_waitcnt lgkmcnt(9)
	v_mfma_f32_32x32x16_bf16 v[112:127], v[192:195], v[170:173], v[112:127]
	v_mfma_f32_32x32x16_bf16 v[96:111], v[192:195], v[188:191], v[96:111]
	s_waitcnt lgkmcnt(8)
	v_mfma_f32_32x32x16_bf16 v[80:95], v[196:199], v[170:173], v[80:95]
	v_mfma_f32_32x32x16_bf16 v[64:79], v[196:199], v[188:191], v[64:79]
	s_waitcnt lgkmcnt(7)
	v_mfma_f32_32x32x16_bf16 v[48:63], v[200:203], v[170:173], v[48:63]
	v_mfma_f32_32x32x16_bf16 v[32:47], v[200:203], v[188:191], v[32:47]
	s_waitcnt vmcnt(0) lgkmcnt(0)
	s_barrier
	v_add_u32_e32 v187, v182, v177
	s_waitcnt lgkmcnt(6)
	v_mfma_f32_32x32x16_bf16 v[16:31], v[204:207], v[170:173], v[16:31]
	v_mfma_f32_32x32x16_bf16 v[0:15], v[204:207], v[188:191], v[0:15]
	ds_read_b128 v[170:173], v187 offset:16384
	ds_read_b128 v[188:191], v187 offset:18432
	v_add_u32_e32 v187, v183, v177
	ds_read_b128 v[192:195], v187
	ds_read_b128 v[196:199], v187 offset:2048
	ds_read_b128 v[200:203], v187 offset:4096
	ds_read_b128 v[204:207], v187 offset:6144
	s_waitcnt lgkmcnt(9)
	v_mfma_f32_32x32x16_bf16 v[112:127], v[138:141], v[130:133], v[112:127]
	v_mfma_f32_32x32x16_bf16 v[96:111], v[138:141], v[134:137], v[96:111]
	s_waitcnt lgkmcnt(8)
	v_mfma_f32_32x32x16_bf16 v[80:95], v[142:145], v[130:133], v[80:95]
	v_mfma_f32_32x32x16_bf16 v[64:79], v[142:145], v[134:137], v[64:79]
	s_waitcnt lgkmcnt(7)
	v_mfma_f32_32x32x16_bf16 v[48:63], v[146:149], v[130:133], v[48:63]
	v_mfma_f32_32x32x16_bf16 v[32:47], v[146:149], v[134:137], v[32:47]
	s_waitcnt lgkmcnt(6)
	v_mfma_f32_32x32x16_bf16 v[16:31], v[150:153], v[130:133], v[16:31]
	v_mfma_f32_32x32x16_bf16 v[0:15], v[150:153], v[134:137], v[0:15]
	v_add_u32_e32 v134, v182, v178
	v_add_u32_e32 v150, v183, v178
	ds_read_b128 v[130:133], v134 offset:16384
	ds_read_b128 v[134:137], v134 offset:18432
	ds_read_b128 v[138:141], v150
	ds_read_b128 v[142:145], v150 offset:2048
	ds_read_b128 v[146:149], v150 offset:4096
	ds_read_b128 v[150:153], v150 offset:6144
	s_waitcnt lgkmcnt(9)
	v_mfma_f32_32x32x16_bf16 v[112:127], v[192:195], v[170:173], v[112:127]
	v_mfma_f32_32x32x16_bf16 v[96:111], v[192:195], v[188:191], v[96:111]
	s_waitcnt lgkmcnt(8)
	v_mfma_f32_32x32x16_bf16 v[80:95], v[196:199], v[170:173], v[80:95]
	v_mfma_f32_32x32x16_bf16 v[64:79], v[196:199], v[188:191], v[64:79]
	s_waitcnt lgkmcnt(7)
	v_mfma_f32_32x32x16_bf16 v[48:63], v[200:203], v[170:173], v[48:63]
	v_mfma_f32_32x32x16_bf16 v[32:47], v[200:203], v[188:191], v[32:47]
	s_waitcnt lgkmcnt(6)
	v_mfma_f32_32x32x16_bf16 v[16:31], v[204:207], v[170:173], v[16:31]
	v_mfma_f32_32x32x16_bf16 v[0:15], v[204:207], v[188:191], v[0:15]
	s_waitcnt lgkmcnt(3)
	v_mfma_f32_32x32x16_bf16 v[112:127], v[138:141], v[130:133], v[112:127]
	s_waitcnt lgkmcnt(2)
	v_mfma_f32_32x32x16_bf16 v[80:95], v[142:145], v[130:133], v[80:95]
	s_waitcnt lgkmcnt(1)
	v_mfma_f32_32x32x16_bf16 v[48:63], v[146:149], v[130:133], v[48:63]
	s_waitcnt lgkmcnt(0)
	v_mfma_f32_32x32x16_bf16 v[16:31], v[150:153], v[130:133], v[16:31]
	v_or_b32_e32 v132, s12, v174
	v_ashrrev_i32_e32 v130, 1, v132
	v_or_b32_e32 v130, v130, v154
	v_ashrrev_i32_e32 v131, 31, v130
	s_movk_i32 s12, 0x5000
	v_mfma_f32_32x32x16_bf16 v[96:111], v[138:141], v[134:137], v[96:111]
	v_mfma_f32_32x32x16_bf16 v[64:79], v[142:145], v[134:137], v[64:79]
	v_add_u32_e32 v142, s13, v155
	s_mov_b32 s13, 0xb000
	v_ashrrev_i32_e32 v133, 7, v142
	v_mfma_f32_32x32x16_bf16 v[32:47], v[146:149], v[134:137], v[32:47]
	v_mfma_f32_32x32x16_bf16 v[0:15], v[150:153], v[134:137], v[0:15]
	v_lshl_add_u64 v[134:135], v[130:131], 2, s[10:11]
	v_add_co_u32_e32 v138, vcc, s12, v134
	s_mov_b32 s12, 0x8000
	s_nop 0
	v_addc_co_u32_e32 v139, vcc, 0, v135, vcc
	global_load_dword v137, v[138:139], off offset:2048
	v_add_co_u32_e32 v138, vcc, s13, v134
	global_load_dword v136, v[134:135], off
	s_nop 0
	v_addc_co_u32_e32 v139, vcc, 0, v135, vcc
	v_add_co_u32_e32 v140, vcc, s47, v134
	global_load_dword v139, v[138:139], off
	s_nop 0
	v_addc_co_u32_e32 v141, vcc, 0, v135, vcc
	global_load_dword v138, v[140:141], off offset:3072
	v_add_co_u32_e32 v140, vcc, s12, v134
	s_mov_b32 s12, 0xd000
	s_nop 0
	v_addc_co_u32_e32 v141, vcc, 0, v135, vcc
	v_add_co_u32_e32 v134, vcc, s12, v134
	global_load_dword v140, v[140:141], off offset:1024
	s_nop 0
	v_addc_co_u32_e32 v135, vcc, 0, v135, vcc
	global_load_dword v141, v[134:135], off offset:3072
	v_readlane_b32 s100, v252, 7
	s_add_i32 s100, s14, s100
	s_cmpk_lt_i32 s100, 0xb0
	s_cbranch_scc0 .Lpf_none_up
	s_and_b32 vcc_lo, s100, 7
	s_or_b32 vcc_lo, vcc_lo, s16
	s_lshl_b32 vcc_lo, vcc_lo, 8
	v_add_u32_e32 v238, vcc_lo, v175
	v_ashrrev_i32_e32 v239, 31, v238
	v_lshlrev_b64 v[238:239], 11, v[238:239]
	v_lshl_add_u64 v[238:239], v[156:157], 0, v[238:239]
	s_lshl_b32 vcc_lo, s100, 5
	s_and_b32 vcc_lo, vcc_lo, 0xffffff00
	v_add_u32_e32 v240, vcc_lo, v175
	v_ashrrev_i32_e32 v241, 31, v240
	v_lshlrev_b64 v[240:241], 11, v[240:241]
	v_lshl_add_u64 v[240:241], v[158:159], 0, v[240:241]
	v_readfirstlane_b32 s100, v180
	s_mov_b32 m0, s100
	s_nop 0
	global_load_lds_dwordx4 v[238:239], off
	v_lshl_add_u64 v[242:243], v[238:239], 0, s[34:35]
	s_add_i32 m0, s100, 0x2000
	s_nop 0
	global_load_lds_dwordx4 v[242:243], off
	s_add_i32 m0, s100, 0x4000
	s_nop 0
	global_load_lds_dwordx4 v[240:241], off
	v_lshl_add_u64 v[242:243], v[240:241], 0, s[34:35]
	s_add_i32 m0, s100, 0x6000
	s_nop 0
	global_load_lds_dwordx4 v[242:243], off
	v_lshl_add_u64 v[242:243], v[238:239], 0, 64
	s_add_i32 m0, s100, 0x8000
	s_nop 0
	global_load_lds_dwordx4 v[242:243], off
	s_mov_b64 vcc, 0x40040
	v_lshl_add_u64 v[242:243], v[238:239], 0, vcc
	s_add_i32 m0, s100, 0xa000
	s_nop 0
	global_load_lds_dwordx4 v[242:243], off
	v_lshl_add_u64 v[242:243], v[240:241], 0, 64
	s_add_i32 m0, s100, 0xc000
	s_nop 0
	global_load_lds_dwordx4 v[242:243], off
	s_mov_b64 vcc, 0x40040
	v_lshl_add_u64 v[242:243], v[240:241], 0, vcc
	s_add_i32 m0, s100, 0xe000
	s_nop 0
	global_load_lds_dwordx4 v[242:243], off
	s_mov_b64 vcc, 0x80
	v_lshl_add_u64 v[242:243], v[238:239], 0, vcc
	s_add_i32 m0, s100, 0x10000
	s_nop 0
	global_load_lds_dwordx4 v[242:243], off
	s_mov_b64 vcc, 0x40080
	v_lshl_add_u64 v[242:243], v[238:239], 0, vcc
	s_add_i32 m0, s100, 0x12000
	s_nop 0
	global_load_lds_dwordx4 v[242:243], off
	s_mov_b64 vcc, 0x80
	v_lshl_add_u64 v[242:243], v[240:241], 0, vcc
	s_add_i32 m0, s100, 0x14000
	s_nop 0
	global_load_lds_dwordx4 v[242:243], off
	s_mov_b64 vcc, 0x40080
	v_lshl_add_u64 v[242:243], v[240:241], 0, vcc
	s_add_i32 m0, s100, 0x16000
	s_nop 0
	global_load_lds_dwordx4 v[242:243], off
	s_mov_b32 s101, 1
	s_branch .Lpf_done_up

.LBB0_2551:
	s_and_b32 s7, s5, 0x18000
	v_add_u32_e32 v222, s7, v180
	s_add_i32 s7, s5, 0xfffe8000
	s_and_b32 s7, s7, 0x18000
	v_or_b32_e32 v223, s7, v179
	v_add_u32_e32 v233, s7, v176
	s_waitcnt lgkmcnt(0)
	v_mfma_f32_32x32x16_bf16 v[112:127], v[150:153], v[142:145], v[112:127]
	v_mfma_f32_32x32x16_bf16 v[96:111], v[150:153], v[130:133], v[96:111]
	v_mfma_f32_32x32x16_bf16 v[80:95], v[146:149], v[142:145], v[80:95]
	v_mfma_f32_32x32x16_bf16 v[64:79], v[146:149], v[130:133], v[64:79]
	s_waitcnt vmcnt(8)
	s_barrier
	v_add_u32_e32 v206, v223, v177
	v_add_u32_e32 v234, v233, v177
	ds_read_b128 v[202:205], v206 offset:16384
	ds_read_b128 v[206:209], v206 offset:18432
	ds_read_b128 v[210:213], v234
	v_mfma_f32_32x32x16_bf16 v[48:63], v[138:141], v[142:145], v[48:63]
	v_mfma_f32_32x32x16_bf16 v[32:47], v[138:141], v[130:133], v[32:47]
	ds_read_b128 v[214:217], v234 offset:2048
	v_readfirstlane_b32 s7, v222
	s_mov_b32 m0, s7
	s_nop 0
	global_load_lds_dwordx4 v[170:171], off
	v_mfma_f32_32x32x16_bf16 v[16:31], v[134:137], v[142:145], v[16:31]
	v_mfma_f32_32x32x16_bf16 v[0:15], v[134:137], v[130:133], v[0:15]
	ds_read_b128 v[224:227], v234 offset:4096
	s_add_i32 s8, s7, 0x2000
	v_lshl_add_u64 v[150:151], v[170:171], 0, s[10:11]
	s_mov_b32 m0, s8
	s_nop 0
	global_load_lds_dwordx4 v[150:151], off
	ds_read_b128 v[234:237], v234 offset:6144
	s_waitcnt lgkmcnt(3)
	v_mfma_f32_32x32x16_bf16 v[112:127], v[210:213], v[202:205], v[112:127]
	v_add_u32_e32 v130, v223, v178
	v_add_u32_e32 v134, v233, v178
	ds_read_b128 v[142:145], v130 offset:16384
	v_mfma_f32_32x32x16_bf16 v[96:111], v[210:213], v[206:209], v[96:111]
	ds_read_b128 v[130:133], v130 offset:18432
	s_add_i32 s8, s7, 0x6000
	s_addk_i32 s7, 0x4000
	s_mov_b32 m0, s7
	s_nop 0
	global_load_lds_dwordx4 v[172:173], off
	s_waitcnt lgkmcnt(4)
	v_mfma_f32_32x32x16_bf16 v[80:95], v[214:217], v[202:205], v[80:95]
	ds_read_b128 v[150:153], v134
	v_mfma_f32_32x32x16_bf16 v[64:79], v[214:217], v[206:209], v[64:79]
	ds_read_b128 v[146:149], v134 offset:2048
	s_waitcnt lgkmcnt(5)
	v_mfma_f32_32x32x16_bf16 v[48:63], v[224:227], v[202:205], v[48:63]
	ds_read_b128 v[138:141], v134 offset:4096
	v_mfma_f32_32x32x16_bf16 v[32:47], v[224:227], v[206:209], v[32:47]
	ds_read_b128 v[134:137], v134 offset:6144
	v_lshl_add_u64 v[222:223], v[172:173], 0, s[10:11]
	s_mov_b32 m0, s8
	s_nop 0
	global_load_lds_dwordx4 v[222:223], off
	s_waitcnt lgkmcnt(6)
	v_mfma_f32_32x32x16_bf16 v[16:31], v[234:237], v[202:205], v[16:31]
	s_add_i32 s5, s5, 0x8000
	v_lshl_add_u64 v[170:171], v[170:171], 0, 64
	v_lshl_add_u64 v[172:173], v[172:173], 0, 64
	s_cmp_eq_u32 s5, 0x2c0000
	v_mfma_f32_32x32x16_bf16 v[0:15], v[234:237], v[206:209], v[0:15]
	s_cbranch_scc0 .LBB0_2551
	s_waitcnt vmcnt(8) lgkmcnt(0)
	s_barrier
	v_add_u32_e32 v202, v179, v177
	v_add_u32_e32 v222, v176, v177
	ds_read_b128 v[170:173], v202 offset:49152
	ds_read_b128 v[202:205], v202 offset:51200
	ds_read_b128 v[206:209], v222 offset:32768
	ds_read_b128 v[210:213], v222 offset:34816
	ds_read_b128 v[214:217], v222 offset:36864
	ds_read_b128 v[224:227], v222 offset:38912
	s_waitcnt lgkmcnt(9)
	v_mfma_f32_32x32x16_bf16 v[112:127], v[150:153], v[142:145], v[112:127]
	v_mfma_f32_32x32x16_bf16 v[96:111], v[150:153], v[130:133], v[96:111]
	s_waitcnt lgkmcnt(8)
	v_mfma_f32_32x32x16_bf16 v[80:95], v[146:149], v[142:145], v[80:95]
	v_mfma_f32_32x32x16_bf16 v[64:79], v[146:149], v[130:133], v[64:79]
	s_waitcnt lgkmcnt(7)
	v_mfma_f32_32x32x16_bf16 v[48:63], v[138:141], v[142:145], v[48:63]
	v_mfma_f32_32x32x16_bf16 v[32:47], v[138:141], v[130:133], v[32:47]
	s_waitcnt lgkmcnt(6)
	v_mfma_f32_32x32x16_bf16 v[16:31], v[134:137], v[142:145], v[16:31]
	v_mfma_f32_32x32x16_bf16 v[0:15], v[134:137], v[130:133], v[0:15]
	v_add_u32_e32 v134, v179, v178
	v_add_u32_e32 v150, v176, v178
	ds_read_b128 v[130:133], v134 offset:49152
	ds_read_b128 v[134:137], v134 offset:51200
	ds_read_b128 v[138:141], v150 offset:32768
	ds_read_b128 v[142:145], v150 offset:34816
	ds_read_b128 v[146:149], v150 offset:36864
	ds_read_b128 v[150:153], v150 offset:38912
	s_waitcnt lgkmcnt(9)
	v_mfma_f32_32x32x16_bf16 v[112:127], v[206:209], v[170:173], v[112:127]
	v_mfma_f32_32x32x16_bf16 v[96:111], v[206:209], v[202:205], v[96:111]
	s_waitcnt lgkmcnt(8)
	v_mfma_f32_32x32x16_bf16 v[80:95], v[210:213], v[170:173], v[80:95]
	v_mfma_f32_32x32x16_bf16 v[64:79], v[210:213], v[202:205], v[64:79]
	s_waitcnt lgkmcnt(7)
	v_mfma_f32_32x32x16_bf16 v[48:63], v[214:217], v[170:173], v[48:63]
	v_mfma_f32_32x32x16_bf16 v[32:47], v[214:217], v[202:205], v[32:47]
	s_waitcnt lgkmcnt(6)
	v_mfma_f32_32x32x16_bf16 v[0:15], v[224:227], v[202:205], v[0:15]
	s_waitcnt vmcnt(4) lgkmcnt(0)
	s_barrier
	v_add_u32_e32 v202, v199, v177
	v_add_u32_e32 v222, v200, v177
	v_mfma_f32_32x32x16_bf16 v[16:31], v[224:227], v[170:173], v[16:31]
	ds_read_b128 v[170:173], v202 offset:16384
	ds_read_b128 v[202:205], v202 offset:18432
	ds_read_b128 v[206:209], v222
	ds_read_b128 v[210:213], v222 offset:2048
	ds_read_b128 v[214:217], v222 offset:4096
	ds_read_b128 v[224:227], v222 offset:6144
	s_waitcnt lgkmcnt(9)
	v_mfma_f32_32x32x16_bf16 v[112:127], v[138:141], v[130:133], v[112:127]
	v_mfma_f32_32x32x16_bf16 v[96:111], v[138:141], v[134:137], v[96:111]
	s_waitcnt lgkmcnt(8)
	v_mfma_f32_32x32x16_bf16 v[80:95], v[142:145], v[130:133], v[80:95]
	v_mfma_f32_32x32x16_bf16 v[64:79], v[142:145], v[134:137], v[64:79]
	s_waitcnt lgkmcnt(7)
	v_mfma_f32_32x32x16_bf16 v[48:63], v[146:149], v[130:133], v[48:63]
	v_mfma_f32_32x32x16_bf16 v[32:47], v[146:149], v[134:137], v[32:47]
	s_waitcnt lgkmcnt(6)
	v_mfma_f32_32x32x16_bf16 v[16:31], v[150:153], v[130:133], v[16:31]
	v_mfma_f32_32x32x16_bf16 v[0:15], v[150:153], v[134:137], v[0:15]
	v_add_u32_e32 v134, v199, v178
	v_add_u32_e32 v150, v200, v178
	ds_read_b128 v[130:133], v134 offset:16384
	ds_read_b128 v[134:137], v134 offset:18432
	ds_read_b128 v[138:141], v150
	ds_read_b128 v[142:145], v150 offset:2048
	ds_read_b128 v[146:149], v150 offset:4096
	ds_read_b128 v[150:153], v150 offset:6144
	s_waitcnt lgkmcnt(9)
	v_mfma_f32_32x32x16_bf16 v[112:127], v[206:209], v[170:173], v[112:127]
	v_mfma_f32_32x32x16_bf16 v[96:111], v[206:209], v[202:205], v[96:111]
	s_waitcnt lgkmcnt(8)
	v_mfma_f32_32x32x16_bf16 v[80:95], v[210:213], v[170:173], v[80:95]
	v_mfma_f32_32x32x16_bf16 v[64:79], v[210:213], v[202:205], v[64:79]
	s_waitcnt lgkmcnt(7)
	v_mfma_f32_32x32x16_bf16 v[48:63], v[214:217], v[170:173], v[48:63]
	v_mfma_f32_32x32x16_bf16 v[32:47], v[214:217], v[202:205], v[32:47]
	s_waitcnt lgkmcnt(6)
	v_mfma_f32_32x32x16_bf16 v[0:15], v[224:227], v[202:205], v[0:15]
	s_waitcnt vmcnt(0) lgkmcnt(0)
	s_barrier
	v_add_u32_e32 v202, v197, v177
	v_add_u32_e32 v222, v198, v177
	v_mfma_f32_32x32x16_bf16 v[16:31], v[224:227], v[170:173], v[16:31]
	ds_read_b128 v[170:173], v202 offset:16384
	ds_read_b128 v[202:205], v202 offset:18432
	ds_read_b128 v[206:209], v222
	ds_read_b128 v[210:213], v222 offset:2048
	ds_read_b128 v[214:217], v222 offset:4096
	ds_read_b128 v[224:227], v222 offset:6144
	s_waitcnt lgkmcnt(9)
	v_mfma_f32_32x32x16_bf16 v[112:127], v[138:141], v[130:133], v[112:127]
	v_mfma_f32_32x32x16_bf16 v[96:111], v[138:141], v[134:137], v[96:111]
	s_waitcnt lgkmcnt(8)
	v_mfma_f32_32x32x16_bf16 v[80:95], v[142:145], v[130:133], v[80:95]
	v_mfma_f32_32x32x16_bf16 v[64:79], v[142:145], v[134:137], v[64:79]
	s_waitcnt lgkmcnt(7)
	v_mfma_f32_32x32x16_bf16 v[48:63], v[146:149], v[130:133], v[48:63]
	v_mfma_f32_32x32x16_bf16 v[32:47], v[146:149], v[134:137], v[32:47]
	s_waitcnt lgkmcnt(6)
	v_mfma_f32_32x32x16_bf16 v[16:31], v[150:153], v[130:133], v[16:31]
	v_mfma_f32_32x32x16_bf16 v[0:15], v[150:153], v[134:137], v[0:15]
	v_add_u32_e32 v134, v197, v178
	v_add_u32_e32 v150, v198, v178
	ds_read_b128 v[130:133], v134 offset:16384
	ds_read_b128 v[134:137], v134 offset:18432
	ds_read_b128 v[138:141], v150
	ds_read_b128 v[142:145], v150 offset:2048
	ds_read_b128 v[146:149], v150 offset:4096
	ds_read_b128 v[150:153], v150 offset:6144
	s_waitcnt lgkmcnt(9)
	v_mfma_f32_32x32x16_bf16 v[112:127], v[206:209], v[170:173], v[112:127]
	v_mfma_f32_32x32x16_bf16 v[96:111], v[206:209], v[202:205], v[96:111]
	s_waitcnt lgkmcnt(8)
	v_mfma_f32_32x32x16_bf16 v[80:95], v[210:213], v[170:173], v[80:95]
	v_mfma_f32_32x32x16_bf16 v[64:79], v[210:213], v[202:205], v[64:79]
	s_waitcnt lgkmcnt(7)
	v_mfma_f32_32x32x16_bf16 v[48:63], v[214:217], v[170:173], v[48:63]
	v_mfma_f32_32x32x16_bf16 v[32:47], v[214:217], v[202:205], v[32:47]
	s_waitcnt lgkmcnt(6)
	v_mfma_f32_32x32x16_bf16 v[16:31], v[224:227], v[170:173], v[16:31]
	s_movk_i32 s7, 0x1600
	v_mfma_f32_32x32x16_bf16 v[0:15], v[224:227], v[202:205], v[0:15]
	s_waitcnt lgkmcnt(3)
	v_mfma_f32_32x32x16_bf16 v[112:127], v[138:141], v[130:133], v[112:127]
	v_mfma_f32_32x32x16_bf16 v[96:111], v[138:141], v[134:137], v[96:111]
	s_nop 10
	v_cvt_pk_bf16_f32 v112, v112, s0
	s_waitcnt lgkmcnt(2)
	v_mfma_f32_32x32x16_bf16 v[80:95], v[142:145], v[130:133], v[80:95]
	v_cvt_pk_bf16_f32 v96, v96, s0
	v_cvt_pk_bf16_f32 v98, v98, s0
	s_waitcnt lgkmcnt(1)
	v_mfma_f32_32x32x16_bf16 v[48:63], v[146:149], v[130:133], v[48:63]
	s_nop 7
	v_cvt_pk_bf16_f32 v80, v80, s0
	s_waitcnt lgkmcnt(0)
	v_mfma_f32_32x32x16_bf16 v[16:31], v[150:153], v[130:133], v[16:31]
	v_add_u32_e32 v132, s3, v128
	v_or_b32_e32 v130, s4, v174
	v_ashrrev_i32_e32 v131, 31, v130
	v_lshl_add_u64 v[130:131], v[130:131], 1, v[158:159]
	v_cvt_pk_bf16_f32 v48, v48, s0
	v_readlane_b32 s3, v252, 7
	s_add_i32 s6, s6, s3
	v_mfma_f32_32x32x16_bf16 v[64:79], v[142:145], v[134:137], v[64:79]
	s_nop 3
	v_cvt_pk_bf16_f32 v16, v16, s0
	v_mfma_f32_32x32x16_bf16 v[32:47], v[146:149], v[134:137], v[32:47]
	s_nop 5
	v_cvt_pk_bf16_f32 v64, v64, s0
	v_cvt_pk_bf16_f32 v66, v66, s0
	v_mfma_f32_32x32x16_bf16 v[0:15], v[150:153], v[134:137], v[0:15]
	v_or_b32_e32 v134, v132, v181
	v_ashrrev_i32_e32 v135, 31, v134
	v_lshlrev_b64 v[134:135], 11, v[134:135]
	v_lshl_add_u64 v[134:135], v[130:131], 0, v[134:135]
	global_store_short v[134:135], v112, off
	global_store_short v[134:135], v96, off offset:64
	v_or_b32_e32 v134, v132, v182
	v_ashrrev_i32_e32 v135, 31, v134
	v_lshlrev_b64 v[134:135], 11, v[134:135]
	v_lshl_add_u64 v[134:135], v[130:131], 0, v[134:135]
	v_cvt_pk_bf16_f32 v96, v113, s0
	global_store_short v[134:135], v96, off
	v_cvt_pk_bf16_f32 v96, v97, s0
	global_store_short v[134:135], v96, off offset:64
	v_or_b32_e32 v96, v132, v183
	v_ashrrev_i32_e32 v97, 31, v96
	v_lshlrev_b64 v[96:97], 11, v[96:97]
	v_lshl_add_u64 v[96:97], v[130:131], 0, v[96:97]
	v_cvt_pk_bf16_f32 v112, v114, s0
	global_store_short v[96:97], v112, off
	global_store_short v[96:97], v98, off offset:64
	v_or_b32_e32 v96, v132, v184
	v_ashrrev_i32_e32 v97, 31, v96
	v_lshlrev_b64 v[96:97], 11, v[96:97]
	v_lshl_add_u64 v[96:97], v[130:131], 0, v[96:97]
	v_cvt_pk_bf16_f32 v98, v115, s0
	global_store_short v[96:97], v98, off
	v_cvt_pk_bf16_f32 v98, v99, s0
	global_store_short v[96:97], v98, off offset:64
	v_or_b32_e32 v96, v132, v185
	v_ashrrev_i32_e32 v97, 31, v96
	v_lshlrev_b64 v[96:97], 11, v[96:97]
	v_lshl_add_u64 v[96:97], v[130:131], 0, v[96:97]
	v_cvt_pk_bf16_f32 v98, v116, s0
	global_store_short v[96:97], v98, off
	v_cvt_pk_bf16_f32 v98, v100, s0
	global_store_short v[96:97], v98, off offset:64
	v_or_b32_e32 v96, v132, v186
	v_ashrrev_i32_e32 v97, 31, v96
	v_lshlrev_b64 v[96:97], 11, v[96:97]
	v_lshl_add_u64 v[96:97], v[130:131], 0, v[96:97]
	v_cvt_pk_bf16_f32 v98, v117, s0
	global_store_short v[96:97], v98, off
	v_cvt_pk_bf16_f32 v98, v101, s0
	global_store_short v[96:97], v98, off offset:64
	v_or_b32_e32 v96, v132, v187
	v_ashrrev_i32_e32 v97, 31, v96
	v_lshlrev_b64 v[96:97], 11, v[96:97]
	v_lshl_add_u64 v[96:97], v[130:131], 0, v[96:97]
	v_cvt_pk_bf16_f32 v98, v118, s0
	global_store_short v[96:97], v98, off
	v_cvt_pk_bf16_f32 v98, v102, s0
	global_store_short v[96:97], v98, off offset:64
	v_or_b32_e32 v96, v132, v188
	v_ashrrev_i32_e32 v97, 31, v96
	v_lshlrev_b64 v[96:97], 11, v[96:97]
	v_lshl_add_u64 v[96:97], v[130:131], 0, v[96:97]
	v_cvt_pk_bf16_f32 v98, v119, s0
	global_store_short v[96:97], v98, off
	v_cvt_pk_bf16_f32 v98, v103, s0
	global_store_short v[96:97], v98, off offset:64
	v_or_b32_e32 v96, v132, v189
	v_ashrrev_i32_e32 v97, 31, v96
	v_lshlrev_b64 v[96:97], 11, v[96:97]
	v_lshl_add_u64 v[96:97], v[130:131], 0, v[96:97]
	v_cvt_pk_bf16_f32 v98, v120, s0
	global_store_short v[96:97], v98, off
	v_cvt_pk_bf16_f32 v98, v104, s0
	global_store_short v[96:97], v98, off offset:64
	v_or_b32_e32 v96, v132, v190
	v_ashrrev_i32_e32 v97, 31, v96
	v_lshlrev_b64 v[96:97], 11, v[96:97]
	v_lshl_add_u64 v[96:97], v[130:131], 0, v[96:97]
	v_cvt_pk_bf16_f32 v98, v121, s0
	global_store_short v[96:97], v98, off
	v_cvt_pk_bf16_f32 v98, v105, s0
	global_store_short v[96:97], v98, off offset:64
	v_or_b32_e32 v96, v132, v191
	v_ashrrev_i32_e32 v97, 31, v96
	v_lshlrev_b64 v[96:97], 11, v[96:97]
	v_lshl_add_u64 v[96:97], v[130:131], 0, v[96:97]
	v_cvt_pk_bf16_f32 v98, v122, s0
	global_store_short v[96:97], v98, off
	v_cvt_pk_bf16_f32 v98, v106, s0
	global_store_short v[96:97], v98, off offset:64
	v_or_b32_e32 v96, v132, v192
	v_ashrrev_i32_e32 v97, 31, v96
	v_lshlrev_b64 v[96:97], 11, v[96:97]
	v_lshl_add_u64 v[96:97], v[130:131], 0, v[96:97]
	v_cvt_pk_bf16_f32 v98, v123, s0
	global_store_short v[96:97], v98, off
	v_cvt_pk_bf16_f32 v98, v107, s0
	global_store_short v[96:97], v98, off offset:64
	v_or_b32_e32 v96, v132, v193
	v_ashrrev_i32_e32 v97, 31, v96
	v_lshlrev_b64 v[96:97], 11, v[96:97]
	v_lshl_add_u64 v[96:97], v[130:131], 0, v[96:97]
	v_cvt_pk_bf16_f32 v98, v124, s0
	global_store_short v[96:97], v98, off
	v_cvt_pk_bf16_f32 v98, v108, s0
	global_store_short v[96:97], v98, off offset:64
	v_or_b32_e32 v96, v132, v194
	v_ashrrev_i32_e32 v97, 31, v96
	v_lshlrev_b64 v[96:97], 11, v[96:97]
	v_lshl_add_u64 v[96:97], v[130:131], 0, v[96:97]
	v_cvt_pk_bf16_f32 v98, v125, s0
	global_store_short v[96:97], v98, off
	v_cvt_pk_bf16_f32 v98, v109, s0
	global_store_short v[96:97], v98, off offset:64
	v_or_b32_e32 v96, v132, v195
	v_ashrrev_i32_e32 v97, 31, v96
	v_lshlrev_b64 v[96:97], 11, v[96:97]
	v_lshl_add_u64 v[96:97], v[130:131], 0, v[96:97]
	v_cvt_pk_bf16_f32 v98, v126, s0
	global_store_short v[96:97], v98, off
	v_cvt_pk_bf16_f32 v98, v110, s0
	global_store_short v[96:97], v98, off offset:64
	v_or_b32_e32 v96, v132, v196
	v_ashrrev_i32_e32 v97, 31, v96
	v_lshlrev_b64 v[96:97], 11, v[96:97]
	v_lshl_add_u64 v[96:97], v[130:131], 0, v[96:97]
	v_cvt_pk_bf16_f32 v98, v127, s0
	global_store_short v[96:97], v98, off
	v_cvt_pk_bf16_f32 v98, v111, s0
	global_store_short v[96:97], v98, off offset:64
	v_or_b32_e32 v98, 32, v132
	v_or_b32_e32 v96, v98, v181
	v_ashrrev_i32_e32 v97, 31, v96
	v_lshlrev_b64 v[96:97], 11, v[96:97]
	v_lshl_add_u64 v[96:97], v[130:131], 0, v[96:97]
	global_store_short v[96:97], v80, off
	global_store_short v[96:97], v64, off offset:64
	v_or_b32_e32 v96, v98, v182
	v_ashrrev_i32_e32 v97, 31, v96
	v_lshlrev_b64 v[96:97], 11, v[96:97]
	v_lshl_add_u64 v[96:97], v[130:131], 0, v[96:97]
	v_cvt_pk_bf16_f32 v64, v81, s0
	global_store_short v[96:97], v64, off
	v_cvt_pk_bf16_f32 v64, v65, s0
	global_store_short v[96:97], v64, off offset:64
	v_or_b32_e32 v64, v98, v183
	v_ashrrev_i32_e32 v65, 31, v64
	v_lshlrev_b64 v[64:65], 11, v[64:65]
	v_lshl_add_u64 v[64:65], v[130:131], 0, v[64:65]
	v_cvt_pk_bf16_f32 v80, v82, s0
	global_store_short v[64:65], v80, off
	global_store_short v[64:65], v66, off offset:64
	v_or_b32_e32 v64, v98, v184
	v_ashrrev_i32_e32 v65, 31, v64
	v_lshlrev_b64 v[64:65], 11, v[64:65]
	v_lshl_add_u64 v[64:65], v[130:131], 0, v[64:65]
	v_cvt_pk_bf16_f32 v66, v83, s0
	global_store_short v[64:65], v66, off
	v_cvt_pk_bf16_f32 v66, v67, s0
	global_store_short v[64:65], v66, off offset:64
	v_or_b32_e32 v64, v98, v185
	v_ashrrev_i32_e32 v65, 31, v64
	v_lshlrev_b64 v[64:65], 11, v[64:65]
	v_lshl_add_u64 v[64:65], v[130:131], 0, v[64:65]
	v_cvt_pk_bf16_f32 v66, v84, s0
	global_store_short v[64:65], v66, off
	v_cvt_pk_bf16_f32 v66, v68, s0
	global_store_short v[64:65], v66, off offset:64
	v_or_b32_e32 v64, v98, v186
	v_ashrrev_i32_e32 v65, 31, v64
	v_lshlrev_b64 v[64:65], 11, v[64:65]
	v_lshl_add_u64 v[64:65], v[130:131], 0, v[64:65]
	v_cvt_pk_bf16_f32 v66, v85, s0
	global_store_short v[64:65], v66, off
	v_cvt_pk_bf16_f32 v66, v69, s0
	global_store_short v[64:65], v66, off offset:64
	v_or_b32_e32 v64, v98, v187
	v_ashrrev_i32_e32 v65, 31, v64
	v_lshlrev_b64 v[64:65], 11, v[64:65]
	v_lshl_add_u64 v[64:65], v[130:131], 0, v[64:65]
	v_cvt_pk_bf16_f32 v66, v86, s0
	global_store_short v[64:65], v66, off
	v_cvt_pk_bf16_f32 v66, v70, s0
	global_store_short v[64:65], v66, off offset:64
	v_or_b32_e32 v64, v98, v188
	v_ashrrev_i32_e32 v65, 31, v64
	v_lshlrev_b64 v[64:65], 11, v[64:65]
	v_lshl_add_u64 v[64:65], v[130:131], 0, v[64:65]
	v_cvt_pk_bf16_f32 v66, v87, s0
	global_store_short v[64:65], v66, off
	v_cvt_pk_bf16_f32 v66, v71, s0
	global_store_short v[64:65], v66, off offset:64
	v_or_b32_e32 v64, v98, v189
	v_ashrrev_i32_e32 v65, 31, v64
	v_lshlrev_b64 v[64:65], 11, v[64:65]
	v_lshl_add_u64 v[64:65], v[130:131], 0, v[64:65]
	v_cvt_pk_bf16_f32 v66, v88, s0
	global_store_short v[64:65], v66, off
	v_cvt_pk_bf16_f32 v66, v72, s0
	global_store_short v[64:65], v66, off offset:64
	v_or_b32_e32 v64, v98, v190
	v_ashrrev_i32_e32 v65, 31, v64
	v_lshlrev_b64 v[64:65], 11, v[64:65]
	v_lshl_add_u64 v[64:65], v[130:131], 0, v[64:65]
	v_cvt_pk_bf16_f32 v66, v89, s0
	global_store_short v[64:65], v66, off
	v_cvt_pk_bf16_f32 v66, v73, s0
	global_store_short v[64:65], v66, off offset:64
	v_or_b32_e32 v64, v98, v191
	v_ashrrev_i32_e32 v65, 31, v64
	v_lshlrev_b64 v[64:65], 11, v[64:65]
	v_lshl_add_u64 v[64:65], v[130:131], 0, v[64:65]
	v_cvt_pk_bf16_f32 v66, v90, s0
	global_store_short v[64:65], v66, off
	v_cvt_pk_bf16_f32 v66, v74, s0
	global_store_short v[64:65], v66, off offset:64
	v_or_b32_e32 v64, v98, v192
	v_ashrrev_i32_e32 v65, 31, v64
	v_lshlrev_b64 v[64:65], 11, v[64:65]
	v_lshl_add_u64 v[64:65], v[130:131], 0, v[64:65]
	v_cvt_pk_bf16_f32 v66, v91, s0
	global_store_short v[64:65], v66, off
	v_cvt_pk_bf16_f32 v66, v75, s0
	global_store_short v[64:65], v66, off offset:64
	v_or_b32_e32 v64, v98, v193
	v_ashrrev_i32_e32 v65, 31, v64
	v_lshlrev_b64 v[64:65], 11, v[64:65]
	v_lshl_add_u64 v[64:65], v[130:131], 0, v[64:65]
	v_cvt_pk_bf16_f32 v66, v92, s0
	global_store_short v[64:65], v66, off
	v_cvt_pk_bf16_f32 v66, v76, s0
	global_store_short v[64:65], v66, off offset:64
	v_or_b32_e32 v64, v98, v194
	v_ashrrev_i32_e32 v65, 31, v64
	v_lshlrev_b64 v[64:65], 11, v[64:65]
	v_lshl_add_u64 v[64:65], v[130:131], 0, v[64:65]
	v_cvt_pk_bf16_f32 v66, v93, s0
	global_store_short v[64:65], v66, off
	v_cvt_pk_bf16_f32 v66, v77, s0
	global_store_short v[64:65], v66, off offset:64
	v_or_b32_e32 v64, v98, v195
	v_ashrrev_i32_e32 v65, 31, v64
	v_lshlrev_b64 v[64:65], 11, v[64:65]
	v_lshl_add_u64 v[64:65], v[130:131], 0, v[64:65]
	v_cvt_pk_bf16_f32 v66, v94, s0
	global_store_short v[64:65], v66, off
	v_cvt_pk_bf16_f32 v66, v78, s0
	global_store_short v[64:65], v66, off offset:64
	v_or_b32_e32 v64, v98, v196
	v_ashrrev_i32_e32 v65, 31, v64
	v_lshlrev_b64 v[64:65], 11, v[64:65]
	v_lshl_add_u64 v[64:65], v[130:131], 0, v[64:65]
	v_cvt_pk_bf16_f32 v66, v95, s0
	global_store_short v[64:65], v66, off
	v_cvt_pk_bf16_f32 v66, v79, s0
	global_store_short v[64:65], v66, off offset:64
	v_or_b32_e32 v66, 64, v132
	v_or_b32_e32 v64, v66, v181
	v_ashrrev_i32_e32 v65, 31, v64
	v_lshlrev_b64 v[64:65], 11, v[64:65]
	v_lshl_add_u64 v[64:65], v[130:131], 0, v[64:65]
	v_cvt_pk_bf16_f32 v32, v32, s0
	global_store_short v[64:65], v48, off
	global_store_short v[64:65], v32, off offset:64
	v_or_b32_e32 v64, v66, v182
	v_ashrrev_i32_e32 v65, 31, v64
	v_lshlrev_b64 v[64:65], 11, v[64:65]
	v_lshl_add_u64 v[64:65], v[130:131], 0, v[64:65]
	v_cvt_pk_bf16_f32 v32, v49, s0
	global_store_short v[64:65], v32, off
	v_cvt_pk_bf16_f32 v32, v33, s0
	global_store_short v[64:65], v32, off offset:64
	v_or_b32_e32 v32, v66, v183
	v_ashrrev_i32_e32 v33, 31, v32
	v_lshlrev_b64 v[32:33], 11, v[32:33]
	v_lshl_add_u64 v[32:33], v[130:131], 0, v[32:33]
	v_cvt_pk_bf16_f32 v48, v50, s0
	v_cvt_pk_bf16_f32 v34, v34, s0
	global_store_short v[32:33], v48, off
	global_store_short v[32:33], v34, off offset:64
	v_or_b32_e32 v32, v66, v184
	v_ashrrev_i32_e32 v33, 31, v32
	v_lshlrev_b64 v[32:33], 11, v[32:33]
	v_lshl_add_u64 v[32:33], v[130:131], 0, v[32:33]
	v_cvt_pk_bf16_f32 v34, v51, s0
	global_store_short v[32:33], v34, off
	v_cvt_pk_bf16_f32 v34, v35, s0
	global_store_short v[32:33], v34, off offset:64
	v_or_b32_e32 v32, v66, v185
	v_ashrrev_i32_e32 v33, 31, v32
	v_lshlrev_b64 v[32:33], 11, v[32:33]
	v_lshl_add_u64 v[32:33], v[130:131], 0, v[32:33]
	v_cvt_pk_bf16_f32 v34, v52, s0
	global_store_short v[32:33], v34, off
	v_cvt_pk_bf16_f32 v34, v36, s0
	global_store_short v[32:33], v34, off offset:64
	v_or_b32_e32 v32, v66, v186
	v_ashrrev_i32_e32 v33, 31, v32
	v_lshlrev_b64 v[32:33], 11, v[32:33]
	v_lshl_add_u64 v[32:33], v[130:131], 0, v[32:33]
	v_cvt_pk_bf16_f32 v34, v53, s0
	global_store_short v[32:33], v34, off
	v_cvt_pk_bf16_f32 v34, v37, s0
	global_store_short v[32:33], v34, off offset:64
	v_or_b32_e32 v32, v66, v187
	v_ashrrev_i32_e32 v33, 31, v32
	v_lshlrev_b64 v[32:33], 11, v[32:33]
	v_lshl_add_u64 v[32:33], v[130:131], 0, v[32:33]
	v_cvt_pk_bf16_f32 v34, v54, s0
	global_store_short v[32:33], v34, off
	v_cvt_pk_bf16_f32 v34, v38, s0
	global_store_short v[32:33], v34, off offset:64
	v_or_b32_e32 v32, v66, v188
	v_ashrrev_i32_e32 v33, 31, v32
	v_lshlrev_b64 v[32:33], 11, v[32:33]
	v_lshl_add_u64 v[32:33], v[130:131], 0, v[32:33]
	v_cvt_pk_bf16_f32 v34, v55, s0
	global_store_short v[32:33], v34, off
	v_cvt_pk_bf16_f32 v34, v39, s0
	global_store_short v[32:33], v34, off offset:64
	v_or_b32_e32 v32, v66, v189
	v_ashrrev_i32_e32 v33, 31, v32
	v_lshlrev_b64 v[32:33], 11, v[32:33]
	v_lshl_add_u64 v[32:33], v[130:131], 0, v[32:33]
	v_cvt_pk_bf16_f32 v34, v56, s0
	global_store_short v[32:33], v34, off
	v_cvt_pk_bf16_f32 v34, v40, s0
	global_store_short v[32:33], v34, off offset:64
	v_or_b32_e32 v32, v66, v190
	v_ashrrev_i32_e32 v33, 31, v32
	v_lshlrev_b64 v[32:33], 11, v[32:33]
	v_lshl_add_u64 v[32:33], v[130:131], 0, v[32:33]
	v_cvt_pk_bf16_f32 v34, v57, s0
	global_store_short v[32:33], v34, off
	v_cvt_pk_bf16_f32 v34, v41, s0
	global_store_short v[32:33], v34, off offset:64
	v_or_b32_e32 v32, v66, v191
	v_ashrrev_i32_e32 v33, 31, v32
	v_lshlrev_b64 v[32:33], 11, v[32:33]
	v_lshl_add_u64 v[32:33], v[130:131], 0, v[32:33]
	v_cvt_pk_bf16_f32 v34, v58, s0
	global_store_short v[32:33], v34, off
	v_cvt_pk_bf16_f32 v34, v42, s0
	global_store_short v[32:33], v34, off offset:64
	v_or_b32_e32 v32, v66, v192
	v_ashrrev_i32_e32 v33, 31, v32
	v_lshlrev_b64 v[32:33], 11, v[32:33]
	v_lshl_add_u64 v[32:33], v[130:131], 0, v[32:33]
	v_cvt_pk_bf16_f32 v34, v59, s0
	global_store_short v[32:33], v34, off
	v_cvt_pk_bf16_f32 v34, v43, s0
	global_store_short v[32:33], v34, off offset:64
	v_or_b32_e32 v32, v66, v193
	v_ashrrev_i32_e32 v33, 31, v32
	v_lshlrev_b64 v[32:33], 11, v[32:33]
	v_lshl_add_u64 v[32:33], v[130:131], 0, v[32:33]
	v_cvt_pk_bf16_f32 v34, v60, s0
	global_store_short v[32:33], v34, off
	v_cvt_pk_bf16_f32 v34, v44, s0
	global_store_short v[32:33], v34, off offset:64
	v_or_b32_e32 v32, v66, v194
	v_ashrrev_i32_e32 v33, 31, v32
	v_lshlrev_b64 v[32:33], 11, v[32:33]
	v_lshl_add_u64 v[32:33], v[130:131], 0, v[32:33]
	v_cvt_pk_bf16_f32 v34, v61, s0
	global_store_short v[32:33], v34, off
	v_cvt_pk_bf16_f32 v34, v45, s0
	global_store_short v[32:33], v34, off offset:64
	v_or_b32_e32 v32, v66, v195
	v_ashrrev_i32_e32 v33, 31, v32
	v_lshlrev_b64 v[32:33], 11, v[32:33]
	v_lshl_add_u64 v[32:33], v[130:131], 0, v[32:33]
	v_cvt_pk_bf16_f32 v34, v62, s0
	global_store_short v[32:33], v34, off
	v_cvt_pk_bf16_f32 v34, v46, s0
	global_store_short v[32:33], v34, off offset:64
	v_or_b32_e32 v32, v66, v196
	v_ashrrev_i32_e32 v33, 31, v32
	v_lshlrev_b64 v[32:33], 11, v[32:33]
	v_lshl_add_u64 v[32:33], v[130:131], 0, v[32:33]
	v_cvt_pk_bf16_f32 v34, v63, s0
	global_store_short v[32:33], v34, off
	v_cvt_pk_bf16_f32 v34, v47, s0
	global_store_short v[32:33], v34, off offset:64
	v_or_b32_e32 v34, 0x60, v132
	v_or_b32_e32 v32, v34, v181
	v_ashrrev_i32_e32 v33, 31, v32
	v_lshlrev_b64 v[32:33], 11, v[32:33]
	v_lshl_add_u64 v[32:33], v[130:131], 0, v[32:33]
	v_cvt_pk_bf16_f32 v0, v0, s0
	global_store_short v[32:33], v16, off
	global_store_short v[32:33], v0, off offset:64
	v_or_b32_e32 v32, v34, v182
	v_ashrrev_i32_e32 v33, 31, v32
	v_lshlrev_b64 v[32:33], 11, v[32:33]
	v_lshl_add_u64 v[32:33], v[130:131], 0, v[32:33]
	v_cvt_pk_bf16_f32 v0, v17, s0
	global_store_short v[32:33], v0, off
	v_cvt_pk_bf16_f32 v0, v1, s0
	global_store_short v[32:33], v0, off offset:64
	v_or_b32_e32 v0, v34, v183
	v_ashrrev_i32_e32 v1, 31, v0
	v_lshlrev_b64 v[0:1], 11, v[0:1]
	v_lshl_add_u64 v[0:1], v[130:131], 0, v[0:1]
	v_cvt_pk_bf16_f32 v16, v18, s0
	v_cvt_pk_bf16_f32 v2, v2, s0
	global_store_short v[0:1], v16, off
	global_store_short v[0:1], v2, off offset:64
	v_or_b32_e32 v0, v34, v184
	v_ashrrev_i32_e32 v1, 31, v0
	v_lshlrev_b64 v[0:1], 11, v[0:1]
	v_lshl_add_u64 v[0:1], v[130:131], 0, v[0:1]
	v_cvt_pk_bf16_f32 v2, v19, s0
	global_store_short v[0:1], v2, off
	v_cvt_pk_bf16_f32 v2, v3, s0
	global_store_short v[0:1], v2, off offset:64
	v_or_b32_e32 v0, v34, v185
	v_ashrrev_i32_e32 v1, 31, v0
	v_lshlrev_b64 v[0:1], 11, v[0:1]
	v_lshl_add_u64 v[0:1], v[130:131], 0, v[0:1]
	v_cvt_pk_bf16_f32 v2, v20, s0
	global_store_short v[0:1], v2, off
	v_cvt_pk_bf16_f32 v2, v4, s0
	global_store_short v[0:1], v2, off offset:64
	v_or_b32_e32 v0, v34, v186
	v_ashrrev_i32_e32 v1, 31, v0
	v_lshlrev_b64 v[0:1], 11, v[0:1]
	v_lshl_add_u64 v[0:1], v[130:131], 0, v[0:1]
	v_cvt_pk_bf16_f32 v2, v21, s0
	global_store_short v[0:1], v2, off
	v_cvt_pk_bf16_f32 v2, v5, s0
	global_store_short v[0:1], v2, off offset:64
	v_or_b32_e32 v0, v34, v187
	v_ashrrev_i32_e32 v1, 31, v0
	v_lshlrev_b64 v[0:1], 11, v[0:1]
	v_lshl_add_u64 v[0:1], v[130:131], 0, v[0:1]
	v_cvt_pk_bf16_f32 v2, v22, s0
	global_store_short v[0:1], v2, off
	v_cvt_pk_bf16_f32 v2, v6, s0
	global_store_short v[0:1], v2, off offset:64
	v_or_b32_e32 v0, v34, v188
	v_ashrrev_i32_e32 v1, 31, v0
	v_lshlrev_b64 v[0:1], 11, v[0:1]
	v_lshl_add_u64 v[0:1], v[130:131], 0, v[0:1]
	v_cvt_pk_bf16_f32 v2, v23, s0
	global_store_short v[0:1], v2, off
	v_cvt_pk_bf16_f32 v2, v7, s0
	global_store_short v[0:1], v2, off offset:64
	v_or_b32_e32 v0, v34, v189
	v_ashrrev_i32_e32 v1, 31, v0
	v_lshlrev_b64 v[0:1], 11, v[0:1]
	v_lshl_add_u64 v[0:1], v[130:131], 0, v[0:1]
	v_cvt_pk_bf16_f32 v2, v24, s0
	global_store_short v[0:1], v2, off
	v_cvt_pk_bf16_f32 v2, v8, s0
	global_store_short v[0:1], v2, off offset:64
	v_or_b32_e32 v0, v34, v190
	v_ashrrev_i32_e32 v1, 31, v0
	v_lshlrev_b64 v[0:1], 11, v[0:1]
	v_lshl_add_u64 v[0:1], v[130:131], 0, v[0:1]
	v_cvt_pk_bf16_f32 v2, v25, s0
	global_store_short v[0:1], v2, off
	v_cvt_pk_bf16_f32 v2, v9, s0
	global_store_short v[0:1], v2, off offset:64
	v_or_b32_e32 v0, v34, v191
	v_ashrrev_i32_e32 v1, 31, v0
	v_lshlrev_b64 v[0:1], 11, v[0:1]
	v_lshl_add_u64 v[0:1], v[130:131], 0, v[0:1]
	v_cvt_pk_bf16_f32 v2, v26, s0
	global_store_short v[0:1], v2, off
	v_cvt_pk_bf16_f32 v2, v10, s0
	global_store_short v[0:1], v2, off offset:64
	v_or_b32_e32 v0, v34, v192
	v_ashrrev_i32_e32 v1, 31, v0
	v_lshlrev_b64 v[0:1], 11, v[0:1]
	v_lshl_add_u64 v[0:1], v[130:131], 0, v[0:1]
	v_cvt_pk_bf16_f32 v2, v27, s0
	global_store_short v[0:1], v2, off
	v_cvt_pk_bf16_f32 v2, v11, s0
	global_store_short v[0:1], v2, off offset:64
	v_or_b32_e32 v0, v34, v193
	v_ashrrev_i32_e32 v1, 31, v0
	v_lshlrev_b64 v[0:1], 11, v[0:1]
	v_lshl_add_u64 v[0:1], v[130:131], 0, v[0:1]
	v_cvt_pk_bf16_f32 v2, v28, s0
	global_store_short v[0:1], v2, off
	v_cvt_pk_bf16_f32 v2, v12, s0
	global_store_short v[0:1], v2, off offset:64
	v_or_b32_e32 v0, v34, v194
	v_ashrrev_i32_e32 v1, 31, v0
	v_lshlrev_b64 v[0:1], 11, v[0:1]
	v_lshl_add_u64 v[0:1], v[130:131], 0, v[0:1]
	v_cvt_pk_bf16_f32 v2, v29, s0
	global_store_short v[0:1], v2, off
	v_cvt_pk_bf16_f32 v2, v13, s0
	global_store_short v[0:1], v2, off offset:64
	v_or_b32_e32 v0, v34, v195
	v_ashrrev_i32_e32 v1, 31, v0
	v_lshlrev_b64 v[0:1], 11, v[0:1]
	v_lshl_add_u64 v[0:1], v[130:131], 0, v[0:1]
	v_cvt_pk_bf16_f32 v2, v30, s0
	global_store_short v[0:1], v2, off
	v_cvt_pk_bf16_f32 v2, v14, s0
	global_store_short v[0:1], v2, off offset:64
	v_or_b32_e32 v0, v34, v196
	v_ashrrev_i32_e32 v1, 31, v0
	v_lshlrev_b64 v[0:1], 11, v[0:1]
	v_lshl_add_u64 v[0:1], v[130:131], 0, v[0:1]
	v_cvt_pk_bf16_f32 v2, v31, s0
	global_store_short v[0:1], v2, off
	v_cvt_pk_bf16_f32 v2, v15, s0
	s_add_i32 s0, s0, s3
	v_readlane_b32 s3, v252, 8
	s_add_i32 s2, s2, s3
	s_cmp_gt_i32 s6, 31
	global_store_short v[0:1], v2, off offset:64
	s_cbranch_scc0 .LBB0_2550
